# GEMM MFMA segments: the lgkmcnt(0) right after each barrier (already drained before the barrier) removed, 44 sites; on top of v37
# speedup vs baseline: 1.0093x; 1.0060x over previous
; #define PG8_STAGE(bufoff, gbase, voff) do { _Pragma("unroll") for (int _i = 0; _i < 2; ++_i) \
;         __builtin_amdgcn_global_load_lds((const unsigned*)((const char*)(gbase) + (voff)[_i]), (PG8_LAS unsigned*)(lds + (bufoff) + ldsw + _i * 8192), 16, 0, 0); } while (0)
; #define PG8_LDA(dst, b, h) do { _Pragma("unroll") for (int m = 0; m < 4; ++m) _Pragma("unroll") for (int k = 0; k < 2; ++k) dst[m][k] = *(const PG8_LAS bf16x8*)(lds + PG8_SA(b, h) + aoff + m * 2048 + k * 1024); } while (0)
; #define PG8_LDB(dst, b, h) do { _Pragma("unroll") for (int n = 0; n < 2; ++n) _Pragma("unroll") for (int k = 0; k < 2; ++k) dst[n][k] = *(const PG8_LAS bf16x8*)(lds + PG8_SB(b, h) + boff + n * 2048 + k * 1024); } while (0)
; #define PG8_MMA(ai, bj, At, Bt) do { __builtin_amdgcn_s_setprio(1); _Pragma("unroll") for (int m = 0; m < 4; ++m) _Pragma("unroll") for (int n = 0; n < 2; ++n) _Pragma("unroll") for (int k = 0; k < 2; ++k) \
;         acc[ai][bj][m][n] = __builtin_amdgcn_mfma_f32_16x16x32_bf16(Bt[n][k], At[m][k], acc[ai][bj][m][n], 0, 0, 0); __builtin_amdgcn_s_setprio(0); } while (0)
; #define PG8_WAIT_V(n) asm volatile("s_waitcnt vmcnt(" #n ")" ::: "memory")
; #define PG8_BAR __builtin_amdgcn_s_barrier()
; template <class Epi, class Sched, bool ALIGN_EPI = false, bool SP2 = false>
; __device__ __forceinline__ void gemm_phase(PG8_LAS unsigned char* lds, const Gemm g, const Sched& S, const Epi& E) {
;     ...
;         for (int t = 0; t < nt; t += 2) {
;             const bool last = (t == nt - 2);
;             const char* a1 = cA + (size_t)(t + 1) * kstep;
;             const char* a2 = last ? nA : cA + (size_t)(t + 2) * kstep; const char* b2 = last ? nB : cB + (size_t)(t + 2) * kstep;
;             const char* a3 = a2 + kstep; const char* b3 = b2 + kstep;
;             if (last && has_next) S.a_ready(nxt);
;             if constexpr (SP2) {
;             PG8_LDB(B0, 0, 0); PG8_LDB(B1, 0, 1); PG8_SCHED; PG8_LDA(At, 0, 0); PG8_STAGE(PG8_SA(1, 1), a1 + hstepA, voffA);
;             PG8_WAIT_V(8); PG8_WAIT_L(0); PG8_BAR; PG8_MMA(0, 0, At, B0); PG8_MMA(0, 1, At, B1); PG8_BAR; PG8_SCHED;
;             PG8_LDA(At, 0, 1); PG8_STAGE(PG8_SB(0, 0), b2, voffB); PG8_STAGE(PG8_SB(0, 1), b2 + hstepB, voffB); PG8_STAGE(PG8_SA(0, 0), a2, voffA);
;             PG8_WAIT_V(8); PG8_WAIT_L(0); PG8_BAR; PG8_MMA(1, 0, At, B0); PG8_MMA(1, 1, At, B1); PG8_BAR; PG8_SCHED;
.LBB0_254:
	s_add_u32 s28, s26, 0xfffc0080
	s_addc_u32 s29, s27, -1
	s_add_i32 s53, 0, 0x10000
	s_cmp_eq_u32 s52, 12
	s_cselect_b32 s31, s7, s29
	s_cselect_b32 s30, s9, s28
	v_add_u32_e32 v150, s53, v153
	s_cselect_b32 s29, s19, s51
	s_cselect_b32 s28, s21, s50
	s_add_i32 s56, 0, 0x14000
	ds_read_b128 v[142:145], v150
	ds_read_b128 v[146:149], v150 offset:1024
	ds_read_b128 v[158:161], v150 offset:2048
	ds_read_b128 v[162:165], v150 offset:3072
	v_add_u32_e32 v150, s56, v153
	ds_read_b128 v[166:169], v150
	ds_read_b128 v[170:173], v150 offset:1024
	ds_read_b128 v[174:177], v150 offset:2048
	ds_read_b128 v[178:181], v150 offset:3072
	s_add_i32 m0, s40, 0xc000
	ds_read_b128 v[182:185], v156
	ds_read_b128 v[202:205], v156 offset:1024
	ds_read_b128 v[206:209], v156 offset:2048
	ds_read_b128 v[210:213], v156 offset:3072
	ds_read_b128 v[232:235], v156 offset:4096
	ds_read_b128 v[236:239], v156 offset:5120
	ds_read_b128 v[240:243], v156 offset:6144
	ds_read_b128 v[244:247], v156 offset:7168
	global_load_lds_dwordx4 v138, s[26:27]
	s_add_i32 m0, s40, 0xe000
	s_nop 0
	global_load_lds_dwordx4 v140, s[26:27]
	s_waitcnt vmcnt(8)
	s_waitcnt lgkmcnt(0)
	s_barrier
	s_setprio 1
	v_mfma_f32_16x16x32_bf16 v[126:129], v[142:145], v[182:185], v[126:129]
	v_mfma_f32_16x16x32_bf16 v[122:125], v[158:161], v[182:185], v[122:125]
	v_mfma_f32_16x16x32_bf16 v[110:113], v[142:145], v[206:209], v[110:113]
	v_mfma_f32_16x16x32_bf16 v[106:109], v[158:161], v[206:209], v[106:109]
	v_mfma_f32_16x16x32_bf16 v[94:97], v[142:145], v[232:235], v[94:97]
	v_mfma_f32_16x16x32_bf16 v[90:93], v[158:161], v[232:235], v[90:93]
	v_mfma_f32_16x16x32_bf16 v[78:81], v[142:145], v[240:243], v[78:81]
	v_mfma_f32_16x16x32_bf16 v[74:77], v[158:161], v[240:243], v[74:77]
	v_mfma_f32_16x16x32_bf16 v[126:129], v[146:149], v[202:205], v[126:129]
	v_mfma_f32_16x16x32_bf16 v[122:125], v[162:165], v[202:205], v[122:125]
	v_mfma_f32_16x16x32_bf16 v[110:113], v[146:149], v[210:213], v[110:113]
	v_mfma_f32_16x16x32_bf16 v[106:109], v[162:165], v[210:213], v[106:109]
	v_mfma_f32_16x16x32_bf16 v[94:97], v[146:149], v[236:239], v[94:97]
	v_mfma_f32_16x16x32_bf16 v[90:93], v[162:165], v[236:239], v[90:93]
	v_mfma_f32_16x16x32_bf16 v[78:81], v[146:149], v[244:247], v[78:81]
	v_mfma_f32_16x16x32_bf16 v[74:77], v[162:165], v[244:247], v[74:77]
	s_setprio 0
	s_setprio 1
	v_mfma_f32_16x16x32_bf16 v[118:121], v[166:169], v[182:185], v[118:121]
	v_mfma_f32_16x16x32_bf16 v[114:117], v[174:177], v[182:185], v[114:117]
	v_mfma_f32_16x16x32_bf16 v[102:105], v[166:169], v[206:209], v[102:105]
	v_mfma_f32_16x16x32_bf16 v[98:101], v[174:177], v[206:209], v[98:101]
	v_mfma_f32_16x16x32_bf16 v[86:89], v[166:169], v[232:235], v[86:89]
	v_mfma_f32_16x16x32_bf16 v[82:85], v[174:177], v[232:235], v[82:85]
	v_mfma_f32_16x16x32_bf16 v[70:73], v[166:169], v[240:243], v[70:73]
	v_mfma_f32_16x16x32_bf16 v[66:69], v[174:177], v[240:243], v[66:69]
	v_mfma_f32_16x16x32_bf16 v[118:121], v[170:173], v[202:205], v[118:121]
	v_mfma_f32_16x16x32_bf16 v[114:117], v[178:181], v[202:205], v[114:117]
	v_mfma_f32_16x16x32_bf16 v[102:105], v[170:173], v[210:213], v[102:105]
	v_mfma_f32_16x16x32_bf16 v[98:101], v[178:181], v[210:213], v[98:101]
	v_mfma_f32_16x16x32_bf16 v[86:89], v[170:173], v[236:239], v[86:89]
	v_mfma_f32_16x16x32_bf16 v[82:85], v[178:181], v[236:239], v[82:85]
	v_mfma_f32_16x16x32_bf16 v[70:73], v[170:173], v[244:247], v[70:73]
	v_mfma_f32_16x16x32_bf16 v[66:69], v[178:181], v[244:247], v[66:69]
	s_setprio 0
	s_barrier
	s_add_i32 s53, s53, s39
	s_mov_b32 m0, s53
	ds_read_b128 v[182:185], v156 offset:16384
	ds_read_b128 v[202:205], v156 offset:17408
	ds_read_b128 v[206:209], v156 offset:18432
	ds_read_b128 v[210:213], v156 offset:19456
	ds_read_b128 v[232:235], v156 offset:20480
	ds_read_b128 v[236:239], v156 offset:21504
	ds_read_b128 v[240:243], v156 offset:22528
	ds_read_b128 v[244:247], v156 offset:23552
	s_add_u32 s60, s28, 0x80
	s_addc_u32 s61, s29, 0
	s_add_u32 s62, s30, 0x80
	s_addc_u32 s63, s31, 0
	global_load_lds_dwordx4 v132, s[28:29]
	s_add_i32 m0, s53, 0x2000
	s_add_u32 s54, s28, 0x40000
	s_addc_u32 s55, s29, 0
	s_add_i32 s53, s56, s39
	global_load_lds_dwordx4 v136, s[28:29]
	s_mov_b32 m0, s53
	s_nop 0
	global_load_lds_dwordx4 v132, s[54:55]
	s_add_i32 m0, s53, 0x2000
	s_nop 0
	global_load_lds_dwordx4 v136, s[54:55]
	s_mov_b32 m0, s40
	s_nop 0
	global_load_lds_dwordx4 v130, s[30:31]
	s_mov_b32 m0, s41
	s_nop 0
	global_load_lds_dwordx4 v134, s[30:31]
	s_waitcnt vmcnt(8)
	s_waitcnt lgkmcnt(0)
	s_barrier
; #define PG8_STAGE(bufoff, gbase, voff) do { _Pragma("unroll") for (int _i = 0; _i < 2; ++_i) \
;         __builtin_amdgcn_global_load_lds((const unsigned*)((const char*)(gbase) + (voff)[_i]), (PG8_LAS unsigned*)(lds + (bufoff) + ldsw + _i * 8192), 16, 0, 0); } while (0)
; #define PG8_LDA(dst, b, h) do { _Pragma("unroll") for (int m = 0; m < 4; ++m) _Pragma("unroll") for (int k = 0; k < 2; ++k) dst[m][k] = *(const PG8_LAS bf16x8*)(lds + PG8_SA(b, h) + aoff + m * 2048 + k * 1024); } while (0)
; #define PG8_LDB(dst, b, h) do { _Pragma("unroll") for (int n = 0; n < 2; ++n) _Pragma("unroll") for (int k = 0; k < 2; ++k) dst[n][k] = *(const PG8_LAS bf16x8*)(lds + PG8_SB(b, h) + boff + n * 2048 + k * 1024); } while (0)
; #define PG8_MMA(ai, bj, At, Bt) do { __builtin_amdgcn_s_setprio(1); _Pragma("unroll") for (int m = 0; m < 4; ++m) _Pragma("unroll") for (int n = 0; n < 2; ++n) _Pragma("unroll") for (int k = 0; k < 2; ++k) \
;         acc[ai][bj][m][n] = __builtin_amdgcn_mfma_f32_16x16x32_bf16(Bt[n][k], At[m][k], acc[ai][bj][m][n], 0, 0, 0); __builtin_amdgcn_s_setprio(0); } while (0)
; #define PG8_WAIT_V(n) asm volatile("s_waitcnt vmcnt(" #n ")" ::: "memory")
; #define PG8_WAIT_L(n) asm volatile("s_waitcnt lgkmcnt(" #n ")" ::: "memory")
; #define PG8_BAR __builtin_amdgcn_s_barrier()
; #define PG8_SCHED __builtin_amdgcn_sched_barrier(0)
; template <class Epi, class Sched, bool ALIGN_EPI = false, bool SP2 = false>
; __device__ __forceinline__ void gemm_phase(PG8_LAS unsigned char* lds, const Gemm g, const Sched& S, const Epi& E) {
;     ...
;             PG8_WAIT_V(8); PG8_WAIT_L(0); PG8_BAR; PG8_MMA(1, 0, At, B0); PG8_MMA(1, 1, At, B1); PG8_BAR; PG8_SCHED;
;             PG8_LDB(B0, 1, 0); PG8_LDB(B1, 1, 1); PG8_SCHED; PG8_LDA(At, 1, 0); PG8_STAGE(PG8_SA(0, 1), a2 + hstepA, voffA);
;             PG8_WAIT_V(8); PG8_WAIT_L(0); PG8_BAR; PG8_MMA(0, 0, At, B0); PG8_MMA(0, 1, At, B1); PG8_BAR; PG8_SCHED;
	s_setprio 1
	v_mfma_f32_16x16x32_bf16 v[62:65], v[142:145], v[182:185], v[62:65]
	v_mfma_f32_16x16x32_bf16 v[58:61], v[158:161], v[182:185], v[58:61]
	v_mfma_f32_16x16x32_bf16 v[46:49], v[142:145], v[206:209], v[46:49]
	v_mfma_f32_16x16x32_bf16 v[42:45], v[158:161], v[206:209], v[42:45]
	v_mfma_f32_16x16x32_bf16 v[30:33], v[142:145], v[232:235], v[30:33]
	v_mfma_f32_16x16x32_bf16 v[26:29], v[158:161], v[232:235], v[26:29]
	v_mfma_f32_16x16x32_bf16 v[14:17], v[142:145], v[240:243], v[14:17]
	v_mfma_f32_16x16x32_bf16 v[10:13], v[158:161], v[240:243], v[10:13]
	v_mfma_f32_16x16x32_bf16 v[62:65], v[146:149], v[202:205], v[62:65]
	v_mfma_f32_16x16x32_bf16 v[58:61], v[162:165], v[202:205], v[58:61]
	v_mfma_f32_16x16x32_bf16 v[46:49], v[146:149], v[210:213], v[46:49]
	v_mfma_f32_16x16x32_bf16 v[42:45], v[162:165], v[210:213], v[42:45]
	v_mfma_f32_16x16x32_bf16 v[30:33], v[146:149], v[236:239], v[30:33]
	v_mfma_f32_16x16x32_bf16 v[26:29], v[162:165], v[236:239], v[26:29]
	v_mfma_f32_16x16x32_bf16 v[14:17], v[146:149], v[244:247], v[14:17]
	v_mfma_f32_16x16x32_bf16 v[10:13], v[162:165], v[244:247], v[10:13]
	s_setprio 0
	s_setprio 1
	v_mfma_f32_16x16x32_bf16 v[54:57], v[166:169], v[182:185], v[54:57]
	v_mfma_f32_16x16x32_bf16 v[50:53], v[174:177], v[182:185], v[50:53]
	v_mfma_f32_16x16x32_bf16 v[38:41], v[166:169], v[206:209], v[38:41]
	v_mfma_f32_16x16x32_bf16 v[34:37], v[174:177], v[206:209], v[34:37]
	v_mfma_f32_16x16x32_bf16 v[22:25], v[166:169], v[232:235], v[22:25]
	v_mfma_f32_16x16x32_bf16 v[18:21], v[174:177], v[232:235], v[18:21]
	v_mfma_f32_16x16x32_bf16 v[6:9], v[166:169], v[240:243], v[6:9]
	v_mfma_f32_16x16x32_bf16 v[2:5], v[174:177], v[240:243], v[2:5]
	v_mfma_f32_16x16x32_bf16 v[54:57], v[170:173], v[202:205], v[54:57]
	v_mfma_f32_16x16x32_bf16 v[50:53], v[178:181], v[202:205], v[50:53]
	v_mfma_f32_16x16x32_bf16 v[38:41], v[170:173], v[210:213], v[38:41]
	v_mfma_f32_16x16x32_bf16 v[34:37], v[178:181], v[210:213], v[34:37]
	v_mfma_f32_16x16x32_bf16 v[22:25], v[170:173], v[236:239], v[22:25]
	v_mfma_f32_16x16x32_bf16 v[18:21], v[178:181], v[236:239], v[18:21]
	v_mfma_f32_16x16x32_bf16 v[6:9], v[170:173], v[244:247], v[6:9]
	v_mfma_f32_16x16x32_bf16 v[2:5], v[178:181], v[244:247], v[2:5]
	s_setprio 0
	s_barrier
	s_add_i32 s53, 0, 0x18000
	v_add_u32_e32 v157, s53, v153
	s_add_i32 s54, 0, 0x1c000
	ds_read_b128 v[142:145], v157
	ds_read_b128 v[146:149], v157 offset:1024
	ds_read_b128 v[158:161], v157 offset:2048
	ds_read_b128 v[162:165], v157 offset:3072
	v_add_u32_e32 v157, s54, v153
	ds_read_b128 v[166:169], v157
	ds_read_b128 v[170:173], v157 offset:1024
	ds_read_b128 v[174:177], v157 offset:2048
	ds_read_b128 v[178:181], v157 offset:3072
	s_add_u32 s30, s30, 0x40000
	s_addc_u32 s31, s31, 0
	s_mov_b32 m0, s42
	ds_read_b128 v[182:185], v156 offset:32768
	ds_read_b128 v[202:205], v156 offset:33792
	ds_read_b128 v[206:209], v156 offset:34816
	ds_read_b128 v[210:213], v156 offset:35840
	ds_read_b128 v[232:235], v156 offset:36864
	ds_read_b128 v[236:239], v156 offset:37888
	ds_read_b128 v[240:243], v156 offset:38912
	ds_read_b128 v[244:247], v156 offset:39936
	global_load_lds_dwordx4 v130, s[30:31]
	s_mov_b32 m0, s43
	s_nop 0
	global_load_lds_dwordx4 v134, s[30:31]
	s_waitcnt vmcnt(8)
	s_waitcnt lgkmcnt(0)
	s_barrier
	s_setprio 1
	v_mfma_f32_16x16x32_bf16 v[126:129], v[142:145], v[182:185], v[126:129]
	v_mfma_f32_16x16x32_bf16 v[122:125], v[158:161], v[182:185], v[122:125]
	v_mfma_f32_16x16x32_bf16 v[110:113], v[142:145], v[206:209], v[110:113]
	v_mfma_f32_16x16x32_bf16 v[106:109], v[158:161], v[206:209], v[106:109]
	v_mfma_f32_16x16x32_bf16 v[94:97], v[142:145], v[232:235], v[94:97]
	v_mfma_f32_16x16x32_bf16 v[90:93], v[158:161], v[232:235], v[90:93]
	v_mfma_f32_16x16x32_bf16 v[78:81], v[142:145], v[240:243], v[78:81]
	v_mfma_f32_16x16x32_bf16 v[74:77], v[158:161], v[240:243], v[74:77]
	v_mfma_f32_16x16x32_bf16 v[126:129], v[146:149], v[202:205], v[126:129]
	v_mfma_f32_16x16x32_bf16 v[122:125], v[162:165], v[202:205], v[122:125]
	v_mfma_f32_16x16x32_bf16 v[110:113], v[146:149], v[210:213], v[110:113]
	v_mfma_f32_16x16x32_bf16 v[106:109], v[162:165], v[210:213], v[106:109]
	v_mfma_f32_16x16x32_bf16 v[94:97], v[146:149], v[236:239], v[94:97]
	v_mfma_f32_16x16x32_bf16 v[90:93], v[162:165], v[236:239], v[90:93]
	v_mfma_f32_16x16x32_bf16 v[78:81], v[146:149], v[244:247], v[78:81]
	v_mfma_f32_16x16x32_bf16 v[74:77], v[162:165], v[244:247], v[74:77]
	s_setprio 0
	s_setprio 1
	v_mfma_f32_16x16x32_bf16 v[118:121], v[166:169], v[182:185], v[118:121]
	v_mfma_f32_16x16x32_bf16 v[114:117], v[174:177], v[182:185], v[114:117]
	v_mfma_f32_16x16x32_bf16 v[102:105], v[166:169], v[206:209], v[102:105]
	v_mfma_f32_16x16x32_bf16 v[98:101], v[174:177], v[206:209], v[98:101]
	v_mfma_f32_16x16x32_bf16 v[86:89], v[166:169], v[232:235], v[86:89]
	v_mfma_f32_16x16x32_bf16 v[82:85], v[174:177], v[232:235], v[82:85]
	v_mfma_f32_16x16x32_bf16 v[70:73], v[166:169], v[240:243], v[70:73]
	v_mfma_f32_16x16x32_bf16 v[66:69], v[174:177], v[240:243], v[66:69]
	v_mfma_f32_16x16x32_bf16 v[118:121], v[170:173], v[202:205], v[118:121]
	v_mfma_f32_16x16x32_bf16 v[114:117], v[178:181], v[202:205], v[114:117]
	v_mfma_f32_16x16x32_bf16 v[102:105], v[170:173], v[210:213], v[102:105]
	v_mfma_f32_16x16x32_bf16 v[98:101], v[178:181], v[210:213], v[98:101]
	v_mfma_f32_16x16x32_bf16 v[86:89], v[170:173], v[236:239], v[86:89]
	v_mfma_f32_16x16x32_bf16 v[82:85], v[178:181], v[236:239], v[82:85]
	v_mfma_f32_16x16x32_bf16 v[70:73], v[170:173], v[244:247], v[70:73]
	v_mfma_f32_16x16x32_bf16 v[66:69], v[178:181], v[244:247], v[66:69]
	s_setprio 0
	s_barrier
; #define PG8_STAGE(bufoff, gbase, voff) do { _Pragma("unroll") for (int _i = 0; _i < 2; ++_i) \
;         __builtin_amdgcn_global_load_lds((const unsigned*)((const char*)(gbase) + (voff)[_i]), (PG8_LAS unsigned*)(lds + (bufoff) + ldsw + _i * 8192), 16, 0, 0); } while (0)
; #define PG8_LDA(dst, b, h) do { _Pragma("unroll") for (int m = 0; m < 4; ++m) _Pragma("unroll") for (int k = 0; k < 2; ++k) dst[m][k] = *(const PG8_LAS bf16x8*)(lds + PG8_SA(b, h) + aoff + m * 2048 + k * 1024); } while (0)
; #define PG8_MMA(ai, bj, At, Bt) do { __builtin_amdgcn_s_setprio(1); _Pragma("unroll") for (int m = 0; m < 4; ++m) _Pragma("unroll") for (int n = 0; n < 2; ++n) _Pragma("unroll") for (int k = 0; k < 2; ++k) \
;         acc[ai][bj][m][n] = __builtin_amdgcn_mfma_f32_16x16x32_bf16(Bt[n][k], At[m][k], acc[ai][bj][m][n], 0, 0, 0); __builtin_amdgcn_s_setprio(0); } while (0)
; #define PG8_WAIT_V(n) asm volatile("s_waitcnt vmcnt(" #n ")" ::: "memory")
; #define PG8_WAIT_L(n) asm volatile("s_waitcnt lgkmcnt(" #n ")" ::: "memory")
; #define PG8_BAR __builtin_amdgcn_s_barrier()
; #define PG8_SCHED __builtin_amdgcn_sched_barrier(0)
; template <class Epi, class Sched, bool ALIGN_EPI = false, bool SP2 = false>
; __device__ __forceinline__ void gemm_phase(PG8_LAS unsigned char* lds, const Gemm g, const Sched& S, const Epi& E) {
;     ...
;             PG8_LDA(At, 1, 1); PG8_STAGE(PG8_SB(1, 0), b3, voffB); PG8_STAGE(PG8_SB(1, 1), b3 + hstepB, voffB); PG8_STAGE(PG8_SA(1, 0), a3, voffA);
;             PG8_WAIT_V(8); PG8_WAIT_L(0); PG8_BAR; PG8_MMA(1, 0, At, B0); PG8_MMA(1, 1, At, B1); PG8_BAR; PG8_SCHED;
	s_add_i32 s30, s53, s39
	s_mov_b32 m0, s30
	ds_read_b128 v[182:185], v156 offset:49152
	ds_read_b128 v[202:205], v156 offset:50176
	ds_read_b128 v[206:209], v156 offset:51200
	ds_read_b128 v[210:213], v156 offset:52224
	ds_read_b128 v[232:235], v156 offset:53248
	ds_read_b128 v[236:239], v156 offset:54272
	ds_read_b128 v[240:243], v156 offset:55296
	ds_read_b128 v[244:247], v156 offset:56320
	global_load_lds_dwordx4 v132, s[60:61]
	s_add_i32 m0, s30, 0x2000
	s_add_u32 s28, s28, 0x40080
	s_addc_u32 s29, s29, 0
	s_add_i32 s30, s54, s39
	global_load_lds_dwordx4 v136, s[60:61]
	s_mov_b32 m0, s30
	s_nop 0
	global_load_lds_dwordx4 v132, s[28:29]
	s_add_i32 m0, s30, 0x2000
	s_nop 0
	global_load_lds_dwordx4 v136, s[28:29]
	s_mov_b32 m0, s45
	s_nop 0
	global_load_lds_dwordx4 v130, s[62:63]
	s_mov_b32 m0, s46
	s_nop 0
	global_load_lds_dwordx4 v134, s[62:63]
	s_waitcnt vmcnt(8)
	s_waitcnt lgkmcnt(0)
	s_barrier
	s_setprio 1
	v_mfma_f32_16x16x32_bf16 v[62:65], v[142:145], v[182:185], v[62:65]
	v_mfma_f32_16x16x32_bf16 v[58:61], v[158:161], v[182:185], v[58:61]
	v_mfma_f32_16x16x32_bf16 v[46:49], v[142:145], v[206:209], v[46:49]
	v_mfma_f32_16x16x32_bf16 v[42:45], v[158:161], v[206:209], v[42:45]
	v_mfma_f32_16x16x32_bf16 v[30:33], v[142:145], v[232:235], v[30:33]
	v_mfma_f32_16x16x32_bf16 v[26:29], v[158:161], v[232:235], v[26:29]
	v_mfma_f32_16x16x32_bf16 v[14:17], v[142:145], v[240:243], v[14:17]
	v_mfma_f32_16x16x32_bf16 v[10:13], v[158:161], v[240:243], v[10:13]
	v_mfma_f32_16x16x32_bf16 v[62:65], v[146:149], v[202:205], v[62:65]
	v_mfma_f32_16x16x32_bf16 v[58:61], v[162:165], v[202:205], v[58:61]
	v_mfma_f32_16x16x32_bf16 v[46:49], v[146:149], v[210:213], v[46:49]
	v_mfma_f32_16x16x32_bf16 v[42:45], v[162:165], v[210:213], v[42:45]
	v_mfma_f32_16x16x32_bf16 v[30:33], v[146:149], v[236:239], v[30:33]
	v_mfma_f32_16x16x32_bf16 v[26:29], v[162:165], v[236:239], v[26:29]
	v_mfma_f32_16x16x32_bf16 v[14:17], v[146:149], v[244:247], v[14:17]
	v_mfma_f32_16x16x32_bf16 v[10:13], v[162:165], v[244:247], v[10:13]
	s_setprio 0
	s_setprio 1
	v_mfma_f32_16x16x32_bf16 v[54:57], v[166:169], v[182:185], v[54:57]
	v_mfma_f32_16x16x32_bf16 v[50:53], v[174:177], v[182:185], v[50:53]
	v_mfma_f32_16x16x32_bf16 v[38:41], v[166:169], v[206:209], v[38:41]
	v_mfma_f32_16x16x32_bf16 v[34:37], v[174:177], v[206:209], v[34:37]
	v_mfma_f32_16x16x32_bf16 v[22:25], v[166:169], v[232:235], v[22:25]
	v_mfma_f32_16x16x32_bf16 v[18:21], v[174:177], v[232:235], v[18:21]
	v_mfma_f32_16x16x32_bf16 v[6:9], v[166:169], v[240:243], v[6:9]
	v_mfma_f32_16x16x32_bf16 v[2:5], v[174:177], v[240:243], v[2:5]
	v_mfma_f32_16x16x32_bf16 v[54:57], v[170:173], v[202:205], v[54:57]
	v_mfma_f32_16x16x32_bf16 v[50:53], v[178:181], v[202:205], v[50:53]
	v_mfma_f32_16x16x32_bf16 v[38:41], v[170:173], v[210:213], v[38:41]
	v_mfma_f32_16x16x32_bf16 v[34:37], v[178:181], v[210:213], v[34:37]
	v_mfma_f32_16x16x32_bf16 v[22:25], v[170:173], v[236:239], v[22:25]
	v_mfma_f32_16x16x32_bf16 v[18:21], v[178:181], v[236:239], v[18:21]
	v_mfma_f32_16x16x32_bf16 v[6:9], v[170:173], v[244:247], v[6:9]
	v_mfma_f32_16x16x32_bf16 v[2:5], v[178:181], v[244:247], v[2:5]
	s_setprio 0
	s_barrier
	s_add_i32 s52, s52, 2
	s_add_u32 s26, s26, 0x100
	s_addc_u32 s27, s27, 0
	s_add_u32 s50, s50, 0x100
	s_addc_u32 s51, s51, 0
	s_cmp_gt_u32 s52, 13
	s_cbranch_scc0 .LBB0_254
	s_and_b64 vcc, exec, s[16:17]
	s_cbranch_vccz .LBB0_257
	s_barrier

; #define PG8_STAGE(bufoff, gbase, voff) do { _Pragma("unroll") for (int _i = 0; _i < 2; ++_i) \
;         __builtin_amdgcn_global_load_lds((const unsigned*)((const char*)(gbase) + (voff)[_i]), (PG8_LAS unsigned*)(lds + (bufoff) + ldsw + _i * 8192), 16, 0, 0); } while (0)
; #define PG8_LDA(dst, b, h) do { _Pragma("unroll") for (int m = 0; m < 4; ++m) _Pragma("unroll") for (int k = 0; k < 2; ++k) dst[m][k] = *(const PG8_LAS bf16x8*)(lds + PG8_SA(b, h) + aoff + m * 2048 + k * 1024); } while (0)
; #define PG8_LDB(dst, b, h) do { _Pragma("unroll") for (int n = 0; n < 2; ++n) _Pragma("unroll") for (int k = 0; k < 2; ++k) dst[n][k] = *(const PG8_LAS bf16x8*)(lds + PG8_SB(b, h) + boff + n * 2048 + k * 1024); } while (0)
; #define PG8_MMA(ai, bj, At, Bt) do { __builtin_amdgcn_s_setprio(1); _Pragma("unroll") for (int m = 0; m < 4; ++m) _Pragma("unroll") for (int n = 0; n < 2; ++n) _Pragma("unroll") for (int k = 0; k < 2; ++k) \
;         acc[ai][bj][m][n] = __builtin_amdgcn_mfma_f32_16x16x32_bf16(Bt[n][k], At[m][k], acc[ai][bj][m][n], 0, 0, 0); __builtin_amdgcn_s_setprio(0); } while (0)
; #define PG8_WAIT_V(n) asm volatile("s_waitcnt vmcnt(" #n ")" ::: "memory")
; #define PG8_WAIT_L(n) asm volatile("s_waitcnt lgkmcnt(" #n ")" ::: "memory")
; #define PG8_BAR __builtin_amdgcn_s_barrier()
; #define PG8_SCHED __builtin_amdgcn_sched_barrier(0)
; template <class Epi, class Sched, bool ALIGN_EPI = false, bool SP2 = false>
; __device__ __forceinline__ void gemm_phase(PG8_LAS unsigned char* lds, const Gemm g, const Sched& S, const Epi& E) {
;     ...
;             PG8_LDB(B0, 0, 0); PG8_LDB(B1, 0, 1); PG8_SCHED; PG8_LDA(At, 0, 0); PG8_STAGE(PG8_SA(1, 1), a1 + hstepA, voffA);
;             PG8_WAIT_V(8); PG8_WAIT_L(0); PG8_BAR; PG8_MMA(0, 0, At, B0); PG8_MMA(0, 1, At, B1); PG8_BAR; PG8_SCHED;
;             PG8_LDA(At, 0, 1); PG8_STAGE(PG8_SB(0, 0), b2, voffB); PG8_STAGE(PG8_SB(0, 1), b2 + hstepB, voffB); PG8_STAGE(PG8_SA(0, 0), a2, voffA);
;             PG8_WAIT_V(8); PG8_WAIT_L(0); PG8_BAR; PG8_MMA(1, 0, At, B0); PG8_MMA(1, 1, At, B1); PG8_BAR; PG8_SCHED;
.LBB0_448:
	s_add_u32 s16, s38, s14
	s_addc_u32 s17, s39, s15
	s_add_u32 s16, s16, 0x4e00100
	s_addc_u32 s17, s17, 0
	s_add_u32 s43, s40, s14
	s_addc_u32 s44, s41, s15
	s_add_i32 s45, 0, 0x10000
	v_add_u32_e32 v96, s45, v82
	ds_read_b128 v[84:87], v96
	ds_read_b128 v[88:91], v96 offset:1024
	ds_read_b128 v[92:95], v96 offset:2048
	ds_read_b128 v[96:99], v96 offset:3072
	s_cmpk_eq_i32 s14, 0x700
	s_cselect_b32 s19, s13, s17
	s_cselect_b32 s18, s12, s16
	s_cselect_b32 s17, s5, s44
	s_cselect_b32 s16, s4, s43
	v_lshl_add_u64 v[132:133], v[76:77], 0, s[14:15]
	s_add_i32 m0, s25, 0xc000
	ds_read_b128 v[100:103], v83
	ds_read_b128 v[104:107], v83 offset:1024
	ds_read_b128 v[108:111], v83 offset:2048
	ds_read_b128 v[112:115], v83 offset:3072
	ds_read_b128 v[116:119], v83 offset:4096
	ds_read_b128 v[120:123], v83 offset:5120
	ds_read_b128 v[124:127], v83 offset:6144
	ds_read_b128 v[128:131], v83 offset:7168
	global_load_lds_dwordx4 v[132:133], off
	v_lshl_add_u64 v[132:133], v[78:79], 0, s[14:15]
	s_add_i32 m0, s25, 0xe000
	s_nop 0
	global_load_lds_dwordx4 v[132:133], off
	s_waitcnt vmcnt(8)
	s_waitcnt lgkmcnt(0)
	s_barrier
	s_setprio 1
	v_mfma_f32_16x16x32_bf16 v[62:65], v[84:87], v[100:103], v[62:65]
	v_mfma_f32_16x16x32_bf16 v[58:61], v[92:95], v[100:103], v[58:61]
	v_mfma_f32_16x16x32_bf16 v[54:57], v[84:87], v[108:111], v[54:57]
	v_mfma_f32_16x16x32_bf16 v[50:53], v[92:95], v[108:111], v[50:53]
	v_mfma_f32_16x16x32_bf16 v[46:49], v[84:87], v[116:119], v[46:49]
	v_mfma_f32_16x16x32_bf16 v[42:45], v[92:95], v[116:119], v[42:45]
	v_mfma_f32_16x16x32_bf16 v[38:41], v[84:87], v[124:127], v[38:41]
	v_mfma_f32_16x16x32_bf16 v[34:37], v[92:95], v[124:127], v[34:37]
	v_mfma_f32_16x16x32_bf16 v[62:65], v[88:91], v[104:107], v[62:65]
	v_mfma_f32_16x16x32_bf16 v[58:61], v[96:99], v[104:107], v[58:61]
	v_mfma_f32_16x16x32_bf16 v[54:57], v[88:91], v[112:115], v[54:57]
	v_mfma_f32_16x16x32_bf16 v[50:53], v[96:99], v[112:115], v[50:53]
	v_mfma_f32_16x16x32_bf16 v[46:49], v[88:91], v[120:123], v[46:49]
	v_mfma_f32_16x16x32_bf16 v[42:45], v[96:99], v[120:123], v[42:45]
	v_mfma_f32_16x16x32_bf16 v[38:41], v[88:91], v[128:131], v[38:41]
	v_mfma_f32_16x16x32_bf16 v[34:37], v[96:99], v[128:131], v[34:37]
	s_setprio 0
	s_setprio 1
	s_setprio 0
	s_barrier
	s_add_i32 s43, s45, s24
	v_lshl_add_u64 v[132:133], s[16:17], 0, v[72:73]
	s_mov_b32 m0, s43
	ds_read_b128 v[100:103], v83 offset:16384
	ds_read_b128 v[104:107], v83 offset:17408
	ds_read_b128 v[108:111], v83 offset:18432
	ds_read_b128 v[112:115], v83 offset:19456
	ds_read_b128 v[116:119], v83 offset:20480
	ds_read_b128 v[120:123], v83 offset:21504
	ds_read_b128 v[124:127], v83 offset:22528
	ds_read_b128 v[128:131], v83 offset:23552
	global_load_lds_dwordx4 v[132:133], off
	s_add_i32 m0, s43, 0x2000
	s_add_u32 s44, s16, 0x40000
	v_lshl_add_u64 v[134:135], s[16:17], 0, v[68:69]
	s_addc_u32 s45, s17, 0
	global_load_lds_dwordx4 v[134:135], off
	v_lshl_add_u64 v[136:137], s[44:45], 0, v[72:73]
	s_mov_b32 m0, s26
	v_lshl_add_u64 v[138:139], s[18:19], 0, v[70:71]
	global_load_lds_dwordx4 v[136:137], off
	v_lshl_add_u64 v[136:137], s[44:45], 0, v[68:69]
	s_mov_b32 m0, s27
	s_nop 0
	global_load_lds_dwordx4 v[136:137], off
	v_lshl_add_u64 v[136:137], s[18:19], 0, v[74:75]
	s_mov_b32 m0, s25
	s_nop 0
	global_load_lds_dwordx4 v[136:137], off
	s_mov_b32 m0, s28
	s_nop 0
	global_load_lds_dwordx4 v[138:139], off
	s_waitcnt vmcnt(8)
	s_waitcnt lgkmcnt(0)
	s_barrier
	s_setprio 1
	v_mfma_f32_16x16x32_bf16 v[30:33], v[84:87], v[100:103], v[30:33]
	v_mfma_f32_16x16x32_bf16 v[26:29], v[92:95], v[100:103], v[26:29]
	v_mfma_f32_16x16x32_bf16 v[22:25], v[84:87], v[108:111], v[22:25]
	v_mfma_f32_16x16x32_bf16 v[18:21], v[92:95], v[108:111], v[18:21]
	v_mfma_f32_16x16x32_bf16 v[14:17], v[84:87], v[116:119], v[14:17]
	v_mfma_f32_16x16x32_bf16 v[10:13], v[92:95], v[116:119], v[10:13]
	v_mfma_f32_16x16x32_bf16 v[6:9], v[84:87], v[124:127], v[6:9]
	v_mfma_f32_16x16x32_bf16 v[2:5], v[92:95], v[124:127], v[2:5]
	v_mfma_f32_16x16x32_bf16 v[30:33], v[88:91], v[104:107], v[30:33]
	v_mfma_f32_16x16x32_bf16 v[26:29], v[96:99], v[104:107], v[26:29]
	v_mfma_f32_16x16x32_bf16 v[22:25], v[88:91], v[112:115], v[22:25]
	v_mfma_f32_16x16x32_bf16 v[18:21], v[96:99], v[112:115], v[18:21]
	v_mfma_f32_16x16x32_bf16 v[14:17], v[88:91], v[120:123], v[14:17]
	v_mfma_f32_16x16x32_bf16 v[10:13], v[96:99], v[120:123], v[10:13]
	v_mfma_f32_16x16x32_bf16 v[6:9], v[88:91], v[128:131], v[6:9]
	v_mfma_f32_16x16x32_bf16 v[2:5], v[96:99], v[128:131], v[2:5]
	s_setprio 0
	s_setprio 1
	s_setprio 0
	s_barrier
; #define PG8_STAGE(bufoff, gbase, voff) do { _Pragma("unroll") for (int _i = 0; _i < 2; ++_i) \
;         __builtin_amdgcn_global_load_lds((const unsigned*)((const char*)(gbase) + (voff)[_i]), (PG8_LAS unsigned*)(lds + (bufoff) + ldsw + _i * 8192), 16, 0, 0); } while (0)
; #define PG8_LDA(dst, b, h) do { _Pragma("unroll") for (int m = 0; m < 4; ++m) _Pragma("unroll") for (int k = 0; k < 2; ++k) dst[m][k] = *(const PG8_LAS bf16x8*)(lds + PG8_SA(b, h) + aoff + m * 2048 + k * 1024); } while (0)
; #define PG8_LDB(dst, b, h) do { _Pragma("unroll") for (int n = 0; n < 2; ++n) _Pragma("unroll") for (int k = 0; k < 2; ++k) dst[n][k] = *(const PG8_LAS bf16x8*)(lds + PG8_SB(b, h) + boff + n * 2048 + k * 1024); } while (0)
; #define PG8_MMA(ai, bj, At, Bt) do { __builtin_amdgcn_s_setprio(1); _Pragma("unroll") for (int m = 0; m < 4; ++m) _Pragma("unroll") for (int n = 0; n < 2; ++n) _Pragma("unroll") for (int k = 0; k < 2; ++k) \
;         acc[ai][bj][m][n] = __builtin_amdgcn_mfma_f32_16x16x32_bf16(Bt[n][k], At[m][k], acc[ai][bj][m][n], 0, 0, 0); __builtin_amdgcn_s_setprio(0); } while (0)
; #define PG8_WAIT_V(n) asm volatile("s_waitcnt vmcnt(" #n ")" ::: "memory")
; #define PG8_WAIT_L(n) asm volatile("s_waitcnt lgkmcnt(" #n ")" ::: "memory")
; #define PG8_BAR __builtin_amdgcn_s_barrier()
; #define PG8_SCHED __builtin_amdgcn_sched_barrier(0)
; template <class Epi, class Sched, bool ALIGN_EPI = false, bool SP2 = false>
; __device__ __forceinline__ void gemm_phase(PG8_LAS unsigned char* lds, const Gemm g, const Sched& S, const Epi& E) {
;     ...
;             PG8_LDB(B0, 1, 0); PG8_LDB(B1, 1, 1); PG8_SCHED; PG8_LDA(At, 1, 0); PG8_STAGE(PG8_SA(0, 1), a2 + hstepA, voffA);
;             PG8_WAIT_V(8); PG8_WAIT_L(0); PG8_BAR; PG8_MMA(0, 0, At, B0); PG8_MMA(0, 1, At, B1); PG8_BAR; PG8_SCHED;
;             PG8_LDA(At, 1, 1); PG8_STAGE(PG8_SB(1, 0), b3, voffB); PG8_STAGE(PG8_SB(1, 1), b3 + hstepB, voffB); PG8_STAGE(PG8_SA(1, 0), a3, voffA);
;             PG8_WAIT_V(8); PG8_WAIT_L(0); PG8_BAR; PG8_MMA(1, 0, At, B0); PG8_MMA(1, 1, At, B1); PG8_BAR; PG8_SCHED;
	s_add_i32 s43, 0, 0x18000
	v_add_u32_e32 v96, s43, v82
	ds_read_b128 v[84:87], v96
	ds_read_b128 v[88:91], v96 offset:1024
	ds_read_b128 v[92:95], v96 offset:2048
	ds_read_b128 v[96:99], v96 offset:3072
	s_add_u32 s18, s18, 0x40000
	s_addc_u32 s19, s19, 0
	s_mov_b32 m0, s29
	v_lshl_add_u64 v[140:141], s[18:19], 0, v[74:75]
	ds_read_b128 v[100:103], v83 offset:32768
	ds_read_b128 v[104:107], v83 offset:33792
	ds_read_b128 v[108:111], v83 offset:34816
	ds_read_b128 v[112:115], v83 offset:35840
	ds_read_b128 v[116:119], v83 offset:36864
	ds_read_b128 v[120:123], v83 offset:37888
	ds_read_b128 v[124:127], v83 offset:38912
	ds_read_b128 v[128:131], v83 offset:39936
	global_load_lds_dwordx4 v[140:141], off
	v_lshl_add_u64 v[140:141], s[18:19], 0, v[70:71]
	s_mov_b32 m0, s30
	s_nop 0
	global_load_lds_dwordx4 v[140:141], off
	s_waitcnt vmcnt(8)
	s_waitcnt lgkmcnt(0)
	s_barrier
	s_setprio 1
	v_mfma_f32_16x16x32_bf16 v[62:65], v[84:87], v[100:103], v[62:65]
	v_mfma_f32_16x16x32_bf16 v[58:61], v[92:95], v[100:103], v[58:61]
	v_mfma_f32_16x16x32_bf16 v[54:57], v[84:87], v[108:111], v[54:57]
	v_mfma_f32_16x16x32_bf16 v[50:53], v[92:95], v[108:111], v[50:53]
	v_mfma_f32_16x16x32_bf16 v[46:49], v[84:87], v[116:119], v[46:49]
	v_mfma_f32_16x16x32_bf16 v[42:45], v[92:95], v[116:119], v[42:45]
	v_mfma_f32_16x16x32_bf16 v[38:41], v[84:87], v[124:127], v[38:41]
	v_mfma_f32_16x16x32_bf16 v[34:37], v[92:95], v[124:127], v[34:37]
	v_mfma_f32_16x16x32_bf16 v[62:65], v[88:91], v[104:107], v[62:65]
	v_mfma_f32_16x16x32_bf16 v[58:61], v[96:99], v[104:107], v[58:61]
	v_mfma_f32_16x16x32_bf16 v[54:57], v[88:91], v[112:115], v[54:57]
	v_mfma_f32_16x16x32_bf16 v[50:53], v[96:99], v[112:115], v[50:53]
	v_mfma_f32_16x16x32_bf16 v[46:49], v[88:91], v[120:123], v[46:49]
	v_mfma_f32_16x16x32_bf16 v[42:45], v[96:99], v[120:123], v[42:45]
	v_mfma_f32_16x16x32_bf16 v[38:41], v[88:91], v[128:131], v[38:41]
	v_mfma_f32_16x16x32_bf16 v[34:37], v[96:99], v[128:131], v[34:37]
	s_setprio 0
	s_setprio 1
	s_setprio 0
	s_barrier
	s_add_i32 s18, s43, s24
	v_lshl_add_u64 v[132:133], v[132:133], 0, s[96:97]
	s_mov_b32 m0, s18
	ds_read_b128 v[100:103], v83 offset:49152
	ds_read_b128 v[104:107], v83 offset:50176
	ds_read_b128 v[108:111], v83 offset:51200
	ds_read_b128 v[112:115], v83 offset:52224
	ds_read_b128 v[116:119], v83 offset:53248
	ds_read_b128 v[120:123], v83 offset:54272
	ds_read_b128 v[124:127], v83 offset:55296
	ds_read_b128 v[128:131], v83 offset:56320
	global_load_lds_dwordx4 v[132:133], off
	s_add_i32 m0, s18, 0x2000
	s_add_u32 s16, s16, 0x40080
	v_lshl_add_u64 v[132:133], v[134:135], 0, s[96:97]
	s_addc_u32 s17, s17, 0
	global_load_lds_dwordx4 v[132:133], off
	v_lshl_add_u64 v[132:133], s[16:17], 0, v[72:73]
	s_mov_b32 m0, s36
	s_nop 0
	global_load_lds_dwordx4 v[132:133], off
	v_lshl_add_u64 v[132:133], s[16:17], 0, v[68:69]
	s_mov_b32 m0, s37
	s_nop 0
	global_load_lds_dwordx4 v[132:133], off
	v_lshl_add_u64 v[132:133], v[136:137], 0, s[96:97]
	s_mov_b32 m0, s34
	s_nop 0
	global_load_lds_dwordx4 v[132:133], off
	v_lshl_add_u64 v[132:133], v[138:139], 0, s[96:97]
	s_mov_b32 m0, s35
	s_nop 0
	global_load_lds_dwordx4 v[132:133], off
	s_waitcnt vmcnt(8)
	s_waitcnt lgkmcnt(0)
	s_barrier
	s_setprio 1
	v_mfma_f32_16x16x32_bf16 v[30:33], v[84:87], v[100:103], v[30:33]
	v_mfma_f32_16x16x32_bf16 v[26:29], v[92:95], v[100:103], v[26:29]
	v_mfma_f32_16x16x32_bf16 v[22:25], v[84:87], v[108:111], v[22:25]
	v_mfma_f32_16x16x32_bf16 v[18:21], v[92:95], v[108:111], v[18:21]
	v_mfma_f32_16x16x32_bf16 v[14:17], v[84:87], v[116:119], v[14:17]
	v_mfma_f32_16x16x32_bf16 v[10:13], v[92:95], v[116:119], v[10:13]
	v_mfma_f32_16x16x32_bf16 v[6:9], v[84:87], v[124:127], v[6:9]
	v_mfma_f32_16x16x32_bf16 v[2:5], v[92:95], v[124:127], v[2:5]
	v_mfma_f32_16x16x32_bf16 v[30:33], v[88:91], v[104:107], v[30:33]
	v_mfma_f32_16x16x32_bf16 v[26:29], v[96:99], v[104:107], v[26:29]
	v_mfma_f32_16x16x32_bf16 v[22:25], v[88:91], v[112:115], v[22:25]
	v_mfma_f32_16x16x32_bf16 v[18:21], v[96:99], v[112:115], v[18:21]
	v_mfma_f32_16x16x32_bf16 v[14:17], v[88:91], v[120:123], v[14:17]
	v_mfma_f32_16x16x32_bf16 v[10:13], v[96:99], v[120:123], v[10:13]
	v_mfma_f32_16x16x32_bf16 v[6:9], v[88:91], v[128:131], v[6:9]
	v_mfma_f32_16x16x32_bf16 v[2:5], v[96:99], v[128:131], v[2:5]
	s_setprio 0
	s_setprio 1
	s_setprio 0
	s_barrier
	s_add_i32 s42, s42, 2
	s_add_u32 s14, s14, 0x100
	s_addc_u32 s15, s15, 0
	s_cmp_gt_u32 s42, 13
	s_cbranch_scc0 .LBB0_448
	s_cmpk_lt_u32 s23, 0x100
	s_cbranch_scc0 .LBB0_451
	s_barrier

; #define PG8_STAGE(bufoff, gbase, voff) do { _Pragma("unroll") for (int _i = 0; _i < 2; ++_i) \
;         __builtin_amdgcn_global_load_lds((const unsigned*)((const char*)(gbase) + (voff)[_i]), (PG8_LAS unsigned*)(lds + (bufoff) + ldsw + _i * 8192), 16, 0, 0); } while (0)
; #define PG8_LDA(dst, b, h) do { _Pragma("unroll") for (int m = 0; m < 4; ++m) _Pragma("unroll") for (int k = 0; k < 2; ++k) dst[m][k] = *(const PG8_LAS bf16x8*)(lds + PG8_SA(b, h) + aoff + m * 2048 + k * 1024); } while (0)
; #define PG8_LDB(dst, b, h) do { _Pragma("unroll") for (int n = 0; n < 2; ++n) _Pragma("unroll") for (int k = 0; k < 2; ++k) dst[n][k] = *(const PG8_LAS bf16x8*)(lds + PG8_SB(b, h) + boff + n * 2048 + k * 1024); } while (0)
; #define PG8_MMA(ai, bj, At, Bt) do { __builtin_amdgcn_s_setprio(1); _Pragma("unroll") for (int m = 0; m < 4; ++m) _Pragma("unroll") for (int n = 0; n < 2; ++n) _Pragma("unroll") for (int k = 0; k < 2; ++k) \
;         acc[ai][bj][m][n] = __builtin_amdgcn_mfma_f32_16x16x32_bf16(Bt[n][k], At[m][k], acc[ai][bj][m][n], 0, 0, 0); __builtin_amdgcn_s_setprio(0); } while (0)
; #define PG8_WAIT_V(n) asm volatile("s_waitcnt vmcnt(" #n ")" ::: "memory")
; #define PG8_WAIT_L(n) asm volatile("s_waitcnt lgkmcnt(" #n ")" ::: "memory")
; #define PG8_BAR __builtin_amdgcn_s_barrier()
; #define PG8_SCHED __builtin_amdgcn_sched_barrier(0)
; template <class Epi, class Sched, bool ALIGN_EPI = false, bool SP2 = false>
; __device__ __forceinline__ void gemm_phase(PG8_LAS unsigned char* lds, const Gemm g, const Sched& S, const Epi& E) {
;     ...
;             PG8_LDB(B0, 0, 0); PG8_LDB(B1, 0, 1); PG8_SCHED; PG8_LDA(At, 0, 0); PG8_STAGE(PG8_SA(1, 1), a1 + hstepA, voffA);
;             PG8_WAIT_V(8); PG8_WAIT_L(0); PG8_BAR; PG8_MMA(0, 0, At, B0); PG8_MMA(0, 1, At, B1); PG8_BAR; PG8_SCHED;
;             PG8_LDA(At, 0, 1); PG8_STAGE(PG8_SB(0, 0), b2, voffB); PG8_STAGE(PG8_SB(0, 1), b2 + hstepB, voffB); PG8_STAGE(PG8_SA(0, 0), a2, voffA);
.LBB0_530:
	s_add_u32 s12, s1, s8
	s_addc_u32 s13, s28, s9
	s_add_u32 s12, s12, 0xfe00100
	s_addc_u32 s13, s13, 0
	s_add_u32 s34, s29, s8
	s_addc_u32 s35, s30, s9
	s_add_i32 s36, 0, 0x10000
	s_cmpk_eq_i32 s8, 0x700
	s_cselect_b32 s15, s7, s13
	s_cselect_b32 s14, s6, s12
	v_add_u32_e32 v145, s36, v143
	s_cselect_b32 s13, s5, s35
	s_cselect_b32 s12, s4, s34
	s_add_i32 s37, 0, 0x14000
	ds_read_b128 v[146:149], v145
	ds_read_b128 v[150:153], v145 offset:1024
	ds_read_b128 v[154:157], v145 offset:2048
	ds_read_b128 v[158:161], v145 offset:3072
	v_add_u32_e32 v145, s37, v143
	ds_read_b128 v[162:165], v145
	ds_read_b128 v[166:169], v145 offset:1024
	ds_read_b128 v[170:173], v145 offset:2048
	ds_read_b128 v[174:177], v145 offset:3072
	v_lshl_add_u64 v[186:187], v[138:139], 0, s[8:9]
	s_add_i32 m0, s21, 0xc000
	ds_read_b128 v[178:181], v144
	ds_read_b128 v[182:185], v144 offset:1024
	ds_read_b128 v[202:205], v144 offset:2048
	ds_read_b128 v[206:209], v144 offset:3072
	ds_read_b128 v[210:213], v144 offset:4096
	ds_read_b128 v[232:235], v144 offset:5120
	ds_read_b128 v[236:239], v144 offset:6144
	ds_read_b128 v[240:243], v144 offset:7168
	global_load_lds_dwordx4 v[186:187], off
	v_lshl_add_u64 v[186:187], v[140:141], 0, s[8:9]
	s_add_i32 m0, s21, 0xe000
	s_nop 0
	global_load_lds_dwordx4 v[186:187], off
	s_waitcnt vmcnt(8)
	s_waitcnt lgkmcnt(0)
	s_barrier
	s_setprio 1
	v_mfma_f32_16x16x32_bf16 v[126:129], v[146:149], v[178:181], v[126:129]
	v_mfma_f32_16x16x32_bf16 v[122:125], v[154:157], v[178:181], v[122:125]
	v_mfma_f32_16x16x32_bf16 v[118:121], v[146:149], v[202:205], v[118:121]
	v_mfma_f32_16x16x32_bf16 v[114:117], v[154:157], v[202:205], v[114:117]
	v_mfma_f32_16x16x32_bf16 v[110:113], v[146:149], v[210:213], v[110:113]
	v_mfma_f32_16x16x32_bf16 v[106:109], v[154:157], v[210:213], v[106:109]
	v_mfma_f32_16x16x32_bf16 v[102:105], v[146:149], v[236:239], v[102:105]
	v_mfma_f32_16x16x32_bf16 v[98:101], v[154:157], v[236:239], v[98:101]
	v_mfma_f32_16x16x32_bf16 v[126:129], v[150:153], v[182:185], v[126:129]
	v_mfma_f32_16x16x32_bf16 v[122:125], v[158:161], v[182:185], v[122:125]
	v_mfma_f32_16x16x32_bf16 v[118:121], v[150:153], v[206:209], v[118:121]
	v_mfma_f32_16x16x32_bf16 v[114:117], v[158:161], v[206:209], v[114:117]
	v_mfma_f32_16x16x32_bf16 v[110:113], v[150:153], v[232:235], v[110:113]
	v_mfma_f32_16x16x32_bf16 v[106:109], v[158:161], v[232:235], v[106:109]
	v_mfma_f32_16x16x32_bf16 v[102:105], v[150:153], v[240:243], v[102:105]
	v_mfma_f32_16x16x32_bf16 v[98:101], v[158:161], v[240:243], v[98:101]
	s_setprio 0
	s_setprio 1
	v_mfma_f32_16x16x32_bf16 v[94:97], v[162:165], v[178:181], v[94:97]
	v_mfma_f32_16x16x32_bf16 v[86:89], v[170:173], v[178:181], v[86:89]
	v_mfma_f32_16x16x32_bf16 v[78:81], v[162:165], v[202:205], v[78:81]
	v_mfma_f32_16x16x32_bf16 v[74:77], v[170:173], v[202:205], v[74:77]
	v_mfma_f32_16x16x32_bf16 v[70:73], v[162:165], v[210:213], v[70:73]
	v_mfma_f32_16x16x32_bf16 v[62:65], v[170:173], v[210:213], v[62:65]
	v_mfma_f32_16x16x32_bf16 v[54:57], v[162:165], v[236:239], v[54:57]
	v_mfma_f32_16x16x32_bf16 v[50:53], v[170:173], v[236:239], v[50:53]
	v_mfma_f32_16x16x32_bf16 v[94:97], v[166:169], v[182:185], v[94:97]
	v_mfma_f32_16x16x32_bf16 v[86:89], v[174:177], v[182:185], v[86:89]
	v_mfma_f32_16x16x32_bf16 v[78:81], v[166:169], v[206:209], v[78:81]
	v_mfma_f32_16x16x32_bf16 v[74:77], v[174:177], v[206:209], v[74:77]
	v_mfma_f32_16x16x32_bf16 v[70:73], v[166:169], v[232:235], v[70:73]
	v_mfma_f32_16x16x32_bf16 v[62:65], v[174:177], v[232:235], v[62:65]
	v_mfma_f32_16x16x32_bf16 v[54:57], v[166:169], v[240:243], v[54:57]
	v_mfma_f32_16x16x32_bf16 v[50:53], v[174:177], v[240:243], v[50:53]
	s_setprio 0
	s_barrier
	s_add_i32 s34, s36, s20
	s_mov_b32 m0, s34
	ds_read_b128 v[178:181], v144 offset:16384
	ds_read_b128 v[182:185], v144 offset:17408
	ds_read_b128 v[202:205], v144 offset:18432
	ds_read_b128 v[206:209], v144 offset:19456
	ds_read_b128 v[210:213], v144 offset:20480
	ds_read_b128 v[232:235], v144 offset:21504
	ds_read_b128 v[236:239], v144 offset:22528
	ds_read_b128 v[240:243], v144 offset:23552
	s_add_u32 s60, s12, 0x80
	s_addc_u32 s61, s13, 0
	s_add_u32 s62, s14, 0x80
	s_addc_u32 s63, s15, 0
	global_load_lds_dwordx4 v134, s[12:13]
	s_add_i32 m0, s34, 0x2000
	s_add_u32 s34, s12, 0x80000
	s_addc_u32 s35, s13, 0
	s_add_i32 s36, s37, s20
	global_load_lds_dwordx4 v130, s[12:13]
	s_mov_b32 m0, s36
	s_nop 0
	global_load_lds_dwordx4 v134, s[34:35]
	s_add_i32 m0, s36, 0x2000
	s_nop 0
	global_load_lds_dwordx4 v130, s[34:35]
	s_mov_b32 m0, s21
	s_nop 0
	global_load_lds_dwordx4 v136, s[14:15]
	s_mov_b32 m0, s22
	s_nop 0
	global_load_lds_dwordx4 v132, s[14:15]
	s_waitcnt vmcnt(8)
	s_waitcnt lgkmcnt(0)
	s_barrier
; #define PG8_STAGE(bufoff, gbase, voff) do { _Pragma("unroll") for (int _i = 0; _i < 2; ++_i) \
;         __builtin_amdgcn_global_load_lds((const unsigned*)((const char*)(gbase) + (voff)[_i]), (PG8_LAS unsigned*)(lds + (bufoff) + ldsw + _i * 8192), 16, 0, 0); } while (0)
; #define PG8_LDA(dst, b, h) do { _Pragma("unroll") for (int m = 0; m < 4; ++m) _Pragma("unroll") for (int k = 0; k < 2; ++k) dst[m][k] = *(const PG8_LAS bf16x8*)(lds + PG8_SA(b, h) + aoff + m * 2048 + k * 1024); } while (0)
; #define PG8_LDB(dst, b, h) do { _Pragma("unroll") for (int n = 0; n < 2; ++n) _Pragma("unroll") for (int k = 0; k < 2; ++k) dst[n][k] = *(const PG8_LAS bf16x8*)(lds + PG8_SB(b, h) + boff + n * 2048 + k * 1024); } while (0)
; #define PG8_MMA(ai, bj, At, Bt) do { __builtin_amdgcn_s_setprio(1); _Pragma("unroll") for (int m = 0; m < 4; ++m) _Pragma("unroll") for (int n = 0; n < 2; ++n) _Pragma("unroll") for (int k = 0; k < 2; ++k) \
;         acc[ai][bj][m][n] = __builtin_amdgcn_mfma_f32_16x16x32_bf16(Bt[n][k], At[m][k], acc[ai][bj][m][n], 0, 0, 0); __builtin_amdgcn_s_setprio(0); } while (0)
; #define PG8_WAIT_V(n) asm volatile("s_waitcnt vmcnt(" #n ")" ::: "memory")
; #define PG8_WAIT_L(n) asm volatile("s_waitcnt lgkmcnt(" #n ")" ::: "memory")
; #define PG8_BAR __builtin_amdgcn_s_barrier()
; #define PG8_SCHED __builtin_amdgcn_sched_barrier(0)
; template <class Epi, class Sched, bool ALIGN_EPI = false, bool SP2 = false>
; __device__ __forceinline__ void gemm_phase(PG8_LAS unsigned char* lds, const Gemm g, const Sched& S, const Epi& E) {
;     ...
;             PG8_WAIT_V(8); PG8_WAIT_L(0); PG8_BAR; PG8_MMA(1, 0, At, B0); PG8_MMA(1, 1, At, B1); PG8_BAR; PG8_SCHED;
;             PG8_LDB(B0, 1, 0); PG8_LDB(B1, 1, 1); PG8_SCHED; PG8_LDA(At, 1, 0); PG8_STAGE(PG8_SA(0, 1), a2 + hstepA, voffA);
;             PG8_WAIT_V(8); PG8_WAIT_L(0); PG8_BAR; PG8_MMA(0, 0, At, B0); PG8_MMA(0, 1, At, B1); PG8_BAR; PG8_SCHED;
	s_setprio 1
	v_mfma_f32_16x16x32_bf16 v[90:93], v[146:149], v[178:181], v[90:93]
	v_mfma_f32_16x16x32_bf16 v[82:85], v[154:157], v[178:181], v[82:85]
	v_mfma_f32_16x16x32_bf16 v[66:69], v[146:149], v[202:205], v[66:69]
	v_mfma_f32_16x16x32_bf16 v[58:61], v[154:157], v[202:205], v[58:61]
	v_mfma_f32_16x16x32_bf16 v[46:49], v[146:149], v[210:213], v[46:49]
	v_mfma_f32_16x16x32_bf16 v[42:45], v[154:157], v[210:213], v[42:45]
	v_mfma_f32_16x16x32_bf16 v[38:41], v[146:149], v[236:239], v[38:41]
	v_mfma_f32_16x16x32_bf16 v[34:37], v[154:157], v[236:239], v[34:37]
	v_mfma_f32_16x16x32_bf16 v[90:93], v[150:153], v[182:185], v[90:93]
	v_mfma_f32_16x16x32_bf16 v[82:85], v[158:161], v[182:185], v[82:85]
	v_mfma_f32_16x16x32_bf16 v[66:69], v[150:153], v[206:209], v[66:69]
	v_mfma_f32_16x16x32_bf16 v[58:61], v[158:161], v[206:209], v[58:61]
	v_mfma_f32_16x16x32_bf16 v[46:49], v[150:153], v[232:235], v[46:49]
	v_mfma_f32_16x16x32_bf16 v[42:45], v[158:161], v[232:235], v[42:45]
	v_mfma_f32_16x16x32_bf16 v[38:41], v[150:153], v[240:243], v[38:41]
	v_mfma_f32_16x16x32_bf16 v[34:37], v[158:161], v[240:243], v[34:37]
	s_setprio 0
	s_setprio 1
	v_mfma_f32_16x16x32_bf16 v[30:33], v[162:165], v[178:181], v[30:33]
	v_mfma_f32_16x16x32_bf16 v[26:29], v[170:173], v[178:181], v[26:29]
	v_mfma_f32_16x16x32_bf16 v[22:25], v[162:165], v[202:205], v[22:25]
	v_mfma_f32_16x16x32_bf16 v[18:21], v[170:173], v[202:205], v[18:21]
	v_mfma_f32_16x16x32_bf16 v[14:17], v[162:165], v[210:213], v[14:17]
	v_mfma_f32_16x16x32_bf16 v[10:13], v[170:173], v[210:213], v[10:13]
	v_mfma_f32_16x16x32_bf16 v[6:9], v[162:165], v[236:239], v[6:9]
	v_mfma_f32_16x16x32_bf16 v[2:5], v[170:173], v[236:239], v[2:5]
	v_mfma_f32_16x16x32_bf16 v[30:33], v[166:169], v[182:185], v[30:33]
	v_mfma_f32_16x16x32_bf16 v[26:29], v[174:177], v[182:185], v[26:29]
	v_mfma_f32_16x16x32_bf16 v[22:25], v[166:169], v[206:209], v[22:25]
	v_mfma_f32_16x16x32_bf16 v[18:21], v[174:177], v[206:209], v[18:21]
	v_mfma_f32_16x16x32_bf16 v[14:17], v[166:169], v[232:235], v[14:17]
	v_mfma_f32_16x16x32_bf16 v[10:13], v[174:177], v[232:235], v[10:13]
	v_mfma_f32_16x16x32_bf16 v[6:9], v[166:169], v[240:243], v[6:9]
	v_mfma_f32_16x16x32_bf16 v[2:5], v[174:177], v[240:243], v[2:5]
	s_setprio 0
	s_barrier
	s_add_i32 s34, 0, 0x18000
	v_add_u32_e32 v145, s34, v143
	s_add_i32 s35, 0, 0x1c000
	ds_read_b128 v[146:149], v145
	ds_read_b128 v[150:153], v145 offset:1024
	ds_read_b128 v[154:157], v145 offset:2048
	ds_read_b128 v[158:161], v145 offset:3072
	v_add_u32_e32 v145, s35, v143
	ds_read_b128 v[162:165], v145
	ds_read_b128 v[166:169], v145 offset:1024
	ds_read_b128 v[170:173], v145 offset:2048
	ds_read_b128 v[174:177], v145 offset:3072
	s_add_u32 s14, s14, 0x40000
	s_addc_u32 s15, s15, 0
	s_mov_b32 m0, s23
	ds_read_b128 v[178:181], v144 offset:32768
	ds_read_b128 v[182:185], v144 offset:33792
	ds_read_b128 v[202:205], v144 offset:34816
	ds_read_b128 v[206:209], v144 offset:35840
	ds_read_b128 v[210:213], v144 offset:36864
	ds_read_b128 v[232:235], v144 offset:37888
	ds_read_b128 v[236:239], v144 offset:38912
	ds_read_b128 v[240:243], v144 offset:39936
	global_load_lds_dwordx4 v136, s[14:15]
	s_mov_b32 m0, s24
	s_nop 0
	global_load_lds_dwordx4 v132, s[14:15]
	s_waitcnt vmcnt(8)
	s_waitcnt lgkmcnt(0)
	s_barrier
	s_setprio 1
	v_mfma_f32_16x16x32_bf16 v[126:129], v[146:149], v[178:181], v[126:129]
	v_mfma_f32_16x16x32_bf16 v[122:125], v[154:157], v[178:181], v[122:125]
	v_mfma_f32_16x16x32_bf16 v[118:121], v[146:149], v[202:205], v[118:121]
	v_mfma_f32_16x16x32_bf16 v[114:117], v[154:157], v[202:205], v[114:117]
	v_mfma_f32_16x16x32_bf16 v[110:113], v[146:149], v[210:213], v[110:113]
	v_mfma_f32_16x16x32_bf16 v[106:109], v[154:157], v[210:213], v[106:109]
	v_mfma_f32_16x16x32_bf16 v[102:105], v[146:149], v[236:239], v[102:105]
	v_mfma_f32_16x16x32_bf16 v[98:101], v[154:157], v[236:239], v[98:101]
	v_mfma_f32_16x16x32_bf16 v[126:129], v[150:153], v[182:185], v[126:129]
	v_mfma_f32_16x16x32_bf16 v[122:125], v[158:161], v[182:185], v[122:125]
	v_mfma_f32_16x16x32_bf16 v[118:121], v[150:153], v[206:209], v[118:121]
	v_mfma_f32_16x16x32_bf16 v[114:117], v[158:161], v[206:209], v[114:117]
	v_mfma_f32_16x16x32_bf16 v[110:113], v[150:153], v[232:235], v[110:113]
	v_mfma_f32_16x16x32_bf16 v[106:109], v[158:161], v[232:235], v[106:109]
	v_mfma_f32_16x16x32_bf16 v[102:105], v[150:153], v[240:243], v[102:105]
	v_mfma_f32_16x16x32_bf16 v[98:101], v[158:161], v[240:243], v[98:101]
	s_setprio 0
	s_setprio 1
	v_mfma_f32_16x16x32_bf16 v[94:97], v[162:165], v[178:181], v[94:97]
	v_mfma_f32_16x16x32_bf16 v[86:89], v[170:173], v[178:181], v[86:89]
	v_mfma_f32_16x16x32_bf16 v[78:81], v[162:165], v[202:205], v[78:81]
	v_mfma_f32_16x16x32_bf16 v[74:77], v[170:173], v[202:205], v[74:77]
	v_mfma_f32_16x16x32_bf16 v[70:73], v[162:165], v[210:213], v[70:73]
	v_mfma_f32_16x16x32_bf16 v[62:65], v[170:173], v[210:213], v[62:65]
	v_mfma_f32_16x16x32_bf16 v[54:57], v[162:165], v[236:239], v[54:57]
	v_mfma_f32_16x16x32_bf16 v[50:53], v[170:173], v[236:239], v[50:53]
	v_mfma_f32_16x16x32_bf16 v[94:97], v[166:169], v[182:185], v[94:97]
	v_mfma_f32_16x16x32_bf16 v[86:89], v[174:177], v[182:185], v[86:89]
	v_mfma_f32_16x16x32_bf16 v[78:81], v[166:169], v[206:209], v[78:81]
	v_mfma_f32_16x16x32_bf16 v[74:77], v[174:177], v[206:209], v[74:77]
	v_mfma_f32_16x16x32_bf16 v[70:73], v[166:169], v[232:235], v[70:73]
	v_mfma_f32_16x16x32_bf16 v[62:65], v[174:177], v[232:235], v[62:65]
	v_mfma_f32_16x16x32_bf16 v[54:57], v[166:169], v[240:243], v[54:57]
	v_mfma_f32_16x16x32_bf16 v[50:53], v[174:177], v[240:243], v[50:53]
	s_setprio 0
	s_barrier
; #define PG8_STAGE(bufoff, gbase, voff) do { _Pragma("unroll") for (int _i = 0; _i < 2; ++_i) \
;         __builtin_amdgcn_global_load_lds((const unsigned*)((const char*)(gbase) + (voff)[_i]), (PG8_LAS unsigned*)(lds + (bufoff) + ldsw + _i * 8192), 16, 0, 0); } while (0)
; #define PG8_LDA(dst, b, h) do { _Pragma("unroll") for (int m = 0; m < 4; ++m) _Pragma("unroll") for (int k = 0; k < 2; ++k) dst[m][k] = *(const PG8_LAS bf16x8*)(lds + PG8_SA(b, h) + aoff + m * 2048 + k * 1024); } while (0)
; #define PG8_MMA(ai, bj, At, Bt) do { __builtin_amdgcn_s_setprio(1); _Pragma("unroll") for (int m = 0; m < 4; ++m) _Pragma("unroll") for (int n = 0; n < 2; ++n) _Pragma("unroll") for (int k = 0; k < 2; ++k) \
;         acc[ai][bj][m][n] = __builtin_amdgcn_mfma_f32_16x16x32_bf16(Bt[n][k], At[m][k], acc[ai][bj][m][n], 0, 0, 0); __builtin_amdgcn_s_setprio(0); } while (0)
; #define PG8_WAIT_V(n) asm volatile("s_waitcnt vmcnt(" #n ")" ::: "memory")
; #define PG8_WAIT_L(n) asm volatile("s_waitcnt lgkmcnt(" #n ")" ::: "memory")
; #define PG8_BAR __builtin_amdgcn_s_barrier()
; #define PG8_SCHED __builtin_amdgcn_sched_barrier(0)
; template <class Epi, class Sched, bool ALIGN_EPI = false, bool SP2 = false>
; __device__ __forceinline__ void gemm_phase(PG8_LAS unsigned char* lds, const Gemm g, const Sched& S, const Epi& E) {
;     ...
;             PG8_LDA(At, 1, 1); PG8_STAGE(PG8_SB(1, 0), b3, voffB); PG8_STAGE(PG8_SB(1, 1), b3 + hstepB, voffB); PG8_STAGE(PG8_SA(1, 0), a3, voffA);
;             PG8_WAIT_V(8); PG8_WAIT_L(0); PG8_BAR; PG8_MMA(1, 0, At, B0); PG8_MMA(1, 1, At, B1); PG8_BAR; PG8_SCHED;
	s_add_i32 s14, s34, s20
	s_mov_b32 m0, s14
	ds_read_b128 v[178:181], v144 offset:49152
	ds_read_b128 v[182:185], v144 offset:50176
	ds_read_b128 v[202:205], v144 offset:51200
	ds_read_b128 v[206:209], v144 offset:52224
	ds_read_b128 v[210:213], v144 offset:53248
	ds_read_b128 v[232:235], v144 offset:54272
	ds_read_b128 v[236:239], v144 offset:55296
	ds_read_b128 v[240:243], v144 offset:56320
	global_load_lds_dwordx4 v134, s[60:61]
	s_add_i32 m0, s14, 0x2000
	s_add_u32 s12, s12, 0x80080
	s_addc_u32 s13, s13, 0
	s_add_i32 s14, s35, s20
	global_load_lds_dwordx4 v130, s[60:61]
	s_mov_b32 m0, s14
	s_nop 0
	global_load_lds_dwordx4 v134, s[12:13]
	s_add_i32 m0, s14, 0x2000
	s_nop 0
	global_load_lds_dwordx4 v130, s[12:13]
	s_mov_b32 m0, s26
	s_nop 0
	global_load_lds_dwordx4 v136, s[62:63]
	s_mov_b32 m0, s27
	s_nop 0
	global_load_lds_dwordx4 v132, s[62:63]
	s_waitcnt vmcnt(8)
	s_waitcnt lgkmcnt(0)
	s_barrier
	s_setprio 1
	v_mfma_f32_16x16x32_bf16 v[90:93], v[146:149], v[178:181], v[90:93]
	v_mfma_f32_16x16x32_bf16 v[82:85], v[154:157], v[178:181], v[82:85]
	v_mfma_f32_16x16x32_bf16 v[66:69], v[146:149], v[202:205], v[66:69]
	v_mfma_f32_16x16x32_bf16 v[58:61], v[154:157], v[202:205], v[58:61]
	v_mfma_f32_16x16x32_bf16 v[46:49], v[146:149], v[210:213], v[46:49]
	v_mfma_f32_16x16x32_bf16 v[42:45], v[154:157], v[210:213], v[42:45]
	v_mfma_f32_16x16x32_bf16 v[38:41], v[146:149], v[236:239], v[38:41]
	v_mfma_f32_16x16x32_bf16 v[34:37], v[154:157], v[236:239], v[34:37]
	v_mfma_f32_16x16x32_bf16 v[90:93], v[150:153], v[182:185], v[90:93]
	v_mfma_f32_16x16x32_bf16 v[82:85], v[158:161], v[182:185], v[82:85]
	v_mfma_f32_16x16x32_bf16 v[66:69], v[150:153], v[206:209], v[66:69]
	v_mfma_f32_16x16x32_bf16 v[58:61], v[158:161], v[206:209], v[58:61]
	v_mfma_f32_16x16x32_bf16 v[46:49], v[150:153], v[232:235], v[46:49]
	v_mfma_f32_16x16x32_bf16 v[42:45], v[158:161], v[232:235], v[42:45]
	v_mfma_f32_16x16x32_bf16 v[38:41], v[150:153], v[240:243], v[38:41]
	v_mfma_f32_16x16x32_bf16 v[34:37], v[158:161], v[240:243], v[34:37]
	s_setprio 0
	s_setprio 1
	v_mfma_f32_16x16x32_bf16 v[30:33], v[162:165], v[178:181], v[30:33]
	v_mfma_f32_16x16x32_bf16 v[26:29], v[170:173], v[178:181], v[26:29]
	v_mfma_f32_16x16x32_bf16 v[22:25], v[162:165], v[202:205], v[22:25]
	v_mfma_f32_16x16x32_bf16 v[18:21], v[170:173], v[202:205], v[18:21]
	v_mfma_f32_16x16x32_bf16 v[14:17], v[162:165], v[210:213], v[14:17]
	v_mfma_f32_16x16x32_bf16 v[10:13], v[170:173], v[210:213], v[10:13]
	v_mfma_f32_16x16x32_bf16 v[6:9], v[162:165], v[236:239], v[6:9]
	v_mfma_f32_16x16x32_bf16 v[2:5], v[170:173], v[236:239], v[2:5]
	v_mfma_f32_16x16x32_bf16 v[30:33], v[166:169], v[182:185], v[30:33]
	v_mfma_f32_16x16x32_bf16 v[26:29], v[174:177], v[182:185], v[26:29]
	v_mfma_f32_16x16x32_bf16 v[22:25], v[166:169], v[206:209], v[22:25]
	v_mfma_f32_16x16x32_bf16 v[18:21], v[174:177], v[206:209], v[18:21]
	v_mfma_f32_16x16x32_bf16 v[14:17], v[166:169], v[232:235], v[14:17]
	v_mfma_f32_16x16x32_bf16 v[10:13], v[174:177], v[232:235], v[10:13]
	v_mfma_f32_16x16x32_bf16 v[6:9], v[166:169], v[240:243], v[6:9]
	v_mfma_f32_16x16x32_bf16 v[2:5], v[174:177], v[240:243], v[2:5]
	s_setprio 0
	s_barrier
	s_add_i32 s31, s31, 2
	s_add_u32 s8, s8, 0x100
	s_addc_u32 s9, s9, 0
	s_cmp_gt_u32 s31, 13
	s_cbranch_scc0 .LBB0_530
	s_cmpk_lt_u32 s19, 0x100
	s_cbranch_scc0 .LBB0_533
	s_barrier

; #define PG8_WAIT_V(n) asm volatile("s_waitcnt vmcnt(" #n ")" ::: "memory")
; #define PG8_BAR __builtin_amdgcn_s_barrier()
; template <class Epi, class Sched, bool ALIGN_EPI = false, bool SP2 = false>
; __device__ __forceinline__ void gemm_phase(PG8_LAS unsigned char* lds, const Gemm g, const Sched& S, const Epi& E) {
;     ...
;         PG8_STAGE(PG8_SB(0, 0), cB, voffB); PG8_STAGE(PG8_SB(0, 1), cB + hstepB, voffB); PG8_STAGE(PG8_SA(0, 0), cA, voffA); PG8_STAGE(PG8_SA(0, 1), cA + hstepA, voffA);
;         if (wr == 1) PG8_BAR;
;         PG8_WAIT_V(2); PG8_BAR;
;         PG8_STAGE(PG8_SB(1, 0), cB + kstep, voffB); PG8_STAGE(PG8_SA(1, 0), cA + kstep, voffA); PG8_STAGE(PG8_SB(1, 1), cB + hstepB + kstep, voffB);
;         PG8_WAIT_V(6); PG8_BAR;
;     } else {
;         PG8_STAGE(PG8_SB(0, 0), cB, voffB); PG8_STAGE(PG8_SA(0, 0), cA, voffA); PG8_STAGE(PG8_SB(0, 1), cB + hstepB, voffB); PG8_STAGE(PG8_SA(0, 1), cA + hstepA, voffA);
;         if (wr == 1) PG8_BAR;
;         PG8_WAIT_V(4); PG8_BAR;
;         PG8_STAGE(PG8_SB(1, 0), cB + kstep, voffB); PG8_STAGE(PG8_SA(1, 0), cA + kstep, voffA); PG8_STAGE(PG8_SB(1, 1), cB + hstepB + kstep, voffB);
;         PG8_WAIT_V(6); PG8_BAR;
;     }
;     for (;;) {
;         const bool has_next = S.next(ui + 1, nxt);
;         const char* nA = has_next ? (const char*)g.A + (size_t)nxt.pm * tstepA : cA; const char* nB = has_next ? (const char*)g.Bt + (size_t)nxt.pn * tstepB : cB;
;         for (int t = 0; t < nt; t += 2) {
;             const bool last = (t == nt - 2);
;             const char* a1 = cA + (size_t)(t + 1) * kstep;
;             const char* a2 = last ? nA : cA + (size_t)(t + 2) * kstep; const char* b2 = last ? nB : cB + (size_t)(t + 2) * kstep;
;             const char* a3 = a2 + kstep; const char* b3 = b2 + kstep;
;             if (last && has_next) S.a_ready(nxt);
;             if constexpr (SP2) {
;             PG8_LDB(B0, 0, 0); PG8_LDB(B1, 0, 1); PG8_SCHED; PG8_LDA(At, 0, 0); PG8_STAGE(PG8_SA(1, 1), a1 + hstepA, voffA);
;             PG8_WAIT_V(8); PG8_WAIT_L(0); PG8_BAR; PG8_MMA(0, 0, At, B0); PG8_MMA(0, 1, At, B1); PG8_BAR; PG8_SCHED;
;             PG8_LDA(At, 0, 1); PG8_STAGE(PG8_SB(0, 0), b2, voffB); PG8_STAGE(PG8_SB(0, 1), b2 + hstepB, voffB); PG8_STAGE(PG8_SA(0, 0), a2, voffA);
;             PG8_WAIT_V(8); PG8_WAIT_L(0); PG8_BAR; PG8_MMA(1, 0, At, B0); PG8_MMA(1, 1, At, B1); PG8_BAR; PG8_SCHED;
.LBB0_592:
	s_add_i32 s44, 0, 0x18000
	s_add_i32 s36, s44, s14
	s_and_b32 s28, s15, 3
	v_lshl_add_u64 v[26:27], v[4:5], 0, s[96:97]
	s_mov_b32 m0, s36
	s_add_i32 s38, s36, 0x2000
	s_lshl_b32 s15, s26, 13
	s_lshl_b32 s43, s28, 12
	s_waitcnt vmcnt(2)
	s_barrier
	global_load_lds_dwordx4 v[26:27], off
	v_lshl_add_u64 v[28:29], v[6:7], 0, s[96:97]
	s_mov_b32 m0, s38
	s_add_i32 s37, s27, 0x8000
	s_add_i32 s39, s27, 0xa000
	global_load_lds_dwordx4 v[28:29], off
	v_lshl_add_u64 v[24:25], v[18:19], 0, s[96:97]
	s_mov_b32 m0, s37
	s_add_u32 s16, s8, 0x10080
	global_load_lds_dwordx4 v[24:25], off
	v_lshl_add_u64 v[30:31], v[22:23], 0, s[96:97]
	s_mov_b32 m0, s39
	s_addc_u32 s17, s9, 0
	s_add_i32 s40, s27, 0x1c000
	global_load_lds_dwordx4 v[30:31], off
	v_lshl_add_u64 v[68:69], s[16:17], 0, v[32:33]
	s_mov_b32 m0, s40
	s_add_i32 s41, s27, 0x1e000
	global_load_lds_dwordx4 v[68:69], off
	v_lshl_add_u64 v[70:71], s[16:17], 0, v[20:21]
	s_mov_b32 m0, s41
	v_lshrrev_b32_e32 v35, 1, v34
	global_load_lds_dwordx4 v[70:71], off
	v_and_b32_e32 v72, 24, v35
	v_and_b32_e32 v67, 15, v34
	v_lshlrev_b32_e32 v35, 1, v72
	v_lshlrev_b32_e32 v34, 2, v34
	v_lshl_or_b32 v35, v67, 6, v35
	v_and_b32_e32 v34, 32, v34
	v_bitop3_b32 v36, v35, s15, v34 bitop3:0xde
	s_add_i32 s15, 0, 0x10000
	v_bitop3_b32 v34, v35, s43, v34 bitop3:0xde
	s_add_u32 s48, s12, 0x10080
	v_add_u32_e32 v157, s44, v34
	s_addc_u32 s49, s13, 0
	s_add_i32 s44, s15, s14
	s_add_i32 s46, s27, 0xc000
	s_add_i32 s45, s27, 0xe000
	s_add_i32 s43, s44, 0x2000
	v_add_u32_e32 v73, s15, v34
	s_add_u32 s50, s8, 0x10100
	s_waitcnt vmcnt(6)
	s_barrier
	v_add_u32_e32 v156, 0, v36
	s_addc_u32 s51, s9, 0
	ds_read_b128 v[34:37], v73
	ds_read_b128 v[38:41], v73 offset:1024
	ds_read_b128 v[42:45], v73 offset:2048
	ds_read_b128 v[46:49], v73 offset:3072
	s_add_u32 s16, s12, 0x10100
	s_addc_u32 s17, s13, 0
	s_add_u32 s14, s8, 0x10180
	s_addc_u32 s15, s9, 0
	s_add_u32 s8, s12, 0x10180
	s_addc_u32 s9, s13, 0
	s_cmpk_gt_u32 s42, 0xff
	s_mov_b32 m0, s46
	v_lshl_add_u64 v[90:91], s[48:49], 0, v[14:15]
	ds_read_b128 v[50:53], v156
	ds_read_b128 v[54:57], v156 offset:1024
	ds_read_b128 v[58:61], v156 offset:2048
	ds_read_b128 v[62:65], v156 offset:3072
	ds_read_b128 v[74:77], v156 offset:4096
	ds_read_b128 v[78:81], v156 offset:5120
	ds_read_b128 v[82:85], v156 offset:6144
	ds_read_b128 v[86:89], v156 offset:7168
	global_load_lds_dwordx4 v[90:91], off
	v_lshl_add_u64 v[90:91], s[48:49], 0, v[2:3]
	s_mov_b32 m0, s45
	s_nop 0
	global_load_lds_dwordx4 v[90:91], off
	s_waitcnt vmcnt(8)
	s_waitcnt lgkmcnt(0)
	s_barrier
	s_setprio 1
	v_mfma_f32_16x16x32_bf16 v[90:93], v[34:37], v[50:53], 0
	v_mfma_f32_16x16x32_bf16 v[50:53], v[42:45], v[50:53], 0
	v_mfma_f32_16x16x32_bf16 v[90:93], v[38:41], v[54:57], v[90:93]
	v_mfma_f32_16x16x32_bf16 v[50:53], v[46:49], v[54:57], v[50:53]
	v_mfma_f32_16x16x32_bf16 v[54:57], v[34:37], v[58:61], 0
	v_mfma_f32_16x16x32_bf16 v[58:61], v[42:45], v[58:61], 0
	v_mfma_f32_16x16x32_bf16 v[54:57], v[38:41], v[62:65], v[54:57]
	v_mfma_f32_16x16x32_bf16 v[58:61], v[46:49], v[62:65], v[58:61]
	v_mfma_f32_16x16x32_bf16 v[62:65], v[34:37], v[74:77], 0
	v_mfma_f32_16x16x32_bf16 v[74:77], v[42:45], v[74:77], 0
	v_mfma_f32_16x16x32_bf16 v[62:65], v[38:41], v[78:81], v[62:65]
	v_mfma_f32_16x16x32_bf16 v[74:77], v[46:49], v[78:81], v[74:77]
	v_mfma_f32_16x16x32_bf16 v[78:81], v[34:37], v[82:85], 0
	v_mfma_f32_16x16x32_bf16 v[82:85], v[42:45], v[82:85], 0
	v_mfma_f32_16x16x32_bf16 v[78:81], v[38:41], v[86:89], v[78:81]
	v_mfma_f32_16x16x32_bf16 v[82:85], v[46:49], v[86:89], v[82:85]
	s_setprio 0
	s_setprio 1
	s_setprio 0
	s_barrier
	s_mov_b64 s[12:13], 0x100
	s_mov_b32 m0, s44
	v_lshl_add_u64 v[122:123], v[4:5], 0, s[12:13]
	ds_read_b128 v[86:89], v156 offset:16384
	ds_read_b128 v[94:97], v156 offset:17408
	ds_read_b128 v[98:101], v156 offset:18432
	ds_read_b128 v[102:105], v156 offset:19456
	ds_read_b128 v[106:109], v156 offset:20480
	ds_read_b128 v[110:113], v156 offset:21504
	ds_read_b128 v[114:117], v156 offset:22528
	ds_read_b128 v[118:121], v156 offset:23552
	global_load_lds_dwordx4 v[122:123], off
	v_lshl_add_u64 v[122:123], v[6:7], 0, s[12:13]
	s_mov_b32 m0, s43
	s_nop 0
	global_load_lds_dwordx4 v[122:123], off
	v_lshl_add_u64 v[122:123], s[50:51], 0, v[32:33]
	s_mov_b32 m0, s29
	s_nop 0
	global_load_lds_dwordx4 v[122:123], off
	v_lshl_add_u64 v[122:123], s[50:51], 0, v[20:21]
	s_mov_b32 m0, s31
	s_nop 0
	global_load_lds_dwordx4 v[122:123], off
	v_lshl_add_u64 v[122:123], v[18:19], 0, s[12:13]
	s_mov_b32 m0, s27
	s_nop 0
	global_load_lds_dwordx4 v[122:123], off
	v_lshl_add_u64 v[122:123], v[22:23], 0, s[12:13]
	s_mov_b32 m0, s35
	s_nop 0
	global_load_lds_dwordx4 v[122:123], off
	s_waitcnt vmcnt(8)
	s_waitcnt lgkmcnt(0)
	s_barrier
	s_setprio 1
	v_mfma_f32_16x16x32_bf16 v[122:125], v[34:37], v[86:89], 0
	v_mfma_f32_16x16x32_bf16 v[86:89], v[42:45], v[86:89], 0
	v_mfma_f32_16x16x32_bf16 v[122:125], v[38:41], v[94:97], v[122:125]
	v_mfma_f32_16x16x32_bf16 v[86:89], v[46:49], v[94:97], v[86:89]
	v_mfma_f32_16x16x32_bf16 v[94:97], v[34:37], v[98:101], 0
	v_mfma_f32_16x16x32_bf16 v[98:101], v[42:45], v[98:101], 0
	v_mfma_f32_16x16x32_bf16 v[94:97], v[38:41], v[102:105], v[94:97]
	v_mfma_f32_16x16x32_bf16 v[98:101], v[46:49], v[102:105], v[98:101]
	v_mfma_f32_16x16x32_bf16 v[102:105], v[34:37], v[106:109], 0
	v_mfma_f32_16x16x32_bf16 v[34:37], v[34:37], v[114:117], 0
	v_mfma_f32_16x16x32_bf16 v[102:105], v[38:41], v[110:113], v[102:105]
	v_mfma_f32_16x16x32_bf16 v[34:37], v[38:41], v[118:121], v[34:37]
	v_mfma_f32_16x16x32_bf16 v[38:41], v[42:45], v[114:117], 0
	v_mfma_f32_16x16x32_bf16 v[106:109], v[42:45], v[106:109], 0
	v_mfma_f32_16x16x32_bf16 v[38:41], v[46:49], v[118:121], v[38:41]
	v_mfma_f32_16x16x32_bf16 v[106:109], v[46:49], v[110:113], v[106:109]
	s_setprio 0
	s_setprio 1
	s_setprio 0
	s_barrier
; #define PG8_STAGE(bufoff, gbase, voff) do { _Pragma("unroll") for (int _i = 0; _i < 2; ++_i) \
;         __builtin_amdgcn_global_load_lds((const unsigned*)((const char*)(gbase) + (voff)[_i]), (PG8_LAS unsigned*)(lds + (bufoff) + ldsw + _i * 8192), 16, 0, 0); } while (0)
; #define PG8_LDA(dst, b, h) do { _Pragma("unroll") for (int m = 0; m < 4; ++m) _Pragma("unroll") for (int k = 0; k < 2; ++k) dst[m][k] = *(const PG8_LAS bf16x8*)(lds + PG8_SA(b, h) + aoff + m * 2048 + k * 1024); } while (0)
; #define PG8_LDB(dst, b, h) do { _Pragma("unroll") for (int n = 0; n < 2; ++n) _Pragma("unroll") for (int k = 0; k < 2; ++k) dst[n][k] = *(const PG8_LAS bf16x8*)(lds + PG8_SB(b, h) + boff + n * 2048 + k * 1024); } while (0)
; #define PG8_MMA(ai, bj, At, Bt) do { __builtin_amdgcn_s_setprio(1); _Pragma("unroll") for (int m = 0; m < 4; ++m) _Pragma("unroll") for (int n = 0; n < 2; ++n) _Pragma("unroll") for (int k = 0; k < 2; ++k) \
;         acc[ai][bj][m][n] = __builtin_amdgcn_mfma_f32_16x16x32_bf16(Bt[n][k], At[m][k], acc[ai][bj][m][n], 0, 0, 0); __builtin_amdgcn_s_setprio(0); } while (0)
; #define PG8_WAIT_V(n) asm volatile("s_waitcnt vmcnt(" #n ")" ::: "memory")
; template <class Epi, class Sched, bool ALIGN_EPI = false, bool SP2 = false>
; __device__ __forceinline__ void gemm_phase(PG8_LAS unsigned char* lds, const Gemm g, const Sched& S, const Epi& E) {
;     ...
;             PG8_LDB(B0, 0, 0); PG8_LDB(B1, 0, 1); PG8_SCHED; PG8_LDA(At, 0, 0); PG8_STAGE(PG8_SA(1, 1), a1 + hstepA, voffA);
;             PG8_WAIT_V(8); PG8_WAIT_L(0); PG8_BAR; PG8_MMA(0, 0, At, B0); PG8_MMA(0, 1, At, B1); PG8_BAR; PG8_SCHED;
;             PG8_LDA(At, 0, 1); PG8_STAGE(PG8_SB(0, 0), b2, voffB); PG8_STAGE(PG8_SB(0, 1), b2 + hstepB, voffB); PG8_STAGE(PG8_SA(0, 0), a2, voffA);
;             PG8_WAIT_V(8); PG8_WAIT_L(0); PG8_BAR; PG8_MMA(1, 0, At, B0); PG8_MMA(1, 1, At, B1); PG8_BAR; PG8_SCHED;
;             PG8_LDB(B0, 1, 0); PG8_LDB(B1, 1, 1); PG8_SCHED; PG8_LDA(At, 1, 0); PG8_STAGE(PG8_SA(0, 1), a2 + hstepA, voffA);
;             PG8_WAIT_V(8); PG8_WAIT_L(0); PG8_BAR; PG8_MMA(0, 0, At, B0); PG8_MMA(0, 1, At, B1); PG8_BAR; PG8_SCHED;
;             PG8_LDA(At, 1, 1); PG8_STAGE(PG8_SB(1, 0), b3, voffB); PG8_STAGE(PG8_SB(1, 1), b3 + hstepB, voffB); PG8_STAGE(PG8_SA(1, 0), a3, voffA);
;             PG8_WAIT_V(8); PG8_WAIT_L(0); PG8_BAR; PG8_MMA(1, 0, At, B0); PG8_MMA(1, 1, At, B1); PG8_BAR; PG8_SCHED;
	ds_read_b128 v[42:45], v157
	ds_read_b128 v[46:49], v157 offset:1024
	ds_read_b128 v[110:113], v157 offset:2048
	ds_read_b128 v[114:117], v157 offset:3072
	s_mov_b32 m0, s30
	v_lshl_add_u64 v[154:155], s[16:17], 0, v[14:15]
	ds_read_b128 v[118:121], v156 offset:32768
	ds_read_b128 v[126:129], v156 offset:33792
	ds_read_b128 v[130:133], v156 offset:34816
	ds_read_b128 v[134:137], v156 offset:35840
	ds_read_b128 v[138:141], v156 offset:36864
	ds_read_b128 v[142:145], v156 offset:37888
	ds_read_b128 v[146:149], v156 offset:38912
	ds_read_b128 v[150:153], v156 offset:39936
	global_load_lds_dwordx4 v[154:155], off
	v_lshl_add_u64 v[154:155], s[16:17], 0, v[2:3]
	s_mov_b32 m0, s34
	s_nop 0
	global_load_lds_dwordx4 v[154:155], off
	s_waitcnt vmcnt(8)
	s_waitcnt lgkmcnt(0)
	s_barrier
	s_setprio 1
	v_mfma_f32_16x16x32_bf16 v[50:53], v[110:113], v[118:121], v[50:53]
	v_mfma_f32_16x16x32_bf16 v[54:57], v[42:45], v[130:133], v[54:57]
	v_mfma_f32_16x16x32_bf16 v[58:61], v[110:113], v[130:133], v[58:61]
	v_mfma_f32_16x16x32_bf16 v[62:65], v[42:45], v[138:141], v[62:65]
	v_mfma_f32_16x16x32_bf16 v[90:93], v[42:45], v[118:121], v[90:93]
	v_mfma_f32_16x16x32_bf16 v[50:53], v[114:117], v[126:129], v[50:53]
	v_mfma_f32_16x16x32_bf16 v[54:57], v[46:49], v[134:137], v[54:57]
	v_mfma_f32_16x16x32_bf16 v[58:61], v[114:117], v[134:137], v[58:61]
	v_mfma_f32_16x16x32_bf16 v[62:65], v[46:49], v[142:145], v[62:65]
	v_mfma_f32_16x16x32_bf16 v[74:77], v[110:113], v[138:141], v[74:77]
	v_mfma_f32_16x16x32_bf16 v[78:81], v[42:45], v[146:149], v[78:81]
	v_mfma_f32_16x16x32_bf16 v[82:85], v[110:113], v[146:149], v[82:85]
	v_mfma_f32_16x16x32_bf16 v[90:93], v[46:49], v[126:129], v[90:93]
	v_mfma_f32_16x16x32_bf16 v[74:77], v[114:117], v[142:145], v[74:77]
	v_mfma_f32_16x16x32_bf16 v[78:81], v[46:49], v[150:153], v[78:81]
	v_mfma_f32_16x16x32_bf16 v[82:85], v[114:117], v[150:153], v[82:85]
	s_setprio 0
	s_setprio 1
	s_setprio 0
	s_barrier
	s_mov_b64 s[12:13], 0x180
	s_mov_b32 m0, s36
	v_lshl_add_u64 v[154:155], v[4:5], 0, s[12:13]
	ds_read_b128 v[118:121], v156 offset:49152
	ds_read_b128 v[126:129], v156 offset:50176
	ds_read_b128 v[130:133], v156 offset:51200
	ds_read_b128 v[134:137], v156 offset:52224
	ds_read_b128 v[138:141], v156 offset:53248
	ds_read_b128 v[142:145], v156 offset:54272
	ds_read_b128 v[146:149], v156 offset:55296
	ds_read_b128 v[150:153], v156 offset:56320
	global_load_lds_dwordx4 v[154:155], off
	v_lshl_add_u64 v[154:155], v[6:7], 0, s[12:13]
	s_mov_b32 m0, s38
	v_lshl_add_u64 v[32:33], s[14:15], 0, v[32:33]
	global_load_lds_dwordx4 v[154:155], off
	s_mov_b32 m0, s40
	v_lshl_add_u64 v[20:21], s[14:15], 0, v[20:21]
	global_load_lds_dwordx4 v[32:33], off
	s_mov_b32 m0, s41
	s_nop 0
	global_load_lds_dwordx4 v[20:21], off
	v_lshl_add_u64 v[20:21], v[18:19], 0, s[12:13]
	s_mov_b32 m0, s37
	s_nop 0
	global_load_lds_dwordx4 v[20:21], off
	v_lshl_add_u64 v[20:21], v[22:23], 0, s[12:13]
	s_mov_b32 m0, s39
	s_nop 0
	global_load_lds_dwordx4 v[20:21], off
	s_waitcnt vmcnt(8)
	s_waitcnt lgkmcnt(0)
	s_barrier
	s_setprio 1
	v_mfma_f32_16x16x32_bf16 v[32:35], v[42:45], v[146:149], v[34:37]
	v_mfma_f32_16x16x32_bf16 v[36:39], v[110:113], v[146:149], v[38:41]
	v_mfma_f32_16x16x32_bf16 v[122:125], v[42:45], v[118:121], v[122:125]
	v_mfma_f32_16x16x32_bf16 v[86:89], v[110:113], v[118:121], v[86:89]
	v_mfma_f32_16x16x32_bf16 v[94:97], v[42:45], v[130:133], v[94:97]
	v_mfma_f32_16x16x32_bf16 v[98:101], v[110:113], v[130:133], v[98:101]
	v_mfma_f32_16x16x32_bf16 v[102:105], v[42:45], v[138:141], v[102:105]
	v_mfma_f32_16x16x32_bf16 v[106:109], v[110:113], v[138:141], v[106:109]
	v_mfma_f32_16x16x32_bf16 v[32:35], v[46:49], v[150:153], v[32:35]
	v_mfma_f32_16x16x32_bf16 v[36:39], v[114:117], v[150:153], v[36:39]
	v_mfma_f32_16x16x32_bf16 v[122:125], v[46:49], v[126:129], v[122:125]
	v_mfma_f32_16x16x32_bf16 v[86:89], v[114:117], v[126:129], v[86:89]
	v_mfma_f32_16x16x32_bf16 v[94:97], v[46:49], v[134:137], v[94:97]
	v_mfma_f32_16x16x32_bf16 v[98:101], v[114:117], v[134:137], v[98:101]
	v_mfma_f32_16x16x32_bf16 v[102:105], v[46:49], v[142:145], v[102:105]
	v_mfma_f32_16x16x32_bf16 v[106:109], v[114:117], v[142:145], v[106:109]
	s_setprio 0
	s_setprio 1
	s_setprio 0
	s_barrier
	ds_read_b128 v[40:43], v73
	ds_read_b128 v[44:47], v73 offset:1024
	ds_read_b128 v[110:113], v73 offset:2048
	ds_read_b128 v[114:117], v73 offset:3072
	s_mov_b32 m0, s46
	v_lshl_add_u64 v[14:15], s[8:9], 0, v[14:15]
	ds_read_b128 v[118:121], v156
	ds_read_b128 v[126:129], v156 offset:1024
	ds_read_b128 v[130:133], v156 offset:2048
	ds_read_b128 v[134:137], v156 offset:3072
	ds_read_b128 v[138:141], v156 offset:4096
	ds_read_b128 v[142:145], v156 offset:5120
	ds_read_b128 v[146:149], v156 offset:6144
	ds_read_b128 v[150:153], v156 offset:7168
	global_load_lds_dwordx4 v[14:15], off
	v_lshl_add_u64 v[2:3], s[8:9], 0, v[2:3]
	s_mov_b32 m0, s45
	s_nop 0
	global_load_lds_dwordx4 v[2:3], off
	s_waitcnt vmcnt(8)
	s_waitcnt lgkmcnt(0)
	s_barrier
	s_setprio 1
	v_mfma_f32_16x16x32_bf16 v[48:51], v[110:113], v[118:121], v[50:53]
	v_mfma_f32_16x16x32_bf16 v[52:55], v[40:43], v[130:133], v[54:57]
	v_mfma_f32_16x16x32_bf16 v[56:59], v[110:113], v[130:133], v[58:61]
	v_mfma_f32_16x16x32_bf16 v[90:93], v[40:43], v[118:121], v[90:93]
	v_mfma_f32_16x16x32_bf16 v[118:121], v[114:117], v[134:137], v[56:59]
	v_mfma_f32_16x16x32_bf16 v[56:59], v[40:43], v[138:141], v[62:65]
	v_mfma_f32_16x16x32_bf16 v[90:93], v[44:47], v[126:129], v[90:93]
	v_mfma_f32_16x16x32_bf16 v[48:51], v[114:117], v[126:129], v[48:51]
	v_mfma_f32_16x16x32_bf16 v[126:129], v[44:47], v[142:145], v[56:59]
	v_mfma_f32_16x16x32_bf16 v[56:59], v[110:113], v[138:141], v[74:77]
	v_mfma_f32_16x16x32_bf16 v[74:77], v[114:117], v[142:145], v[56:59]
	v_mfma_f32_16x16x32_bf16 v[56:59], v[40:43], v[146:149], v[78:81]
	v_mfma_f32_16x16x32_bf16 v[52:55], v[44:47], v[134:137], v[52:55]
	v_mfma_f32_16x16x32_bf16 v[78:81], v[44:47], v[150:153], v[56:59]
	v_mfma_f32_16x16x32_bf16 v[56:59], v[110:113], v[146:149], v[82:85]
	v_mfma_f32_16x16x32_bf16 v[82:85], v[114:117], v[150:153], v[56:59]
	s_setprio 0
	s_setprio 1
	s_setprio 0
	s_barrier
; #define PG8_STAGE(bufoff, gbase, voff) do { _Pragma("unroll") for (int _i = 0; _i < 2; ++_i) \
;         __builtin_amdgcn_global_load_lds((const unsigned*)((const char*)(gbase) + (voff)[_i]), (PG8_LAS unsigned*)(lds + (bufoff) + ldsw + _i * 8192), 16, 0, 0); } while (0)
; #define PG8_LDA(dst, b, h) do { _Pragma("unroll") for (int m = 0; m < 4; ++m) _Pragma("unroll") for (int k = 0; k < 2; ++k) dst[m][k] = *(const PG8_LAS bf16x8*)(lds + PG8_SA(b, h) + aoff + m * 2048 + k * 1024); } while (0)
; #define PG8_LDB(dst, b, h) do { _Pragma("unroll") for (int n = 0; n < 2; ++n) _Pragma("unroll") for (int k = 0; k < 2; ++k) dst[n][k] = *(const PG8_LAS bf16x8*)(lds + PG8_SB(b, h) + boff + n * 2048 + k * 1024); } while (0)
; #define PG8_MMA(ai, bj, At, Bt) do { __builtin_amdgcn_s_setprio(1); _Pragma("unroll") for (int m = 0; m < 4; ++m) _Pragma("unroll") for (int n = 0; n < 2; ++n) _Pragma("unroll") for (int k = 0; k < 2; ++k) \
;         acc[ai][bj][m][n] = __builtin_amdgcn_mfma_f32_16x16x32_bf16(Bt[n][k], At[m][k], acc[ai][bj][m][n], 0, 0, 0); __builtin_amdgcn_s_setprio(0); } while (0)
; #define PG8_WAIT_V(n) asm volatile("s_waitcnt vmcnt(" #n ")" ::: "memory")
; #define PG8_WAIT_L(n) asm volatile("s_waitcnt lgkmcnt(" #n ")" ::: "memory")
; #define PG8_BAR __builtin_amdgcn_s_barrier()
; #define PG8_SCHED __builtin_amdgcn_sched_barrier(0)
; template <class Epi, class Sched, bool ALIGN_EPI = false, bool SP2 = false>
; __device__ __forceinline__ void gemm_phase(PG8_LAS unsigned char* lds, const Gemm g, const Sched& S, const Epi& E) {
;     ...
;             PG8_LDA(At, 0, 1); PG8_STAGE(PG8_SB(0, 0), b2, voffB); PG8_STAGE(PG8_SB(0, 1), b2 + hstepB, voffB); PG8_STAGE(PG8_SA(0, 0), a2, voffA);
;             PG8_WAIT_V(8); PG8_WAIT_L(0); PG8_BAR; PG8_MMA(1, 0, At, B0); PG8_MMA(1, 1, At, B1); PG8_BAR; PG8_SCHED;
;             PG8_LDB(B0, 1, 0); PG8_LDB(B1, 1, 1); PG8_SCHED; PG8_LDA(At, 1, 0); PG8_STAGE(PG8_SA(0, 1), a2 + hstepA, voffA);
;             PG8_WAIT_V(8); PG8_WAIT_L(0); PG8_BAR; PG8_MMA(0, 0, At, B0); PG8_MMA(0, 1, At, B1); PG8_BAR; PG8_SCHED;
;             PG8_LDA(At, 1, 1); PG8_STAGE(PG8_SB(1, 0), b3, voffB); PG8_STAGE(PG8_SB(1, 1), b3 + hstepB, voffB); PG8_STAGE(PG8_SA(1, 0), a3, voffA);
;             PG8_WAIT_V(8); PG8_WAIT_L(0); PG8_BAR; PG8_MMA(1, 0, At, B0); PG8_MMA(1, 1, At, B1); PG8_BAR; PG8_SCHED;
	s_mov_b32 m0, s44
	s_nop 1
	ds_read_b128 v[56:59], v156 offset:16384
	ds_read_b128 v[60:63], v156 offset:17408
	ds_read_b128 v[130:133], v156 offset:18432
	ds_read_b128 v[134:137], v156 offset:19456
	ds_read_b128 v[138:141], v156 offset:20480
	ds_read_b128 v[142:145], v156 offset:21504
	ds_read_b128 v[146:149], v156 offset:22528
	ds_read_b128 v[150:153], v156 offset:23552
	global_load_lds_dwordx4 v[4:5], off
	s_mov_b32 m0, s43
	s_nop 0
	global_load_lds_dwordx4 v[6:7], off
	s_mov_b32 m0, s29
	s_nop 0
	global_load_lds_dwordx4 v[8:9], off
	s_mov_b32 m0, s31
	s_nop 0
	global_load_lds_dwordx4 v[10:11], off
	s_mov_b32 m0, s27
	s_nop 0
	global_load_lds_dwordx4 v[18:19], off
	s_mov_b32 m0, s35
	s_nop 0
	global_load_lds_dwordx4 v[22:23], off
	s_waitcnt vmcnt(8)
	s_waitcnt lgkmcnt(0)
	s_barrier
	s_setprio 1
	v_mfma_f32_16x16x32_bf16 v[2:5], v[40:43], v[56:59], v[122:125]
	v_mfma_f32_16x16x32_bf16 v[6:9], v[110:113], v[56:59], v[86:89]
	v_mfma_f32_16x16x32_bf16 v[56:59], v[110:113], v[130:133], v[98:101]
	v_mfma_f32_16x16x32_bf16 v[18:21], v[40:43], v[130:133], v[94:97]
	v_mfma_f32_16x16x32_bf16 v[86:89], v[114:117], v[134:137], v[56:59]
	v_mfma_f32_16x16x32_bf16 v[56:59], v[40:43], v[138:141], v[102:105]
	v_mfma_f32_16x16x32_bf16 v[32:35], v[40:43], v[146:149], v[32:35]
	v_mfma_f32_16x16x32_bf16 v[2:5], v[44:47], v[60:63], v[2:5]
	v_mfma_f32_16x16x32_bf16 v[6:9], v[114:117], v[60:63], v[6:9]
	v_mfma_f32_16x16x32_bf16 v[18:21], v[44:47], v[134:137], v[18:21]
	v_mfma_f32_16x16x32_bf16 v[94:97], v[44:47], v[142:145], v[56:59]
	v_mfma_f32_16x16x32_bf16 v[56:59], v[110:113], v[138:141], v[106:109]
	v_mfma_f32_16x16x32_bf16 v[102:105], v[44:47], v[150:153], v[32:35]
	v_mfma_f32_16x16x32_bf16 v[32:35], v[110:113], v[146:149], v[36:39]
	v_mfma_f32_16x16x32_bf16 v[98:101], v[114:117], v[142:145], v[56:59]
	v_mfma_f32_16x16x32_bf16 v[106:109], v[114:117], v[150:153], v[32:35]
	s_setprio 0
	s_setprio 1
	s_setprio 0
	s_barrier
	ds_read_b128 v[110:113], v157
	ds_read_b128 v[114:117], v157 offset:1024
	ds_read_b128 v[122:125], v157 offset:2048
	ds_read_b128 v[130:133], v157 offset:3072
	s_mov_b32 m0, s30
	ds_read_b128 v[32:35], v156 offset:32768
	ds_read_b128 v[36:39], v156 offset:33792
	ds_read_b128 v[40:43], v156 offset:34816
	ds_read_b128 v[44:47], v156 offset:35840
	ds_read_b128 v[134:137], v156 offset:36864
	ds_read_b128 v[138:141], v156 offset:37888
	ds_read_b128 v[142:145], v156 offset:38912
	ds_read_b128 v[146:149], v156 offset:39936
	global_load_lds_dwordx4 v[12:13], off
	s_mov_b32 m0, s34
	s_nop 0
	global_load_lds_dwordx4 v[16:17], off
	s_waitcnt vmcnt(8)
	s_waitcnt lgkmcnt(0)
	s_barrier
	s_setprio 1
	v_mfma_f32_16x16x32_bf16 v[10:13], v[110:113], v[32:35], v[90:93]
	v_mfma_f32_16x16x32_bf16 v[58:61], v[114:117], v[36:39], v[10:13]
	v_mfma_f32_16x16x32_bf16 v[10:13], v[122:125], v[32:35], v[48:51]
	v_mfma_f32_16x16x32_bf16 v[62:65], v[130:133], v[36:39], v[10:13]
	v_mfma_f32_16x16x32_bf16 v[10:13], v[110:113], v[40:43], v[52:55]
	v_mfma_f32_16x16x32_bf16 v[50:53], v[114:117], v[44:47], v[10:13]
	v_mfma_f32_16x16x32_bf16 v[10:13], v[122:125], v[40:43], v[118:121]
	v_mfma_f32_16x16x32_bf16 v[54:57], v[130:133], v[44:47], v[10:13]
	v_mfma_f32_16x16x32_bf16 v[10:13], v[110:113], v[134:137], v[126:129]
	v_mfma_f32_16x16x32_bf16 v[42:45], v[114:117], v[138:141], v[10:13]
	v_mfma_f32_16x16x32_bf16 v[10:13], v[122:125], v[134:137], v[74:77]
	v_mfma_f32_16x16x32_bf16 v[46:49], v[130:133], v[138:141], v[10:13]
	v_mfma_f32_16x16x32_bf16 v[10:13], v[110:113], v[142:145], v[78:81]
	v_mfma_f32_16x16x32_bf16 v[34:37], v[114:117], v[146:149], v[10:13]
	v_mfma_f32_16x16x32_bf16 v[10:13], v[122:125], v[142:145], v[82:85]
	v_mfma_f32_16x16x32_bf16 v[38:41], v[130:133], v[146:149], v[10:13]
	s_setprio 0
	s_setprio 1
	s_setprio 0
	s_barrier
	s_mov_b32 m0, s36
	s_nop 1
	ds_read_b128 v[10:13], v156 offset:49152
	ds_read_b128 v[14:17], v156 offset:50176
	ds_read_b128 v[74:77], v156 offset:51200
	ds_read_b128 v[78:81], v156 offset:52224
	ds_read_b128 v[82:85], v156 offset:53248
	ds_read_b128 v[90:93], v156 offset:54272
	ds_read_b128 v[118:121], v156 offset:55296
	ds_read_b128 v[126:129], v156 offset:56320
	global_load_lds_dwordx4 v[26:27], off
	s_mov_b32 m0, s38
	s_nop 0
	global_load_lds_dwordx4 v[28:29], off
	s_mov_b32 m0, s40
	s_nop 0
	global_load_lds_dwordx4 v[68:69], off
	s_mov_b32 m0, s41
	s_nop 0
	global_load_lds_dwordx4 v[70:71], off
	s_mov_b32 m0, s37
	s_nop 0
	global_load_lds_dwordx4 v[24:25], off
	s_mov_b32 m0, s39
	s_nop 0
	global_load_lds_dwordx4 v[30:31], off
	s_waitcnt vmcnt(8)
	s_waitcnt lgkmcnt(0)
	s_barrier
	s_setprio 1
	v_mfma_f32_16x16x32_bf16 v[2:5], v[110:113], v[10:13], v[2:5]
	v_mfma_f32_16x16x32_bf16 v[26:29], v[114:117], v[14:17], v[2:5]
	v_mfma_f32_16x16x32_bf16 v[2:5], v[122:125], v[10:13], v[6:9]
	v_mfma_f32_16x16x32_bf16 v[30:33], v[130:133], v[14:17], v[2:5]
	v_mfma_f32_16x16x32_bf16 v[2:5], v[110:113], v[74:77], v[18:21]
	v_mfma_f32_16x16x32_bf16 v[18:21], v[114:117], v[78:81], v[2:5]
	v_mfma_f32_16x16x32_bf16 v[2:5], v[122:125], v[74:77], v[86:89]
	v_mfma_f32_16x16x32_bf16 v[22:25], v[130:133], v[78:81], v[2:5]
	v_mfma_f32_16x16x32_bf16 v[2:5], v[110:113], v[82:85], v[94:97]
	v_mfma_f32_16x16x32_bf16 v[10:13], v[114:117], v[90:93], v[2:5]
	v_mfma_f32_16x16x32_bf16 v[2:5], v[122:125], v[82:85], v[98:101]
	v_mfma_f32_16x16x32_bf16 v[14:17], v[130:133], v[90:93], v[2:5]
	v_mfma_f32_16x16x32_bf16 v[2:5], v[110:113], v[118:121], v[102:105]
	v_mfma_f32_16x16x32_bf16 v[6:9], v[122:125], v[118:121], v[106:109]
	v_mfma_f32_16x16x32_bf16 v[2:5], v[114:117], v[126:129], v[2:5]
	v_mfma_f32_16x16x32_bf16 v[6:9], v[130:133], v[126:129], v[6:9]
	s_setprio 0
	s_setprio 1
	s_setprio 0
	s_barrier
	s_cbranch_scc1 .LBB0_594
	s_barrier

; #define PG8_STAGE(bufoff, gbase, voff) do { _Pragma("unroll") for (int _i = 0; _i < 2; ++_i) \
;         __builtin_amdgcn_global_load_lds((const unsigned*)((const char*)(gbase) + (voff)[_i]), (PG8_LAS unsigned*)(lds + (bufoff) + ldsw + _i * 8192), 16, 0, 0); } while (0)
; #define PG8_LDA(dst, b, h) do { _Pragma("unroll") for (int m = 0; m < 4; ++m) _Pragma("unroll") for (int k = 0; k < 2; ++k) dst[m][k] = *(const PG8_LAS bf16x8*)(lds + PG8_SA(b, h) + aoff + m * 2048 + k * 1024); } while (0)
; #define PG8_LDB(dst, b, h) do { _Pragma("unroll") for (int n = 0; n < 2; ++n) _Pragma("unroll") for (int k = 0; k < 2; ++k) dst[n][k] = *(const PG8_LAS bf16x8*)(lds + PG8_SB(b, h) + boff + n * 2048 + k * 1024); } while (0)
; #define PG8_MMA(ai, bj, At, Bt) do { __builtin_amdgcn_s_setprio(1); _Pragma("unroll") for (int m = 0; m < 4; ++m) _Pragma("unroll") for (int n = 0; n < 2; ++n) _Pragma("unroll") for (int k = 0; k < 2; ++k) \
;         acc[ai][bj][m][n] = __builtin_amdgcn_mfma_f32_16x16x32_bf16(Bt[n][k], At[m][k], acc[ai][bj][m][n], 0, 0, 0); __builtin_amdgcn_s_setprio(0); } while (0)
; #define PG8_WAIT_V(n) asm volatile("s_waitcnt vmcnt(" #n ")" ::: "memory")
; #define PG8_WAIT_L(n) asm volatile("s_waitcnt lgkmcnt(" #n ")" ::: "memory")
; #define PG8_BAR __builtin_amdgcn_s_barrier()
; #define PG8_SCHED __builtin_amdgcn_sched_barrier(0)
; template <class Epi, class Sched, bool ALIGN_EPI = false, bool SP2 = false>
; __device__ __forceinline__ void gemm_phase(PG8_LAS unsigned char* lds, const Gemm g, const Sched& S, const Epi& E) {
;     ...
;             PG8_LDB(B0, 0, 0); PG8_LDB(B1, 0, 1); PG8_SCHED; PG8_LDA(At, 0, 0); PG8_STAGE(PG8_SA(1, 1), a1 + hstepA, voffA);
;             PG8_WAIT_V(8); PG8_WAIT_L(0); PG8_BAR; PG8_MMA(0, 0, At, B0); PG8_MMA(0, 1, At, B1); PG8_BAR; PG8_SCHED;
;             PG8_LDA(At, 0, 1); PG8_STAGE(PG8_SB(0, 0), b2, voffB); PG8_STAGE(PG8_SB(0, 1), b2 + hstepB, voffB); PG8_STAGE(PG8_SA(0, 0), a2, voffA);
;             PG8_WAIT_V(8); PG8_WAIT_L(0); PG8_BAR; PG8_MMA(1, 0, At, B0); PG8_MMA(1, 1, At, B1); PG8_BAR; PG8_SCHED;
.LBB0_1160:
	s_add_u32 s24, s22, 0x100
	s_addc_u32 s25, s23, 0
	s_add_i32 s57, 0, 0x10000
	s_cmp_eq_u32 s56, 4
	s_cselect_b32 s29, s17, s25
	s_cselect_b32 s28, s16, s24
	v_add_u32_e32 v145, s57, v142
	s_cselect_b32 s27, s52, s55
	s_cselect_b32 s26, s53, s54
	s_add_i32 s58, 0, 0x14000
	ds_read_b128 v[146:149], v145
	ds_read_b128 v[150:153], v145 offset:1024
	ds_read_b128 v[154:157], v145 offset:2048
	ds_read_b128 v[158:161], v145 offset:3072
	v_add_u32_e32 v145, s58, v142
	ds_read_b128 v[162:165], v145
	ds_read_b128 v[166:169], v145 offset:1024
	ds_read_b128 v[170:173], v145 offset:2048
	ds_read_b128 v[174:177], v145 offset:3072
	s_add_i32 m0, s39, 0xc000
	ds_read_b128 v[178:181], v143
	ds_read_b128 v[182:185], v143 offset:1024
	ds_read_b128 v[202:205], v143 offset:2048
	ds_read_b128 v[206:209], v143 offset:3072
	ds_read_b128 v[210:213], v143 offset:4096
	ds_read_b128 v[232:235], v143 offset:5120
	ds_read_b128 v[236:239], v143 offset:6144
	ds_read_b128 v[240:243], v143 offset:7168
	global_load_lds_dwordx4 v138, s[22:23]
	s_add_i32 m0, s39, 0xe000
	s_nop 0
	global_load_lds_dwordx4 v140, s[22:23]
	s_waitcnt vmcnt(8)
	s_waitcnt lgkmcnt(0)
	s_barrier
	s_setprio 1
	v_mfma_f32_16x16x32_bf16 v[126:129], v[146:149], v[178:181], v[126:129]
	v_mfma_f32_16x16x32_bf16 v[122:125], v[154:157], v[178:181], v[122:125]
	v_mfma_f32_16x16x32_bf16 v[118:121], v[146:149], v[202:205], v[118:121]
	v_mfma_f32_16x16x32_bf16 v[114:117], v[154:157], v[202:205], v[114:117]
	v_mfma_f32_16x16x32_bf16 v[110:113], v[146:149], v[210:213], v[110:113]
	v_mfma_f32_16x16x32_bf16 v[106:109], v[154:157], v[210:213], v[106:109]
	v_mfma_f32_16x16x32_bf16 v[102:105], v[146:149], v[236:239], v[102:105]
	v_mfma_f32_16x16x32_bf16 v[98:101], v[154:157], v[236:239], v[98:101]
	v_mfma_f32_16x16x32_bf16 v[126:129], v[150:153], v[182:185], v[126:129]
	v_mfma_f32_16x16x32_bf16 v[122:125], v[158:161], v[182:185], v[122:125]
	v_mfma_f32_16x16x32_bf16 v[118:121], v[150:153], v[206:209], v[118:121]
	v_mfma_f32_16x16x32_bf16 v[114:117], v[158:161], v[206:209], v[114:117]
	v_mfma_f32_16x16x32_bf16 v[110:113], v[150:153], v[232:235], v[110:113]
	v_mfma_f32_16x16x32_bf16 v[106:109], v[158:161], v[232:235], v[106:109]
	v_mfma_f32_16x16x32_bf16 v[102:105], v[150:153], v[240:243], v[102:105]
	v_mfma_f32_16x16x32_bf16 v[98:101], v[158:161], v[240:243], v[98:101]
	s_setprio 0
	s_setprio 1
	v_mfma_f32_16x16x32_bf16 v[78:81], v[162:165], v[178:181], v[78:81]
	v_mfma_f32_16x16x32_bf16 v[70:73], v[170:173], v[178:181], v[70:73]
	v_mfma_f32_16x16x32_bf16 v[62:65], v[162:165], v[202:205], v[62:65]
	v_mfma_f32_16x16x32_bf16 v[54:57], v[170:173], v[202:205], v[54:57]
	v_mfma_f32_16x16x32_bf16 v[46:49], v[162:165], v[210:213], v[46:49]
	v_mfma_f32_16x16x32_bf16 v[42:45], v[170:173], v[210:213], v[42:45]
	v_mfma_f32_16x16x32_bf16 v[38:41], v[162:165], v[236:239], v[38:41]
	v_mfma_f32_16x16x32_bf16 v[34:37], v[170:173], v[236:239], v[34:37]
	v_mfma_f32_16x16x32_bf16 v[78:81], v[166:169], v[182:185], v[78:81]
	v_mfma_f32_16x16x32_bf16 v[70:73], v[174:177], v[182:185], v[70:73]
	v_mfma_f32_16x16x32_bf16 v[62:65], v[166:169], v[206:209], v[62:65]
	v_mfma_f32_16x16x32_bf16 v[54:57], v[174:177], v[206:209], v[54:57]
	v_mfma_f32_16x16x32_bf16 v[46:49], v[166:169], v[232:235], v[46:49]
	v_mfma_f32_16x16x32_bf16 v[42:45], v[174:177], v[232:235], v[42:45]
	v_mfma_f32_16x16x32_bf16 v[38:41], v[166:169], v[240:243], v[38:41]
	v_mfma_f32_16x16x32_bf16 v[34:37], v[174:177], v[240:243], v[34:37]
	s_setprio 0
	s_barrier
	s_add_i32 s22, s57, s38
	s_mov_b32 m0, s22
	ds_read_b128 v[178:181], v143 offset:16384
	ds_read_b128 v[182:185], v143 offset:17408
	ds_read_b128 v[202:205], v143 offset:18432
	ds_read_b128 v[206:209], v143 offset:19456
	ds_read_b128 v[210:213], v143 offset:20480
	ds_read_b128 v[232:235], v143 offset:21504
	ds_read_b128 v[236:239], v143 offset:22528
	ds_read_b128 v[240:243], v143 offset:23552
	s_add_u32 s60, s26, 0x80
	s_addc_u32 s61, s27, 0
	s_add_u32 s62, s28, 0x80
	s_addc_u32 s63, s29, 0
	global_load_lds_dwordx4 v134, s[26:27]
	s_add_i32 m0, s22, 0x2000
	s_add_u32 s22, s26, 0x20000
	s_addc_u32 s23, s27, 0
	s_add_i32 s57, s58, s38
	global_load_lds_dwordx4 v130, s[26:27]
	s_mov_b32 m0, s57
	s_nop 0
	global_load_lds_dwordx4 v134, s[22:23]
	s_add_i32 m0, s57, 0x2000
	s_nop 0
	global_load_lds_dwordx4 v130, s[22:23]
	s_mov_b32 m0, s39
	s_nop 0
	global_load_lds_dwordx4 v136, s[28:29]
	s_mov_b32 m0, s40
	s_nop 0
	global_load_lds_dwordx4 v132, s[28:29]
	s_waitcnt vmcnt(8)
	s_waitcnt lgkmcnt(0)
	s_barrier
	s_setprio 1
	v_mfma_f32_16x16x32_bf16 v[94:97], v[146:149], v[178:181], v[94:97]
	v_mfma_f32_16x16x32_bf16 v[90:93], v[154:157], v[178:181], v[90:93]
	v_mfma_f32_16x16x32_bf16 v[86:89], v[146:149], v[202:205], v[86:89]
	v_mfma_f32_16x16x32_bf16 v[82:85], v[154:157], v[202:205], v[82:85]
	v_mfma_f32_16x16x32_bf16 v[74:77], v[146:149], v[210:213], v[74:77]
	v_mfma_f32_16x16x32_bf16 v[66:69], v[154:157], v[210:213], v[66:69]
	v_mfma_f32_16x16x32_bf16 v[58:61], v[146:149], v[236:239], v[58:61]
	v_mfma_f32_16x16x32_bf16 v[50:53], v[154:157], v[236:239], v[50:53]
	v_mfma_f32_16x16x32_bf16 v[94:97], v[150:153], v[182:185], v[94:97]
	v_mfma_f32_16x16x32_bf16 v[90:93], v[158:161], v[182:185], v[90:93]
	v_mfma_f32_16x16x32_bf16 v[86:89], v[150:153], v[206:209], v[86:89]
	v_mfma_f32_16x16x32_bf16 v[82:85], v[158:161], v[206:209], v[82:85]
	v_mfma_f32_16x16x32_bf16 v[74:77], v[150:153], v[232:235], v[74:77]
	v_mfma_f32_16x16x32_bf16 v[66:69], v[158:161], v[232:235], v[66:69]
	v_mfma_f32_16x16x32_bf16 v[58:61], v[150:153], v[240:243], v[58:61]
	v_mfma_f32_16x16x32_bf16 v[50:53], v[158:161], v[240:243], v[50:53]
	s_setprio 0
	s_setprio 1
	v_mfma_f32_16x16x32_bf16 v[30:33], v[162:165], v[178:181], v[30:33]
	v_mfma_f32_16x16x32_bf16 v[26:29], v[170:173], v[178:181], v[26:29]
	v_mfma_f32_16x16x32_bf16 v[22:25], v[162:165], v[202:205], v[22:25]
	v_mfma_f32_16x16x32_bf16 v[18:21], v[170:173], v[202:205], v[18:21]
	v_mfma_f32_16x16x32_bf16 v[14:17], v[162:165], v[210:213], v[14:17]
	v_mfma_f32_16x16x32_bf16 v[10:13], v[170:173], v[210:213], v[10:13]
	v_mfma_f32_16x16x32_bf16 v[6:9], v[162:165], v[236:239], v[6:9]
	v_mfma_f32_16x16x32_bf16 v[2:5], v[170:173], v[236:239], v[2:5]
	v_mfma_f32_16x16x32_bf16 v[30:33], v[166:169], v[182:185], v[30:33]
	v_mfma_f32_16x16x32_bf16 v[26:29], v[174:177], v[182:185], v[26:29]
	v_mfma_f32_16x16x32_bf16 v[22:25], v[166:169], v[206:209], v[22:25]
	v_mfma_f32_16x16x32_bf16 v[18:21], v[174:177], v[206:209], v[18:21]
	v_mfma_f32_16x16x32_bf16 v[14:17], v[166:169], v[232:235], v[14:17]
	v_mfma_f32_16x16x32_bf16 v[10:13], v[174:177], v[232:235], v[10:13]
	v_mfma_f32_16x16x32_bf16 v[6:9], v[166:169], v[240:243], v[6:9]
	v_mfma_f32_16x16x32_bf16 v[2:5], v[174:177], v[240:243], v[2:5]
	s_setprio 0
	s_barrier
; #define PG8_STAGE(bufoff, gbase, voff) do { _Pragma("unroll") for (int _i = 0; _i < 2; ++_i) \
;         __builtin_amdgcn_global_load_lds((const unsigned*)((const char*)(gbase) + (voff)[_i]), (PG8_LAS unsigned*)(lds + (bufoff) + ldsw + _i * 8192), 16, 0, 0); } while (0)
; #define PG8_LDA(dst, b, h) do { _Pragma("unroll") for (int m = 0; m < 4; ++m) _Pragma("unroll") for (int k = 0; k < 2; ++k) dst[m][k] = *(const PG8_LAS bf16x8*)(lds + PG8_SA(b, h) + aoff + m * 2048 + k * 1024); } while (0)
; #define PG8_LDB(dst, b, h) do { _Pragma("unroll") for (int n = 0; n < 2; ++n) _Pragma("unroll") for (int k = 0; k < 2; ++k) dst[n][k] = *(const PG8_LAS bf16x8*)(lds + PG8_SB(b, h) + boff + n * 2048 + k * 1024); } while (0)
; #define PG8_MMA(ai, bj, At, Bt) do { __builtin_amdgcn_s_setprio(1); _Pragma("unroll") for (int m = 0; m < 4; ++m) _Pragma("unroll") for (int n = 0; n < 2; ++n) _Pragma("unroll") for (int k = 0; k < 2; ++k) \
;         acc[ai][bj][m][n] = __builtin_amdgcn_mfma_f32_16x16x32_bf16(Bt[n][k], At[m][k], acc[ai][bj][m][n], 0, 0, 0); __builtin_amdgcn_s_setprio(0); } while (0)
; #define PG8_WAIT_V(n) asm volatile("s_waitcnt vmcnt(" #n ")" ::: "memory")
; #define PG8_WAIT_L(n) asm volatile("s_waitcnt lgkmcnt(" #n ")" ::: "memory")
; #define PG8_BAR __builtin_amdgcn_s_barrier()
; #define PG8_SCHED __builtin_amdgcn_sched_barrier(0)
; template <class Epi, class Sched, bool ALIGN_EPI = false, bool SP2 = false>
; __device__ __forceinline__ void gemm_phase(PG8_LAS unsigned char* lds, const Gemm g, const Sched& S, const Epi& E) {
;     ...
;             PG8_LDB(B0, 1, 0); PG8_LDB(B1, 1, 1); PG8_SCHED; PG8_LDA(At, 1, 0); PG8_STAGE(PG8_SA(0, 1), a2 + hstepA, voffA);
;             PG8_WAIT_V(8); PG8_WAIT_L(0); PG8_BAR; PG8_MMA(0, 0, At, B0); PG8_MMA(0, 1, At, B1); PG8_BAR; PG8_SCHED;
;             PG8_LDA(At, 1, 1); PG8_STAGE(PG8_SB(1, 0), b3, voffB); PG8_STAGE(PG8_SB(1, 1), b3 + hstepB, voffB); PG8_STAGE(PG8_SA(1, 0), a3, voffA);
;             PG8_WAIT_V(8); PG8_WAIT_L(0); PG8_BAR; PG8_MMA(1, 0, At, B0); PG8_MMA(1, 1, At, B1); PG8_BAR; PG8_SCHED;
	s_add_i32 s57, 0, 0x18000
	v_add_u32_e32 v145, s57, v142
	s_add_i32 s58, 0, 0x1c000
	ds_read_b128 v[146:149], v145
	ds_read_b128 v[150:153], v145 offset:1024
	ds_read_b128 v[154:157], v145 offset:2048
	ds_read_b128 v[158:161], v145 offset:3072
	v_add_u32_e32 v145, s58, v142
	ds_read_b128 v[162:165], v145
	ds_read_b128 v[166:169], v145 offset:1024
	ds_read_b128 v[170:173], v145 offset:2048
	ds_read_b128 v[174:177], v145 offset:3072
	s_add_u32 s22, s28, 0x30000
	s_addc_u32 s23, s29, 0
	s_mov_b32 m0, s41
	ds_read_b128 v[178:181], v143 offset:32768
	ds_read_b128 v[182:185], v143 offset:33792
	ds_read_b128 v[202:205], v143 offset:34816
	ds_read_b128 v[206:209], v143 offset:35840
	ds_read_b128 v[210:213], v143 offset:36864
	ds_read_b128 v[232:235], v143 offset:37888
	ds_read_b128 v[236:239], v143 offset:38912
	ds_read_b128 v[240:243], v143 offset:39936
	global_load_lds_dwordx4 v136, s[22:23]
	s_mov_b32 m0, s42
	s_nop 0
	global_load_lds_dwordx4 v132, s[22:23]
	s_waitcnt vmcnt(8)
	s_waitcnt lgkmcnt(0)
	s_barrier
	s_setprio 1
	v_mfma_f32_16x16x32_bf16 v[126:129], v[146:149], v[178:181], v[126:129]
	v_mfma_f32_16x16x32_bf16 v[122:125], v[154:157], v[178:181], v[122:125]
	v_mfma_f32_16x16x32_bf16 v[118:121], v[146:149], v[202:205], v[118:121]
	v_mfma_f32_16x16x32_bf16 v[114:117], v[154:157], v[202:205], v[114:117]
	v_mfma_f32_16x16x32_bf16 v[110:113], v[146:149], v[210:213], v[110:113]
	v_mfma_f32_16x16x32_bf16 v[106:109], v[154:157], v[210:213], v[106:109]
	v_mfma_f32_16x16x32_bf16 v[102:105], v[146:149], v[236:239], v[102:105]
	v_mfma_f32_16x16x32_bf16 v[98:101], v[154:157], v[236:239], v[98:101]
	v_mfma_f32_16x16x32_bf16 v[126:129], v[150:153], v[182:185], v[126:129]
	v_mfma_f32_16x16x32_bf16 v[122:125], v[158:161], v[182:185], v[122:125]
	v_mfma_f32_16x16x32_bf16 v[118:121], v[150:153], v[206:209], v[118:121]
	v_mfma_f32_16x16x32_bf16 v[114:117], v[158:161], v[206:209], v[114:117]
	v_mfma_f32_16x16x32_bf16 v[110:113], v[150:153], v[232:235], v[110:113]
	v_mfma_f32_16x16x32_bf16 v[106:109], v[158:161], v[232:235], v[106:109]
	v_mfma_f32_16x16x32_bf16 v[102:105], v[150:153], v[240:243], v[102:105]
	v_mfma_f32_16x16x32_bf16 v[98:101], v[158:161], v[240:243], v[98:101]
	s_setprio 0
	s_setprio 1
	v_mfma_f32_16x16x32_bf16 v[78:81], v[162:165], v[178:181], v[78:81]
	v_mfma_f32_16x16x32_bf16 v[70:73], v[170:173], v[178:181], v[70:73]
	v_mfma_f32_16x16x32_bf16 v[62:65], v[162:165], v[202:205], v[62:65]
	v_mfma_f32_16x16x32_bf16 v[54:57], v[170:173], v[202:205], v[54:57]
	v_mfma_f32_16x16x32_bf16 v[46:49], v[162:165], v[210:213], v[46:49]
	v_mfma_f32_16x16x32_bf16 v[42:45], v[170:173], v[210:213], v[42:45]
	v_mfma_f32_16x16x32_bf16 v[38:41], v[162:165], v[236:239], v[38:41]
	v_mfma_f32_16x16x32_bf16 v[34:37], v[170:173], v[236:239], v[34:37]
	v_mfma_f32_16x16x32_bf16 v[78:81], v[166:169], v[182:185], v[78:81]
	v_mfma_f32_16x16x32_bf16 v[70:73], v[174:177], v[182:185], v[70:73]
	v_mfma_f32_16x16x32_bf16 v[62:65], v[166:169], v[206:209], v[62:65]
	v_mfma_f32_16x16x32_bf16 v[54:57], v[174:177], v[206:209], v[54:57]
	v_mfma_f32_16x16x32_bf16 v[46:49], v[166:169], v[232:235], v[46:49]
	v_mfma_f32_16x16x32_bf16 v[42:45], v[174:177], v[232:235], v[42:45]
	v_mfma_f32_16x16x32_bf16 v[38:41], v[166:169], v[240:243], v[38:41]
	v_mfma_f32_16x16x32_bf16 v[34:37], v[174:177], v[240:243], v[34:37]
	s_setprio 0
	s_barrier
	s_add_i32 s22, s57, s38
	s_mov_b32 m0, s22
	ds_read_b128 v[178:181], v143 offset:49152
	ds_read_b128 v[182:185], v143 offset:50176
	ds_read_b128 v[202:205], v143 offset:51200
	ds_read_b128 v[206:209], v143 offset:52224
	ds_read_b128 v[210:213], v143 offset:53248
	ds_read_b128 v[232:235], v143 offset:54272
	ds_read_b128 v[236:239], v143 offset:55296
	ds_read_b128 v[240:243], v143 offset:56320
	global_load_lds_dwordx4 v134, s[60:61]
	s_add_i32 m0, s22, 0x2000
	s_add_u32 s22, s26, 0x20080
	s_addc_u32 s23, s27, 0
	s_add_i32 s26, s58, s38
	global_load_lds_dwordx4 v130, s[60:61]
	s_mov_b32 m0, s26
	s_nop 0
	global_load_lds_dwordx4 v134, s[22:23]
	s_add_i32 m0, s26, 0x2000
	s_nop 0
	global_load_lds_dwordx4 v130, s[22:23]
	s_mov_b32 m0, s43
	s_nop 0
	global_load_lds_dwordx4 v136, s[62:63]
	s_mov_b32 m0, s46
	s_nop 0
	global_load_lds_dwordx4 v132, s[62:63]
	s_waitcnt vmcnt(8)
	s_waitcnt lgkmcnt(0)
	s_barrier
	s_setprio 1
	v_mfma_f32_16x16x32_bf16 v[94:97], v[146:149], v[178:181], v[94:97]
	v_mfma_f32_16x16x32_bf16 v[90:93], v[154:157], v[178:181], v[90:93]
	v_mfma_f32_16x16x32_bf16 v[86:89], v[146:149], v[202:205], v[86:89]
	v_mfma_f32_16x16x32_bf16 v[82:85], v[154:157], v[202:205], v[82:85]
	v_mfma_f32_16x16x32_bf16 v[74:77], v[146:149], v[210:213], v[74:77]
	v_mfma_f32_16x16x32_bf16 v[66:69], v[154:157], v[210:213], v[66:69]
	v_mfma_f32_16x16x32_bf16 v[58:61], v[146:149], v[236:239], v[58:61]
	v_mfma_f32_16x16x32_bf16 v[50:53], v[154:157], v[236:239], v[50:53]
	v_mfma_f32_16x16x32_bf16 v[94:97], v[150:153], v[182:185], v[94:97]
	v_mfma_f32_16x16x32_bf16 v[90:93], v[158:161], v[182:185], v[90:93]
	v_mfma_f32_16x16x32_bf16 v[86:89], v[150:153], v[206:209], v[86:89]
	v_mfma_f32_16x16x32_bf16 v[82:85], v[158:161], v[206:209], v[82:85]
	v_mfma_f32_16x16x32_bf16 v[74:77], v[150:153], v[232:235], v[74:77]
	v_mfma_f32_16x16x32_bf16 v[66:69], v[158:161], v[232:235], v[66:69]
	v_mfma_f32_16x16x32_bf16 v[58:61], v[150:153], v[240:243], v[58:61]
	v_mfma_f32_16x16x32_bf16 v[50:53], v[158:161], v[240:243], v[50:53]
	s_setprio 0
	s_setprio 1
	v_mfma_f32_16x16x32_bf16 v[30:33], v[162:165], v[178:181], v[30:33]
	v_mfma_f32_16x16x32_bf16 v[26:29], v[170:173], v[178:181], v[26:29]
	v_mfma_f32_16x16x32_bf16 v[22:25], v[162:165], v[202:205], v[22:25]
	v_mfma_f32_16x16x32_bf16 v[18:21], v[170:173], v[202:205], v[18:21]
	v_mfma_f32_16x16x32_bf16 v[14:17], v[162:165], v[210:213], v[14:17]
	v_mfma_f32_16x16x32_bf16 v[10:13], v[170:173], v[210:213], v[10:13]
	v_mfma_f32_16x16x32_bf16 v[6:9], v[162:165], v[236:239], v[6:9]
	v_mfma_f32_16x16x32_bf16 v[2:5], v[170:173], v[236:239], v[2:5]
	v_mfma_f32_16x16x32_bf16 v[30:33], v[166:169], v[182:185], v[30:33]
	v_mfma_f32_16x16x32_bf16 v[26:29], v[174:177], v[182:185], v[26:29]
	v_mfma_f32_16x16x32_bf16 v[22:25], v[166:169], v[206:209], v[22:25]
	v_mfma_f32_16x16x32_bf16 v[18:21], v[174:177], v[206:209], v[18:21]
	v_mfma_f32_16x16x32_bf16 v[14:17], v[166:169], v[232:235], v[14:17]
	v_mfma_f32_16x16x32_bf16 v[10:13], v[174:177], v[232:235], v[10:13]
	v_mfma_f32_16x16x32_bf16 v[6:9], v[166:169], v[240:243], v[6:9]
	v_mfma_f32_16x16x32_bf16 v[2:5], v[174:177], v[240:243], v[2:5]
	s_setprio 0
	s_barrier
	s_add_i32 s56, s56, 2
	s_add_u32 s54, s54, 0x100
	s_addc_u32 s55, s55, 0
	s_cmp_gt_u32 s56, 5
	s_mov_b64 s[22:23], s[24:25]
	s_cbranch_scc0 .LBB0_1160
	s_and_b64 vcc, exec, s[8:9]
	s_cbranch_vccz .LBB0_1163
	s_barrier

; #define PG8_STAGE(bufoff, gbase, voff) do { _Pragma("unroll") for (int _i = 0; _i < 2; ++_i) \
;         __builtin_amdgcn_global_load_lds((const unsigned*)((const char*)(gbase) + (voff)[_i]), (PG8_LAS unsigned*)(lds + (bufoff) + ldsw + _i * 8192), 16, 0, 0); } while (0)
; #define PG8_LDA(dst, b, h) do { _Pragma("unroll") for (int m = 0; m < 4; ++m) _Pragma("unroll") for (int k = 0; k < 2; ++k) dst[m][k] = *(const PG8_LAS bf16x8*)(lds + PG8_SA(b, h) + aoff + m * 2048 + k * 1024); } while (0)
; #define PG8_LDB(dst, b, h) do { _Pragma("unroll") for (int n = 0; n < 2; ++n) _Pragma("unroll") for (int k = 0; k < 2; ++k) dst[n][k] = *(const PG8_LAS bf16x8*)(lds + PG8_SB(b, h) + boff + n * 2048 + k * 1024); } while (0)
; #define PG8_MMA(ai, bj, At, Bt) do { __builtin_amdgcn_s_setprio(1); _Pragma("unroll") for (int m = 0; m < 4; ++m) _Pragma("unroll") for (int n = 0; n < 2; ++n) _Pragma("unroll") for (int k = 0; k < 2; ++k) \
;         acc[ai][bj][m][n] = __builtin_amdgcn_mfma_f32_16x16x32_bf16(Bt[n][k], At[m][k], acc[ai][bj][m][n], 0, 0, 0); __builtin_amdgcn_s_setprio(0); } while (0)
; #define PG8_WAIT_V(n) asm volatile("s_waitcnt vmcnt(" #n ")" ::: "memory")
; #define PG8_WAIT_L(n) asm volatile("s_waitcnt lgkmcnt(" #n ")" ::: "memory")
; #define PG8_BAR __builtin_amdgcn_s_barrier()
; #define PG8_SCHED __builtin_amdgcn_sched_barrier(0)
; template <class Epi, class Sched, bool ALIGN_EPI = false, bool SP2 = false>
; __device__ __forceinline__ void gemm_phase(PG8_LAS unsigned char* lds, const Gemm g, const Sched& S, const Epi& E) {
;     ...
;             PG8_LDB(B0, 0, 0); PG8_LDB(B1, 0, 1); PG8_SCHED; PG8_LDA(At, 0, 0); PG8_STAGE(PG8_SA(1, 1), a1 + hstepA, voffA);
;             PG8_WAIT_V(8); PG8_WAIT_L(0); PG8_BAR; PG8_MMA(0, 0, At, B0); PG8_MMA(0, 1, At, B1); PG8_BAR; PG8_SCHED;
;             PG8_LDA(At, 0, 1); PG8_STAGE(PG8_SB(0, 0), b2, voffB); PG8_STAGE(PG8_SB(0, 1), b2 + hstepB, voffB); PG8_STAGE(PG8_SA(0, 0), a2, voffA);
.LBB0_1176:
	s_add_u32 s35, s26, s34
	s_addc_u32 s40, s27, 0
	s_add_u32 s38, s35, 0x100
	s_addc_u32 s39, s40, 0
	s_and_b64 s[36:37], s[30:31], exec
	s_cselect_b32 s37, s19, s39
	s_cselect_b32 s36, s18, s38
	s_add_u32 s34, s24, s34
	s_addc_u32 s38, s25, 0
	s_add_u32 s34, s34, 0x100
	s_addc_u32 s38, s38, 0
	s_add_i32 s72, 0, 0x10000
	s_and_b64 s[30:31], s[30:31], exec
	s_cselect_b32 s39, s61, s38
	s_cselect_b32 s38, s62, s34
	s_add_i32 s31, 0, 0x14000
	s_add_u32 s42, s35, 0x30080
	s_addc_u32 s43, s40, 0
	s_add_i32 s71, s72, s50
	s_add_i32 m0, s51, 0xc000
	s_add_i32 s74, s51, 0xe000
	s_add_i32 s67, s71, 0x2000
	v_add_u32_e32 v141, s72, v138
	s_add_u32 s40, s38, 0x10000
	ds_read_b128 v[142:145], v141
	ds_read_b128 v[146:149], v141 offset:1024
	ds_read_b128 v[150:153], v141 offset:2048
	ds_read_b128 v[154:157], v141 offset:3072
	v_add_u32_e32 v141, s31, v138
	s_addc_u32 s41, s39, 0
	s_add_i32 s69, s31, s50
	ds_read_b128 v[158:161], v141
	ds_read_b128 v[162:165], v141 offset:1024
	ds_read_b128 v[166:169], v141 offset:2048
	ds_read_b128 v[170:173], v141 offset:3072
	s_add_i32 s68, s69, 0x2000
	s_add_i32 s66, 0, 0x18000
	s_add_i32 s65, 0, 0x1c000
	s_add_u32 s34, s36, 0x30000
	s_addc_u32 s35, s37, 0
	s_add_i32 s64, s66, s50
	s_add_i32 s63, s64, 0x2000
	s_add_u32 s30, s38, 0x10080
	s_addc_u32 s31, s39, 0
	s_add_i32 s73, s65, s50
	s_add_i32 s72, s73, 0x2000
	v_lshl_add_u64 v[186:187], s[42:43], 0, v[136:137]
	ds_read_b128 v[174:177], v140
	ds_read_b128 v[178:181], v140 offset:1024
	ds_read_b128 v[182:185], v140 offset:2048
	ds_read_b128 v[202:205], v140 offset:3072
	ds_read_b128 v[206:209], v140 offset:4096
	ds_read_b128 v[210:213], v140 offset:5120
	ds_read_b128 v[232:235], v140 offset:6144
	ds_read_b128 v[236:239], v140 offset:7168
	global_load_lds_dwordx4 v[186:187], off
	v_lshl_add_u64 v[186:187], s[42:43], 0, v[132:133]
	s_mov_b32 m0, s74
	s_nop 0
	global_load_lds_dwordx4 v[186:187], off
	s_waitcnt vmcnt(8)
	s_waitcnt lgkmcnt(0)
	s_barrier
	s_setprio 1
	v_mfma_f32_16x16x32_bf16 v[126:129], v[142:145], v[174:177], v[126:129]
	v_mfma_f32_16x16x32_bf16 v[122:125], v[150:153], v[174:177], v[122:125]
	v_mfma_f32_16x16x32_bf16 v[118:121], v[142:145], v[182:185], v[118:121]
	v_mfma_f32_16x16x32_bf16 v[114:117], v[150:153], v[182:185], v[114:117]
	v_mfma_f32_16x16x32_bf16 v[110:113], v[142:145], v[206:209], v[110:113]
	v_mfma_f32_16x16x32_bf16 v[106:109], v[150:153], v[206:209], v[106:109]
	v_mfma_f32_16x16x32_bf16 v[102:105], v[142:145], v[232:235], v[102:105]
	v_mfma_f32_16x16x32_bf16 v[98:101], v[150:153], v[232:235], v[98:101]
	v_mfma_f32_16x16x32_bf16 v[126:129], v[146:149], v[178:181], v[126:129]
	v_mfma_f32_16x16x32_bf16 v[122:125], v[154:157], v[178:181], v[122:125]
	v_mfma_f32_16x16x32_bf16 v[118:121], v[146:149], v[202:205], v[118:121]
	v_mfma_f32_16x16x32_bf16 v[114:117], v[154:157], v[202:205], v[114:117]
	v_mfma_f32_16x16x32_bf16 v[110:113], v[146:149], v[210:213], v[110:113]
	v_mfma_f32_16x16x32_bf16 v[106:109], v[154:157], v[210:213], v[106:109]
	v_mfma_f32_16x16x32_bf16 v[102:105], v[146:149], v[236:239], v[102:105]
	v_mfma_f32_16x16x32_bf16 v[98:101], v[154:157], v[236:239], v[98:101]
	s_setprio 0
	s_setprio 1
	v_mfma_f32_16x16x32_bf16 v[78:81], v[158:161], v[174:177], v[78:81]
	v_mfma_f32_16x16x32_bf16 v[70:73], v[166:169], v[174:177], v[70:73]
	v_mfma_f32_16x16x32_bf16 v[62:65], v[158:161], v[182:185], v[62:65]
	v_mfma_f32_16x16x32_bf16 v[54:57], v[166:169], v[182:185], v[54:57]
	v_mfma_f32_16x16x32_bf16 v[46:49], v[158:161], v[206:209], v[46:49]
	v_mfma_f32_16x16x32_bf16 v[42:45], v[166:169], v[206:209], v[42:45]
	v_mfma_f32_16x16x32_bf16 v[38:41], v[158:161], v[232:235], v[38:41]
	v_mfma_f32_16x16x32_bf16 v[34:37], v[166:169], v[232:235], v[34:37]
	v_mfma_f32_16x16x32_bf16 v[78:81], v[162:165], v[178:181], v[78:81]
	v_mfma_f32_16x16x32_bf16 v[70:73], v[170:173], v[178:181], v[70:73]
	v_mfma_f32_16x16x32_bf16 v[62:65], v[162:165], v[202:205], v[62:65]
	v_mfma_f32_16x16x32_bf16 v[54:57], v[170:173], v[202:205], v[54:57]
	v_mfma_f32_16x16x32_bf16 v[46:49], v[162:165], v[210:213], v[46:49]
	v_mfma_f32_16x16x32_bf16 v[42:45], v[170:173], v[210:213], v[42:45]
	v_mfma_f32_16x16x32_bf16 v[38:41], v[162:165], v[236:239], v[38:41]
	v_mfma_f32_16x16x32_bf16 v[34:37], v[170:173], v[236:239], v[34:37]
	s_setprio 0
	s_barrier
	s_mov_b32 m0, s71
	v_lshl_add_u64 v[186:187], s[38:39], 0, v[134:135]
	ds_read_b128 v[174:177], v140 offset:16384
	ds_read_b128 v[178:181], v140 offset:17408
	ds_read_b128 v[182:185], v140 offset:18432
	ds_read_b128 v[202:205], v140 offset:19456
	ds_read_b128 v[206:209], v140 offset:20480
	ds_read_b128 v[210:213], v140 offset:21504
	ds_read_b128 v[232:235], v140 offset:22528
	ds_read_b128 v[236:239], v140 offset:23552
	global_load_lds_dwordx4 v[186:187], off
	v_lshl_add_u64 v[214:215], s[38:39], 0, v[130:131]
	s_mov_b32 m0, s67
	v_lshl_add_u64 v[240:241], s[40:41], 0, v[134:135]
	global_load_lds_dwordx4 v[214:215], off
	s_mov_b32 m0, s69
	v_lshl_add_u64 v[242:243], s[36:37], 0, v[132:133]
	global_load_lds_dwordx4 v[240:241], off
	v_lshl_add_u64 v[240:241], s[40:41], 0, v[130:131]
	s_mov_b32 m0, s68
	s_nop 0
	global_load_lds_dwordx4 v[240:241], off
	v_lshl_add_u64 v[240:241], s[36:37], 0, v[136:137]
	s_mov_b32 m0, s51
	s_nop 0
	global_load_lds_dwordx4 v[240:241], off
	s_mov_b32 m0, s52
	s_nop 0
	global_load_lds_dwordx4 v[242:243], off
	s_waitcnt vmcnt(8)
	s_waitcnt lgkmcnt(0)
	s_barrier
; #define PG8_STAGE(bufoff, gbase, voff) do { _Pragma("unroll") for (int _i = 0; _i < 2; ++_i) \
;         __builtin_amdgcn_global_load_lds((const unsigned*)((const char*)(gbase) + (voff)[_i]), (PG8_LAS unsigned*)(lds + (bufoff) + ldsw + _i * 8192), 16, 0, 0); } while (0)
; #define PG8_LDA(dst, b, h) do { _Pragma("unroll") for (int m = 0; m < 4; ++m) _Pragma("unroll") for (int k = 0; k < 2; ++k) dst[m][k] = *(const PG8_LAS bf16x8*)(lds + PG8_SA(b, h) + aoff + m * 2048 + k * 1024); } while (0)
; #define PG8_LDB(dst, b, h) do { _Pragma("unroll") for (int n = 0; n < 2; ++n) _Pragma("unroll") for (int k = 0; k < 2; ++k) dst[n][k] = *(const PG8_LAS bf16x8*)(lds + PG8_SB(b, h) + boff + n * 2048 + k * 1024); } while (0)
; #define PG8_MMA(ai, bj, At, Bt) do { __builtin_amdgcn_s_setprio(1); _Pragma("unroll") for (int m = 0; m < 4; ++m) _Pragma("unroll") for (int n = 0; n < 2; ++n) _Pragma("unroll") for (int k = 0; k < 2; ++k) \
;         acc[ai][bj][m][n] = __builtin_amdgcn_mfma_f32_16x16x32_bf16(Bt[n][k], At[m][k], acc[ai][bj][m][n], 0, 0, 0); __builtin_amdgcn_s_setprio(0); } while (0)
; #define PG8_WAIT_V(n) asm volatile("s_waitcnt vmcnt(" #n ")" ::: "memory")
; #define PG8_WAIT_L(n) asm volatile("s_waitcnt lgkmcnt(" #n ")" ::: "memory")
; #define PG8_BAR __builtin_amdgcn_s_barrier()
; #define PG8_SCHED __builtin_amdgcn_sched_barrier(0)
; template <class Epi, class Sched, bool ALIGN_EPI = false, bool SP2 = false>
; __device__ __forceinline__ void gemm_phase(PG8_LAS unsigned char* lds, const Gemm g, const Sched& S, const Epi& E) {
;     ...
;             PG8_WAIT_V(8); PG8_WAIT_L(0); PG8_BAR; PG8_MMA(1, 0, At, B0); PG8_MMA(1, 1, At, B1); PG8_BAR; PG8_SCHED;
;             PG8_LDB(B0, 1, 0); PG8_LDB(B1, 1, 1); PG8_SCHED; PG8_LDA(At, 1, 0); PG8_STAGE(PG8_SA(0, 1), a2 + hstepA, voffA);
;             PG8_WAIT_V(8); PG8_WAIT_L(0); PG8_BAR; PG8_MMA(0, 0, At, B0); PG8_MMA(0, 1, At, B1); PG8_BAR; PG8_SCHED;
	s_setprio 1
	v_mfma_f32_16x16x32_bf16 v[94:97], v[142:145], v[174:177], v[94:97]
	v_mfma_f32_16x16x32_bf16 v[90:93], v[150:153], v[174:177], v[90:93]
	v_mfma_f32_16x16x32_bf16 v[86:89], v[142:145], v[182:185], v[86:89]
	v_mfma_f32_16x16x32_bf16 v[82:85], v[150:153], v[182:185], v[82:85]
	v_mfma_f32_16x16x32_bf16 v[74:77], v[142:145], v[206:209], v[74:77]
	v_mfma_f32_16x16x32_bf16 v[66:69], v[150:153], v[206:209], v[66:69]
	v_mfma_f32_16x16x32_bf16 v[58:61], v[142:145], v[232:235], v[58:61]
	v_mfma_f32_16x16x32_bf16 v[50:53], v[150:153], v[232:235], v[50:53]
	v_mfma_f32_16x16x32_bf16 v[94:97], v[146:149], v[178:181], v[94:97]
	v_mfma_f32_16x16x32_bf16 v[90:93], v[154:157], v[178:181], v[90:93]
	v_mfma_f32_16x16x32_bf16 v[86:89], v[146:149], v[202:205], v[86:89]
	v_mfma_f32_16x16x32_bf16 v[82:85], v[154:157], v[202:205], v[82:85]
	v_mfma_f32_16x16x32_bf16 v[74:77], v[146:149], v[210:213], v[74:77]
	v_mfma_f32_16x16x32_bf16 v[66:69], v[154:157], v[210:213], v[66:69]
	v_mfma_f32_16x16x32_bf16 v[58:61], v[146:149], v[236:239], v[58:61]
	v_mfma_f32_16x16x32_bf16 v[50:53], v[154:157], v[236:239], v[50:53]
	s_setprio 0
	s_setprio 1
	v_mfma_f32_16x16x32_bf16 v[30:33], v[158:161], v[174:177], v[30:33]
	v_mfma_f32_16x16x32_bf16 v[26:29], v[166:169], v[174:177], v[26:29]
	v_mfma_f32_16x16x32_bf16 v[22:25], v[158:161], v[182:185], v[22:25]
	v_mfma_f32_16x16x32_bf16 v[18:21], v[166:169], v[182:185], v[18:21]
	v_mfma_f32_16x16x32_bf16 v[14:17], v[158:161], v[206:209], v[14:17]
	v_mfma_f32_16x16x32_bf16 v[10:13], v[166:169], v[206:209], v[10:13]
	v_mfma_f32_16x16x32_bf16 v[6:9], v[158:161], v[232:235], v[6:9]
	v_mfma_f32_16x16x32_bf16 v[2:5], v[166:169], v[232:235], v[2:5]
	v_mfma_f32_16x16x32_bf16 v[30:33], v[162:165], v[178:181], v[30:33]
	v_mfma_f32_16x16x32_bf16 v[26:29], v[170:173], v[178:181], v[26:29]
	v_mfma_f32_16x16x32_bf16 v[22:25], v[162:165], v[202:205], v[22:25]
	v_mfma_f32_16x16x32_bf16 v[18:21], v[170:173], v[202:205], v[18:21]
	v_mfma_f32_16x16x32_bf16 v[14:17], v[162:165], v[210:213], v[14:17]
	v_mfma_f32_16x16x32_bf16 v[10:13], v[170:173], v[210:213], v[10:13]
	v_mfma_f32_16x16x32_bf16 v[6:9], v[162:165], v[236:239], v[6:9]
	v_mfma_f32_16x16x32_bf16 v[2:5], v[170:173], v[236:239], v[2:5]
	s_setprio 0
	s_barrier
	v_add_u32_e32 v141, s66, v138
	ds_read_b128 v[142:145], v141
	ds_read_b128 v[146:149], v141 offset:1024
	ds_read_b128 v[150:153], v141 offset:2048
	ds_read_b128 v[154:157], v141 offset:3072
	v_add_u32_e32 v141, s65, v138
	ds_read_b128 v[158:161], v141
	ds_read_b128 v[162:165], v141 offset:1024
	ds_read_b128 v[166:169], v141 offset:2048
	ds_read_b128 v[170:173], v141 offset:3072
	s_mov_b32 m0, s53
	v_lshl_add_u64 v[244:245], s[34:35], 0, v[136:137]
	ds_read_b128 v[174:177], v140 offset:32768
	ds_read_b128 v[178:181], v140 offset:33792
	ds_read_b128 v[182:185], v140 offset:34816
	ds_read_b128 v[202:205], v140 offset:35840
	ds_read_b128 v[206:209], v140 offset:36864
	ds_read_b128 v[210:213], v140 offset:37888
	ds_read_b128 v[232:235], v140 offset:38912
	ds_read_b128 v[236:239], v140 offset:39936
	global_load_lds_dwordx4 v[244:245], off
	v_lshl_add_u64 v[244:245], s[34:35], 0, v[132:133]
	s_mov_b32 m0, s54
	s_nop 0
	global_load_lds_dwordx4 v[244:245], off
	s_waitcnt vmcnt(8)
	s_waitcnt lgkmcnt(0)
	s_barrier
	s_setprio 1
	v_mfma_f32_16x16x32_bf16 v[126:129], v[142:145], v[174:177], v[126:129]
	v_mfma_f32_16x16x32_bf16 v[122:125], v[150:153], v[174:177], v[122:125]
	v_mfma_f32_16x16x32_bf16 v[118:121], v[142:145], v[182:185], v[118:121]
	v_mfma_f32_16x16x32_bf16 v[114:117], v[150:153], v[182:185], v[114:117]
	v_mfma_f32_16x16x32_bf16 v[110:113], v[142:145], v[206:209], v[110:113]
	v_mfma_f32_16x16x32_bf16 v[106:109], v[150:153], v[206:209], v[106:109]
	v_mfma_f32_16x16x32_bf16 v[102:105], v[142:145], v[232:235], v[102:105]
	v_mfma_f32_16x16x32_bf16 v[98:101], v[150:153], v[232:235], v[98:101]
	v_mfma_f32_16x16x32_bf16 v[126:129], v[146:149], v[178:181], v[126:129]
	v_mfma_f32_16x16x32_bf16 v[122:125], v[154:157], v[178:181], v[122:125]
	v_mfma_f32_16x16x32_bf16 v[118:121], v[146:149], v[202:205], v[118:121]
	v_mfma_f32_16x16x32_bf16 v[114:117], v[154:157], v[202:205], v[114:117]
	v_mfma_f32_16x16x32_bf16 v[110:113], v[146:149], v[210:213], v[110:113]
	v_mfma_f32_16x16x32_bf16 v[106:109], v[154:157], v[210:213], v[106:109]
	v_mfma_f32_16x16x32_bf16 v[102:105], v[146:149], v[236:239], v[102:105]
	v_mfma_f32_16x16x32_bf16 v[98:101], v[154:157], v[236:239], v[98:101]
	s_setprio 0
	s_setprio 1
	v_mfma_f32_16x16x32_bf16 v[78:81], v[158:161], v[174:177], v[78:81]
	v_mfma_f32_16x16x32_bf16 v[70:73], v[166:169], v[174:177], v[70:73]
	v_mfma_f32_16x16x32_bf16 v[62:65], v[158:161], v[182:185], v[62:65]
	v_mfma_f32_16x16x32_bf16 v[54:57], v[166:169], v[182:185], v[54:57]
	v_mfma_f32_16x16x32_bf16 v[46:49], v[158:161], v[206:209], v[46:49]
	v_mfma_f32_16x16x32_bf16 v[42:45], v[166:169], v[206:209], v[42:45]
	v_mfma_f32_16x16x32_bf16 v[38:41], v[158:161], v[232:235], v[38:41]
	v_mfma_f32_16x16x32_bf16 v[34:37], v[166:169], v[232:235], v[34:37]
	v_mfma_f32_16x16x32_bf16 v[78:81], v[162:165], v[178:181], v[78:81]
	v_mfma_f32_16x16x32_bf16 v[70:73], v[170:173], v[178:181], v[70:73]
	v_mfma_f32_16x16x32_bf16 v[62:65], v[162:165], v[202:205], v[62:65]
	v_mfma_f32_16x16x32_bf16 v[54:57], v[170:173], v[202:205], v[54:57]
	v_mfma_f32_16x16x32_bf16 v[46:49], v[162:165], v[210:213], v[46:49]
	v_mfma_f32_16x16x32_bf16 v[42:45], v[170:173], v[210:213], v[42:45]
	v_mfma_f32_16x16x32_bf16 v[38:41], v[162:165], v[236:239], v[38:41]
	v_mfma_f32_16x16x32_bf16 v[34:37], v[170:173], v[236:239], v[34:37]
	s_setprio 0
	s_barrier
; #define PG8_STAGE(bufoff, gbase, voff) do { _Pragma("unroll") for (int _i = 0; _i < 2; ++_i) \
;         __builtin_amdgcn_global_load_lds((const unsigned*)((const char*)(gbase) + (voff)[_i]), (PG8_LAS unsigned*)(lds + (bufoff) + ldsw + _i * 8192), 16, 0, 0); } while (0)
; #define PG8_LDA(dst, b, h) do { _Pragma("unroll") for (int m = 0; m < 4; ++m) _Pragma("unroll") for (int k = 0; k < 2; ++k) dst[m][k] = *(const PG8_LAS bf16x8*)(lds + PG8_SA(b, h) + aoff + m * 2048 + k * 1024); } while (0)
; #define PG8_MMA(ai, bj, At, Bt) do { __builtin_amdgcn_s_setprio(1); _Pragma("unroll") for (int m = 0; m < 4; ++m) _Pragma("unroll") for (int n = 0; n < 2; ++n) _Pragma("unroll") for (int k = 0; k < 2; ++k) \
;         acc[ai][bj][m][n] = __builtin_amdgcn_mfma_f32_16x16x32_bf16(Bt[n][k], At[m][k], acc[ai][bj][m][n], 0, 0, 0); __builtin_amdgcn_s_setprio(0); } while (0)
; #define PG8_WAIT_V(n) asm volatile("s_waitcnt vmcnt(" #n ")" ::: "memory")
; #define PG8_WAIT_L(n) asm volatile("s_waitcnt lgkmcnt(" #n ")" ::: "memory")
; #define PG8_BAR __builtin_amdgcn_s_barrier()
; #define PG8_SCHED __builtin_amdgcn_sched_barrier(0)
; template <class Epi, class Sched, bool ALIGN_EPI = false, bool SP2 = false>
; __device__ __forceinline__ void gemm_phase(PG8_LAS unsigned char* lds, const Gemm g, const Sched& S, const Epi& E) {
;     ...
;             PG8_LDA(At, 1, 1); PG8_STAGE(PG8_SB(1, 0), b3, voffB); PG8_STAGE(PG8_SB(1, 1), b3 + hstepB, voffB); PG8_STAGE(PG8_SA(1, 0), a3, voffA);
;             PG8_WAIT_V(8); PG8_WAIT_L(0); PG8_BAR; PG8_MMA(1, 0, At, B0); PG8_MMA(1, 1, At, B1); PG8_BAR; PG8_SCHED;
	s_mov_b32 m0, s64
	v_lshl_add_u64 v[186:187], v[186:187], 0, s[96:97]
	ds_read_b128 v[174:177], v140 offset:49152
	ds_read_b128 v[178:181], v140 offset:50176
	ds_read_b128 v[182:185], v140 offset:51200
	ds_read_b128 v[202:205], v140 offset:52224
	ds_read_b128 v[206:209], v140 offset:53248
	ds_read_b128 v[210:213], v140 offset:54272
	ds_read_b128 v[232:235], v140 offset:55296
	ds_read_b128 v[236:239], v140 offset:56320
	global_load_lds_dwordx4 v[186:187], off
	v_lshl_add_u64 v[186:187], v[214:215], 0, s[96:97]
	s_mov_b32 m0, s63
	s_nop 0
	global_load_lds_dwordx4 v[186:187], off
	v_lshl_add_u64 v[186:187], s[30:31], 0, v[134:135]
	s_mov_b32 m0, s73
	s_nop 0
	global_load_lds_dwordx4 v[186:187], off
	v_lshl_add_u64 v[186:187], s[30:31], 0, v[130:131]
	s_mov_b32 m0, s72
	s_nop 0
	global_load_lds_dwordx4 v[186:187], off
	v_lshl_add_u64 v[186:187], v[240:241], 0, s[96:97]
	s_mov_b32 m0, s55
	s_nop 0
	global_load_lds_dwordx4 v[186:187], off
	v_lshl_add_u64 v[186:187], v[242:243], 0, s[96:97]
	s_mov_b32 m0, s56
	s_nop 0
	global_load_lds_dwordx4 v[186:187], off
	s_waitcnt vmcnt(8)
	s_waitcnt lgkmcnt(0)
	s_barrier
	s_setprio 1
	v_mfma_f32_16x16x32_bf16 v[94:97], v[142:145], v[174:177], v[94:97]
	v_mfma_f32_16x16x32_bf16 v[90:93], v[150:153], v[174:177], v[90:93]
	v_mfma_f32_16x16x32_bf16 v[86:89], v[142:145], v[182:185], v[86:89]
	v_mfma_f32_16x16x32_bf16 v[82:85], v[150:153], v[182:185], v[82:85]
	v_mfma_f32_16x16x32_bf16 v[74:77], v[142:145], v[206:209], v[74:77]
	v_mfma_f32_16x16x32_bf16 v[66:69], v[150:153], v[206:209], v[66:69]
	v_mfma_f32_16x16x32_bf16 v[58:61], v[142:145], v[232:235], v[58:61]
	v_mfma_f32_16x16x32_bf16 v[50:53], v[150:153], v[232:235], v[50:53]
	v_mfma_f32_16x16x32_bf16 v[94:97], v[146:149], v[178:181], v[94:97]
	v_mfma_f32_16x16x32_bf16 v[90:93], v[154:157], v[178:181], v[90:93]
	v_mfma_f32_16x16x32_bf16 v[86:89], v[146:149], v[202:205], v[86:89]
	v_mfma_f32_16x16x32_bf16 v[82:85], v[154:157], v[202:205], v[82:85]
	v_mfma_f32_16x16x32_bf16 v[74:77], v[146:149], v[210:213], v[74:77]
	v_mfma_f32_16x16x32_bf16 v[66:69], v[154:157], v[210:213], v[66:69]
	v_mfma_f32_16x16x32_bf16 v[58:61], v[146:149], v[236:239], v[58:61]
	v_mfma_f32_16x16x32_bf16 v[50:53], v[154:157], v[236:239], v[50:53]
	s_setprio 0
	s_setprio 1
	v_mfma_f32_16x16x32_bf16 v[30:33], v[158:161], v[174:177], v[30:33]
	v_mfma_f32_16x16x32_bf16 v[26:29], v[166:169], v[174:177], v[26:29]
	v_mfma_f32_16x16x32_bf16 v[22:25], v[158:161], v[182:185], v[22:25]
	v_mfma_f32_16x16x32_bf16 v[18:21], v[166:169], v[182:185], v[18:21]
	v_mfma_f32_16x16x32_bf16 v[14:17], v[158:161], v[206:209], v[14:17]
	v_mfma_f32_16x16x32_bf16 v[10:13], v[166:169], v[206:209], v[10:13]
	v_mfma_f32_16x16x32_bf16 v[6:9], v[158:161], v[232:235], v[6:9]
	v_mfma_f32_16x16x32_bf16 v[2:5], v[166:169], v[232:235], v[2:5]
	v_mfma_f32_16x16x32_bf16 v[30:33], v[162:165], v[178:181], v[30:33]
	v_mfma_f32_16x16x32_bf16 v[26:29], v[170:173], v[178:181], v[26:29]
	v_mfma_f32_16x16x32_bf16 v[22:25], v[162:165], v[202:205], v[22:25]
	v_mfma_f32_16x16x32_bf16 v[18:21], v[170:173], v[202:205], v[18:21]
	v_mfma_f32_16x16x32_bf16 v[14:17], v[162:165], v[210:213], v[14:17]
	v_mfma_f32_16x16x32_bf16 v[10:13], v[170:173], v[210:213], v[10:13]
	v_mfma_f32_16x16x32_bf16 v[6:9], v[162:165], v[236:239], v[6:9]
	v_mfma_f32_16x16x32_bf16 v[2:5], v[170:173], v[236:239], v[2:5]
	s_setprio 0
	s_barrier
	s_movk_i32 s34, 0x100
	s_andn2_b64 vcc, exec, s[28:29]
	s_mov_b64 s[30:31], -1
	s_mov_b64 s[28:29], 0
	s_cbranch_vccz .LBB0_1176
	s_and_b64 vcc, exec, s[16:17]
	s_cbranch_vccz .LBB0_1179
	s_barrier

; #define PG8_STAGE(bufoff, gbase, voff) do { _Pragma("unroll") for (int _i = 0; _i < 2; ++_i) \
;         __builtin_amdgcn_global_load_lds((const unsigned*)((const char*)(gbase) + (voff)[_i]), (PG8_LAS unsigned*)(lds + (bufoff) + ldsw + _i * 8192), 16, 0, 0); } while (0)
; #define PG8_LDA(dst, b, h) do { _Pragma("unroll") for (int m = 0; m < 4; ++m) _Pragma("unroll") for (int k = 0; k < 2; ++k) dst[m][k] = *(const PG8_LAS bf16x8*)(lds + PG8_SA(b, h) + aoff + m * 2048 + k * 1024); } while (0)
; #define PG8_LDB(dst, b, h) do { _Pragma("unroll") for (int n = 0; n < 2; ++n) _Pragma("unroll") for (int k = 0; k < 2; ++k) dst[n][k] = *(const PG8_LAS bf16x8*)(lds + PG8_SB(b, h) + boff + n * 2048 + k * 1024); } while (0)
; #define PG8_MMA(ai, bj, At, Bt) do { __builtin_amdgcn_s_setprio(1); _Pragma("unroll") for (int m = 0; m < 4; ++m) _Pragma("unroll") for (int n = 0; n < 2; ++n) _Pragma("unroll") for (int k = 0; k < 2; ++k) \
;         acc[ai][bj][m][n] = __builtin_amdgcn_mfma_f32_16x16x32_bf16(Bt[n][k], At[m][k], acc[ai][bj][m][n], 0, 0, 0); __builtin_amdgcn_s_setprio(0); } while (0)
; #define PG8_WAIT_V(n) asm volatile("s_waitcnt vmcnt(" #n ")" ::: "memory")
; #define PG8_WAIT_L(n) asm volatile("s_waitcnt lgkmcnt(" #n ")" ::: "memory")
; #define PG8_BAR __builtin_amdgcn_s_barrier()
; #define PG8_SCHED __builtin_amdgcn_sched_barrier(0)
; template <class Epi, class Sched, bool ALIGN_EPI = false, bool SP2 = false>
; __device__ __forceinline__ void gemm_phase(PG8_LAS unsigned char* lds, const Gemm g, const Sched& S, const Epi& E) {
;     ...
;             PG8_LDB(B0, 0, 0); PG8_LDB(B1, 0, 1); PG8_SCHED; PG8_LDA(At, 0, 0); PG8_STAGE(PG8_SA(1, 1), a1 + hstepA, voffA);
;             PG8_WAIT_V(8); PG8_WAIT_L(0); PG8_BAR; PG8_MMA(0, 0, At, B0); PG8_MMA(0, 1, At, B1); PG8_BAR; PG8_SCHED;
;             PG8_LDA(At, 0, 1); PG8_STAGE(PG8_SB(0, 0), b2, voffB); PG8_STAGE(PG8_SB(0, 1), b2 + hstepB, voffB); PG8_STAGE(PG8_SA(0, 0), a2, voffA);
.LBB0_1190:
	s_add_u32 s24, s22, 0xfffc0080
	s_addc_u32 s25, s23, -1
	s_add_i32 s51, 0, 0x10000
	s_cmp_eq_u32 s50, 12
	s_cselect_b32 s27, s44, s25
	s_cselect_b32 s26, s45, s24
	s_cselect_b32 s25, s46, s49
	s_cselect_b32 s24, s47, s48
	s_add_i32 s54, 0, 0x14000
	v_add_u32_e32 v142, s51, v168
	v_add_u32_e32 v166, s54, v168
	ds_read_b128 v[130:133], v142
	ds_read_b128 v[134:137], v142 offset:1024
	ds_read_b128 v[138:141], v142 offset:2048
	ds_read_b128 v[142:145], v142 offset:3072
	ds_read_b128 v[158:161], v166
	ds_read_b128 v[162:165], v166 offset:1024
	ds_read_b128 v[172:175], v166 offset:2048
	ds_read_b128 v[176:179], v166 offset:3072
	s_add_i32 m0, s7, 0xc000
	ds_read_b128 v[180:183], v171
	ds_read_b128 v[184:187], v171 offset:1024
	ds_read_b128 v[202:205], v171 offset:2048
	ds_read_b128 v[206:209], v171 offset:3072
	ds_read_b128 v[210:213], v171 offset:4096
	ds_read_b128 v[232:235], v171 offset:5120
	ds_read_b128 v[236:239], v171 offset:6144
	ds_read_b128 v[240:243], v171 offset:7168
	global_load_lds_dwordx4 v154, s[22:23]
	s_add_i32 m0, s7, 0xe000
	s_nop 0
	global_load_lds_dwordx4 v156, s[22:23]
	s_waitcnt vmcnt(8)
	s_waitcnt lgkmcnt(0)
	s_barrier
	s_setprio 1
	v_mfma_f32_16x16x32_bf16 v[126:129], v[130:133], v[180:183], v[126:129]
	v_mfma_f32_16x16x32_bf16 v[118:121], v[138:141], v[180:183], v[118:121]
	v_mfma_f32_16x16x32_bf16 v[110:113], v[130:133], v[202:205], v[110:113]
	v_mfma_f32_16x16x32_bf16 v[102:105], v[138:141], v[202:205], v[102:105]
	v_mfma_f32_16x16x32_bf16 v[94:97], v[130:133], v[210:213], v[94:97]
	v_mfma_f32_16x16x32_bf16 v[86:89], v[138:141], v[210:213], v[86:89]
	v_mfma_f32_16x16x32_bf16 v[78:81], v[130:133], v[236:239], v[78:81]
	v_mfma_f32_16x16x32_bf16 v[70:73], v[138:141], v[236:239], v[70:73]
	v_mfma_f32_16x16x32_bf16 v[126:129], v[134:137], v[184:187], v[126:129]
	v_mfma_f32_16x16x32_bf16 v[118:121], v[142:145], v[184:187], v[118:121]
	v_mfma_f32_16x16x32_bf16 v[110:113], v[134:137], v[206:209], v[110:113]
	v_mfma_f32_16x16x32_bf16 v[102:105], v[142:145], v[206:209], v[102:105]
	v_mfma_f32_16x16x32_bf16 v[94:97], v[134:137], v[232:235], v[94:97]
	v_mfma_f32_16x16x32_bf16 v[86:89], v[142:145], v[232:235], v[86:89]
	v_mfma_f32_16x16x32_bf16 v[78:81], v[134:137], v[240:243], v[78:81]
	v_mfma_f32_16x16x32_bf16 v[70:73], v[142:145], v[240:243], v[70:73]
	s_setprio 0
	s_setprio 1
	v_mfma_f32_16x16x32_bf16 v[122:125], v[158:161], v[180:183], v[122:125]
	v_mfma_f32_16x16x32_bf16 v[114:117], v[172:175], v[180:183], v[114:117]
	v_mfma_f32_16x16x32_bf16 v[106:109], v[158:161], v[202:205], v[106:109]
	v_mfma_f32_16x16x32_bf16 v[98:101], v[172:175], v[202:205], v[98:101]
	v_mfma_f32_16x16x32_bf16 v[90:93], v[158:161], v[210:213], v[90:93]
	v_mfma_f32_16x16x32_bf16 v[82:85], v[172:175], v[210:213], v[82:85]
	v_mfma_f32_16x16x32_bf16 v[74:77], v[158:161], v[236:239], v[74:77]
	v_mfma_f32_16x16x32_bf16 v[66:69], v[172:175], v[236:239], v[66:69]
	v_mfma_f32_16x16x32_bf16 v[122:125], v[162:165], v[184:187], v[122:125]
	v_mfma_f32_16x16x32_bf16 v[114:117], v[176:179], v[184:187], v[114:117]
	v_mfma_f32_16x16x32_bf16 v[106:109], v[162:165], v[206:209], v[106:109]
	v_mfma_f32_16x16x32_bf16 v[98:101], v[176:179], v[206:209], v[98:101]
	v_mfma_f32_16x16x32_bf16 v[90:93], v[162:165], v[232:235], v[90:93]
	v_mfma_f32_16x16x32_bf16 v[82:85], v[176:179], v[232:235], v[82:85]
	v_mfma_f32_16x16x32_bf16 v[74:77], v[162:165], v[240:243], v[74:77]
	v_mfma_f32_16x16x32_bf16 v[66:69], v[176:179], v[240:243], v[66:69]
	s_setprio 0
	s_barrier
	s_add_i32 s51, s51, s30
	s_mov_b32 m0, s51
	ds_read_b128 v[180:183], v171 offset:16384
	ds_read_b128 v[184:187], v171 offset:17408
	ds_read_b128 v[202:205], v171 offset:18432
	ds_read_b128 v[206:209], v171 offset:19456
	ds_read_b128 v[210:213], v171 offset:20480
	ds_read_b128 v[232:235], v171 offset:21504
	ds_read_b128 v[236:239], v171 offset:22528
	ds_read_b128 v[240:243], v171 offset:23552
	s_add_u32 s60, s24, 0x80
	s_addc_u32 s61, s25, 0
	s_add_u32 s62, s26, 0x80
	s_addc_u32 s63, s27, 0
	global_load_lds_dwordx4 v150, s[24:25]
	s_add_i32 m0, s51, 0x2000
	s_add_u32 s52, s24, 0x40000
	s_addc_u32 s53, s25, 0
	s_add_i32 s51, s54, s30
	global_load_lds_dwordx4 v146, s[24:25]
	s_mov_b32 m0, s51
	s_nop 0
	global_load_lds_dwordx4 v150, s[52:53]
	s_add_i32 m0, s51, 0x2000
	s_nop 0
	global_load_lds_dwordx4 v146, s[52:53]
	s_mov_b32 m0, s7
	s_nop 0
	global_load_lds_dwordx4 v152, s[26:27]
	s_mov_b32 m0, s36
	s_nop 0
	global_load_lds_dwordx4 v148, s[26:27]
	s_waitcnt vmcnt(8)
	s_waitcnt lgkmcnt(0)
	s_barrier
; #define PG8_STAGE(bufoff, gbase, voff) do { _Pragma("unroll") for (int _i = 0; _i < 2; ++_i) \
;         __builtin_amdgcn_global_load_lds((const unsigned*)((const char*)(gbase) + (voff)[_i]), (PG8_LAS unsigned*)(lds + (bufoff) + ldsw + _i * 8192), 16, 0, 0); } while (0)
; #define PG8_LDA(dst, b, h) do { _Pragma("unroll") for (int m = 0; m < 4; ++m) _Pragma("unroll") for (int k = 0; k < 2; ++k) dst[m][k] = *(const PG8_LAS bf16x8*)(lds + PG8_SA(b, h) + aoff + m * 2048 + k * 1024); } while (0)
; #define PG8_LDB(dst, b, h) do { _Pragma("unroll") for (int n = 0; n < 2; ++n) _Pragma("unroll") for (int k = 0; k < 2; ++k) dst[n][k] = *(const PG8_LAS bf16x8*)(lds + PG8_SB(b, h) + boff + n * 2048 + k * 1024); } while (0)
; #define PG8_MMA(ai, bj, At, Bt) do { __builtin_amdgcn_s_setprio(1); _Pragma("unroll") for (int m = 0; m < 4; ++m) _Pragma("unroll") for (int n = 0; n < 2; ++n) _Pragma("unroll") for (int k = 0; k < 2; ++k) \
;         acc[ai][bj][m][n] = __builtin_amdgcn_mfma_f32_16x16x32_bf16(Bt[n][k], At[m][k], acc[ai][bj][m][n], 0, 0, 0); __builtin_amdgcn_s_setprio(0); } while (0)
; #define PG8_WAIT_V(n) asm volatile("s_waitcnt vmcnt(" #n ")" ::: "memory")
; #define PG8_WAIT_L(n) asm volatile("s_waitcnt lgkmcnt(" #n ")" ::: "memory")
; #define PG8_BAR __builtin_amdgcn_s_barrier()
; #define PG8_SCHED __builtin_amdgcn_sched_barrier(0)
; template <class Epi, class Sched, bool ALIGN_EPI = false, bool SP2 = false>
; __device__ __forceinline__ void gemm_phase(PG8_LAS unsigned char* lds, const Gemm g, const Sched& S, const Epi& E) {
;     ...
;             PG8_WAIT_V(8); PG8_WAIT_L(0); PG8_BAR; PG8_MMA(1, 0, At, B0); PG8_MMA(1, 1, At, B1); PG8_BAR; PG8_SCHED;
;             PG8_LDB(B0, 1, 0); PG8_LDB(B1, 1, 1); PG8_SCHED; PG8_LDA(At, 1, 0); PG8_STAGE(PG8_SA(0, 1), a2 + hstepA, voffA);
;             PG8_WAIT_V(8); PG8_WAIT_L(0); PG8_BAR; PG8_MMA(0, 0, At, B0); PG8_MMA(0, 1, At, B1); PG8_BAR; PG8_SCHED;
	s_setprio 1
	v_mfma_f32_16x16x32_bf16 v[62:65], v[130:133], v[180:183], v[62:65]
	v_mfma_f32_16x16x32_bf16 v[54:57], v[138:141], v[180:183], v[54:57]
	v_mfma_f32_16x16x32_bf16 v[46:49], v[130:133], v[202:205], v[46:49]
	v_mfma_f32_16x16x32_bf16 v[38:41], v[138:141], v[202:205], v[38:41]
	v_mfma_f32_16x16x32_bf16 v[30:33], v[130:133], v[210:213], v[30:33]
	v_mfma_f32_16x16x32_bf16 v[22:25], v[138:141], v[210:213], v[22:25]
	v_mfma_f32_16x16x32_bf16 v[14:17], v[130:133], v[236:239], v[14:17]
	v_mfma_f32_16x16x32_bf16 v[6:9], v[138:141], v[236:239], v[6:9]
	v_mfma_f32_16x16x32_bf16 v[62:65], v[134:137], v[184:187], v[62:65]
	v_mfma_f32_16x16x32_bf16 v[54:57], v[142:145], v[184:187], v[54:57]
	v_mfma_f32_16x16x32_bf16 v[46:49], v[134:137], v[206:209], v[46:49]
	v_mfma_f32_16x16x32_bf16 v[38:41], v[142:145], v[206:209], v[38:41]
	v_mfma_f32_16x16x32_bf16 v[30:33], v[134:137], v[232:235], v[30:33]
	v_mfma_f32_16x16x32_bf16 v[22:25], v[142:145], v[232:235], v[22:25]
	v_mfma_f32_16x16x32_bf16 v[14:17], v[134:137], v[240:243], v[14:17]
	v_mfma_f32_16x16x32_bf16 v[6:9], v[142:145], v[240:243], v[6:9]
	s_setprio 0
	s_setprio 1
	v_mfma_f32_16x16x32_bf16 v[58:61], v[158:161], v[180:183], v[58:61]
	v_mfma_f32_16x16x32_bf16 v[50:53], v[172:175], v[180:183], v[50:53]
	v_mfma_f32_16x16x32_bf16 v[42:45], v[158:161], v[202:205], v[42:45]
	v_mfma_f32_16x16x32_bf16 v[34:37], v[172:175], v[202:205], v[34:37]
	v_mfma_f32_16x16x32_bf16 v[26:29], v[158:161], v[210:213], v[26:29]
	v_mfma_f32_16x16x32_bf16 v[18:21], v[172:175], v[210:213], v[18:21]
	v_mfma_f32_16x16x32_bf16 v[10:13], v[158:161], v[236:239], v[10:13]
	v_mfma_f32_16x16x32_bf16 v[2:5], v[172:175], v[236:239], v[2:5]
	v_mfma_f32_16x16x32_bf16 v[58:61], v[162:165], v[184:187], v[58:61]
	v_mfma_f32_16x16x32_bf16 v[50:53], v[176:179], v[184:187], v[50:53]
	v_mfma_f32_16x16x32_bf16 v[42:45], v[162:165], v[206:209], v[42:45]
	v_mfma_f32_16x16x32_bf16 v[34:37], v[176:179], v[206:209], v[34:37]
	v_mfma_f32_16x16x32_bf16 v[26:29], v[162:165], v[232:235], v[26:29]
	v_mfma_f32_16x16x32_bf16 v[18:21], v[176:179], v[232:235], v[18:21]
	v_mfma_f32_16x16x32_bf16 v[10:13], v[162:165], v[240:243], v[10:13]
	v_mfma_f32_16x16x32_bf16 v[2:5], v[176:179], v[240:243], v[2:5]
	s_setprio 0
	s_barrier
	s_add_i32 s51, 0, 0x18000
	s_add_i32 s52, 0, 0x1c000
	v_add_u32_e32 v142, s51, v168
	v_add_u32_e32 v176, s52, v168
	ds_read_b128 v[130:133], v142
	ds_read_b128 v[134:137], v142 offset:1024
	ds_read_b128 v[138:141], v142 offset:2048
	ds_read_b128 v[142:145], v142 offset:3072
	ds_read_b128 v[158:161], v176
	ds_read_b128 v[162:165], v176 offset:1024
	ds_read_b128 v[172:175], v176 offset:2048
	ds_read_b128 v[176:179], v176 offset:3072
	s_add_u32 s26, s26, 0x40000
	s_addc_u32 s27, s27, 0
	s_mov_b32 m0, s37
	ds_read_b128 v[180:183], v171 offset:32768
	ds_read_b128 v[184:187], v171 offset:33792
	ds_read_b128 v[202:205], v171 offset:34816
	ds_read_b128 v[206:209], v171 offset:35840
	ds_read_b128 v[210:213], v171 offset:36864
	ds_read_b128 v[232:235], v171 offset:37888
	ds_read_b128 v[236:239], v171 offset:38912
	ds_read_b128 v[240:243], v171 offset:39936
	global_load_lds_dwordx4 v152, s[26:27]
	s_mov_b32 m0, s38
	s_nop 0
	global_load_lds_dwordx4 v148, s[26:27]
	s_waitcnt vmcnt(8)
	s_waitcnt lgkmcnt(0)
	s_barrier
	s_setprio 1
	v_mfma_f32_16x16x32_bf16 v[126:129], v[130:133], v[180:183], v[126:129]
	v_mfma_f32_16x16x32_bf16 v[118:121], v[138:141], v[180:183], v[118:121]
	v_mfma_f32_16x16x32_bf16 v[110:113], v[130:133], v[202:205], v[110:113]
	v_mfma_f32_16x16x32_bf16 v[102:105], v[138:141], v[202:205], v[102:105]
	v_mfma_f32_16x16x32_bf16 v[94:97], v[130:133], v[210:213], v[94:97]
	v_mfma_f32_16x16x32_bf16 v[86:89], v[138:141], v[210:213], v[86:89]
	v_mfma_f32_16x16x32_bf16 v[78:81], v[130:133], v[236:239], v[78:81]
	v_mfma_f32_16x16x32_bf16 v[70:73], v[138:141], v[236:239], v[70:73]
	v_mfma_f32_16x16x32_bf16 v[126:129], v[134:137], v[184:187], v[126:129]
	v_mfma_f32_16x16x32_bf16 v[118:121], v[142:145], v[184:187], v[118:121]
	v_mfma_f32_16x16x32_bf16 v[110:113], v[134:137], v[206:209], v[110:113]
	v_mfma_f32_16x16x32_bf16 v[102:105], v[142:145], v[206:209], v[102:105]
	v_mfma_f32_16x16x32_bf16 v[94:97], v[134:137], v[232:235], v[94:97]
	v_mfma_f32_16x16x32_bf16 v[86:89], v[142:145], v[232:235], v[86:89]
	v_mfma_f32_16x16x32_bf16 v[78:81], v[134:137], v[240:243], v[78:81]
	v_mfma_f32_16x16x32_bf16 v[70:73], v[142:145], v[240:243], v[70:73]
	s_setprio 0
	s_setprio 1
	v_mfma_f32_16x16x32_bf16 v[122:125], v[158:161], v[180:183], v[122:125]
	v_mfma_f32_16x16x32_bf16 v[114:117], v[172:175], v[180:183], v[114:117]
	v_mfma_f32_16x16x32_bf16 v[106:109], v[158:161], v[202:205], v[106:109]
	v_mfma_f32_16x16x32_bf16 v[98:101], v[172:175], v[202:205], v[98:101]
	v_mfma_f32_16x16x32_bf16 v[90:93], v[158:161], v[210:213], v[90:93]
	v_mfma_f32_16x16x32_bf16 v[82:85], v[172:175], v[210:213], v[82:85]
	v_mfma_f32_16x16x32_bf16 v[74:77], v[158:161], v[236:239], v[74:77]
	v_mfma_f32_16x16x32_bf16 v[66:69], v[172:175], v[236:239], v[66:69]
	v_mfma_f32_16x16x32_bf16 v[122:125], v[162:165], v[184:187], v[122:125]
	v_mfma_f32_16x16x32_bf16 v[114:117], v[176:179], v[184:187], v[114:117]
	v_mfma_f32_16x16x32_bf16 v[106:109], v[162:165], v[206:209], v[106:109]
	v_mfma_f32_16x16x32_bf16 v[98:101], v[176:179], v[206:209], v[98:101]
	v_mfma_f32_16x16x32_bf16 v[90:93], v[162:165], v[232:235], v[90:93]
	v_mfma_f32_16x16x32_bf16 v[82:85], v[176:179], v[232:235], v[82:85]
	v_mfma_f32_16x16x32_bf16 v[74:77], v[162:165], v[240:243], v[74:77]
	v_mfma_f32_16x16x32_bf16 v[66:69], v[176:179], v[240:243], v[66:69]
	s_setprio 0
	s_barrier
; #define PG8_STAGE(bufoff, gbase, voff) do { _Pragma("unroll") for (int _i = 0; _i < 2; ++_i) \
;         __builtin_amdgcn_global_load_lds((const unsigned*)((const char*)(gbase) + (voff)[_i]), (PG8_LAS unsigned*)(lds + (bufoff) + ldsw + _i * 8192), 16, 0, 0); } while (0)
; #define PG8_LDA(dst, b, h) do { _Pragma("unroll") for (int m = 0; m < 4; ++m) _Pragma("unroll") for (int k = 0; k < 2; ++k) dst[m][k] = *(const PG8_LAS bf16x8*)(lds + PG8_SA(b, h) + aoff + m * 2048 + k * 1024); } while (0)
; #define PG8_MMA(ai, bj, At, Bt) do { __builtin_amdgcn_s_setprio(1); _Pragma("unroll") for (int m = 0; m < 4; ++m) _Pragma("unroll") for (int n = 0; n < 2; ++n) _Pragma("unroll") for (int k = 0; k < 2; ++k) \
;         acc[ai][bj][m][n] = __builtin_amdgcn_mfma_f32_16x16x32_bf16(Bt[n][k], At[m][k], acc[ai][bj][m][n], 0, 0, 0); __builtin_amdgcn_s_setprio(0); } while (0)
; #define PG8_WAIT_V(n) asm volatile("s_waitcnt vmcnt(" #n ")" ::: "memory")
; #define PG8_WAIT_L(n) asm volatile("s_waitcnt lgkmcnt(" #n ")" ::: "memory")
; #define PG8_BAR __builtin_amdgcn_s_barrier()
; #define PG8_SCHED __builtin_amdgcn_sched_barrier(0)
; template <class Epi, class Sched, bool ALIGN_EPI = false, bool SP2 = false>
; __device__ __forceinline__ void gemm_phase(PG8_LAS unsigned char* lds, const Gemm g, const Sched& S, const Epi& E) {
;     ...
;             PG8_LDA(At, 1, 1); PG8_STAGE(PG8_SB(1, 0), b3, voffB); PG8_STAGE(PG8_SB(1, 1), b3 + hstepB, voffB); PG8_STAGE(PG8_SA(1, 0), a3, voffA);
;             PG8_WAIT_V(8); PG8_WAIT_L(0); PG8_BAR; PG8_MMA(1, 0, At, B0); PG8_MMA(1, 1, At, B1); PG8_BAR; PG8_SCHED;
	s_add_i32 s26, s51, s30
	s_mov_b32 m0, s26
	ds_read_b128 v[180:183], v171 offset:49152
	ds_read_b128 v[184:187], v171 offset:50176
	ds_read_b128 v[202:205], v171 offset:51200
	ds_read_b128 v[206:209], v171 offset:52224
	ds_read_b128 v[210:213], v171 offset:53248
	ds_read_b128 v[232:235], v171 offset:54272
	ds_read_b128 v[236:239], v171 offset:55296
	ds_read_b128 v[240:243], v171 offset:56320
	global_load_lds_dwordx4 v150, s[60:61]
	s_add_i32 m0, s26, 0x2000
	s_add_u32 s24, s24, 0x40080
	s_addc_u32 s25, s25, 0
	s_add_i32 s26, s52, s30
	global_load_lds_dwordx4 v146, s[60:61]
	s_mov_b32 m0, s26
	s_nop 0
	global_load_lds_dwordx4 v150, s[24:25]
	s_add_i32 m0, s26, 0x2000
	s_nop 0
	global_load_lds_dwordx4 v146, s[24:25]
	s_mov_b32 m0, s39
	s_nop 0
	global_load_lds_dwordx4 v152, s[62:63]
	s_mov_b32 m0, s40
	s_nop 0
	global_load_lds_dwordx4 v148, s[62:63]
	s_waitcnt vmcnt(8)
	s_waitcnt lgkmcnt(0)
	s_barrier
	s_setprio 1
	v_mfma_f32_16x16x32_bf16 v[62:65], v[130:133], v[180:183], v[62:65]
	v_mfma_f32_16x16x32_bf16 v[54:57], v[138:141], v[180:183], v[54:57]
	v_mfma_f32_16x16x32_bf16 v[46:49], v[130:133], v[202:205], v[46:49]
	v_mfma_f32_16x16x32_bf16 v[38:41], v[138:141], v[202:205], v[38:41]
	v_mfma_f32_16x16x32_bf16 v[30:33], v[130:133], v[210:213], v[30:33]
	v_mfma_f32_16x16x32_bf16 v[22:25], v[138:141], v[210:213], v[22:25]
	v_mfma_f32_16x16x32_bf16 v[14:17], v[130:133], v[236:239], v[14:17]
	v_mfma_f32_16x16x32_bf16 v[6:9], v[138:141], v[236:239], v[6:9]
	v_mfma_f32_16x16x32_bf16 v[62:65], v[134:137], v[184:187], v[62:65]
	v_mfma_f32_16x16x32_bf16 v[54:57], v[142:145], v[184:187], v[54:57]
	v_mfma_f32_16x16x32_bf16 v[46:49], v[134:137], v[206:209], v[46:49]
	v_mfma_f32_16x16x32_bf16 v[38:41], v[142:145], v[206:209], v[38:41]
	v_mfma_f32_16x16x32_bf16 v[30:33], v[134:137], v[232:235], v[30:33]
	v_mfma_f32_16x16x32_bf16 v[22:25], v[142:145], v[232:235], v[22:25]
	v_mfma_f32_16x16x32_bf16 v[14:17], v[134:137], v[240:243], v[14:17]
	v_mfma_f32_16x16x32_bf16 v[6:9], v[142:145], v[240:243], v[6:9]
	s_setprio 0
	s_setprio 1
	v_mfma_f32_16x16x32_bf16 v[58:61], v[158:161], v[180:183], v[58:61]
	v_mfma_f32_16x16x32_bf16 v[50:53], v[172:175], v[180:183], v[50:53]
	v_mfma_f32_16x16x32_bf16 v[42:45], v[158:161], v[202:205], v[42:45]
	v_mfma_f32_16x16x32_bf16 v[34:37], v[172:175], v[202:205], v[34:37]
	v_mfma_f32_16x16x32_bf16 v[26:29], v[158:161], v[210:213], v[26:29]
	v_mfma_f32_16x16x32_bf16 v[18:21], v[172:175], v[210:213], v[18:21]
	v_mfma_f32_16x16x32_bf16 v[10:13], v[158:161], v[236:239], v[10:13]
	v_mfma_f32_16x16x32_bf16 v[2:5], v[172:175], v[236:239], v[2:5]
	v_mfma_f32_16x16x32_bf16 v[58:61], v[162:165], v[184:187], v[58:61]
	v_mfma_f32_16x16x32_bf16 v[50:53], v[176:179], v[184:187], v[50:53]
	v_mfma_f32_16x16x32_bf16 v[42:45], v[162:165], v[206:209], v[42:45]
	v_mfma_f32_16x16x32_bf16 v[34:37], v[176:179], v[206:209], v[34:37]
	v_mfma_f32_16x16x32_bf16 v[26:29], v[162:165], v[232:235], v[26:29]
	v_mfma_f32_16x16x32_bf16 v[18:21], v[176:179], v[232:235], v[18:21]
	v_mfma_f32_16x16x32_bf16 v[10:13], v[162:165], v[240:243], v[10:13]
	v_mfma_f32_16x16x32_bf16 v[2:5], v[176:179], v[240:243], v[2:5]
	s_setprio 0
	s_barrier
	s_add_i32 s50, s50, 2
	s_add_u32 s22, s22, 0x100
	s_addc_u32 s23, s23, 0
	s_add_u32 s48, s48, 0x100
	s_addc_u32 s49, s49, 0
	s_cmp_gt_u32 s50, 13
	s_cbranch_scc0 .LBB0_1190
	s_and_b64 vcc, exec, s[18:19]
	s_cbranch_vccz .LBB0_1193
	s_barrier

; #define PG8_STAGE(bufoff, gbase, voff) do { _Pragma("unroll") for (int _i = 0; _i < 2; ++_i) \
;         __builtin_amdgcn_global_load_lds((const unsigned*)((const char*)(gbase) + (voff)[_i]), (PG8_LAS unsigned*)(lds + (bufoff) + ldsw + _i * 8192), 16, 0, 0); } while (0)
; #define PG8_LDA(dst, b, h) do { _Pragma("unroll") for (int m = 0; m < 4; ++m) _Pragma("unroll") for (int k = 0; k < 2; ++k) dst[m][k] = *(const PG8_LAS bf16x8*)(lds + PG8_SA(b, h) + aoff + m * 2048 + k * 1024); } while (0)
; #define PG8_LDB(dst, b, h) do { _Pragma("unroll") for (int n = 0; n < 2; ++n) _Pragma("unroll") for (int k = 0; k < 2; ++k) dst[n][k] = *(const PG8_LAS bf16x8*)(lds + PG8_SB(b, h) + boff + n * 2048 + k * 1024); } while (0)
; #define PG8_MMA(ai, bj, At, Bt) do { __builtin_amdgcn_s_setprio(1); _Pragma("unroll") for (int m = 0; m < 4; ++m) _Pragma("unroll") for (int n = 0; n < 2; ++n) _Pragma("unroll") for (int k = 0; k < 2; ++k) \
;         acc[ai][bj][m][n] = __builtin_amdgcn_mfma_f32_16x16x32_bf16(Bt[n][k], At[m][k], acc[ai][bj][m][n], 0, 0, 0); __builtin_amdgcn_s_setprio(0); } while (0)
; #define PG8_WAIT_V(n) asm volatile("s_waitcnt vmcnt(" #n ")" ::: "memory")
; #define PG8_WAIT_L(n) asm volatile("s_waitcnt lgkmcnt(" #n ")" ::: "memory")
; #define PG8_BAR __builtin_amdgcn_s_barrier()
; #define PG8_SCHED __builtin_amdgcn_sched_barrier(0)
; template <class Epi, class Sched, bool ALIGN_EPI = false, bool SP2 = false>
; __device__ __forceinline__ void gemm_phase(PG8_LAS unsigned char* lds, const Gemm g, const Sched& S, const Epi& E) {
;     ...
;             PG8_LDB(B0, 0, 0); PG8_LDB(B1, 0, 1); PG8_SCHED; PG8_LDA(At, 0, 0); PG8_STAGE(PG8_SA(1, 1), a1 + hstepA, voffA);
;             PG8_WAIT_V(8); PG8_WAIT_L(0); PG8_BAR; PG8_MMA(0, 0, At, B0); PG8_MMA(0, 1, At, B1); PG8_BAR; PG8_SCHED;
;             PG8_LDA(At, 0, 1); PG8_STAGE(PG8_SB(0, 0), b2, voffB); PG8_STAGE(PG8_SB(0, 1), b2 + hstepB, voffB); PG8_STAGE(PG8_SA(0, 0), a2, voffA);
.LBB0_1270:
	s_add_u32 s28, s26, 0xfffc0080
	s_addc_u32 s29, s27, -1
	s_add_i32 s52, 0, 0x10000
	s_cmp_eq_u32 s51, 12
	s_cselect_b32 s31, s17, s29
	s_cselect_b32 s30, s23, s28
	s_cselect_b32 s29, s15, s50
	s_cselect_b32 s28, s25, s49
	s_add_i32 s54, 0, 0x14000
	v_add_u32_e32 v142, s52, v186
	v_add_u32_e32 v172, s54, v186
	ds_read_b128 v[130:133], v142
	ds_read_b128 v[134:137], v142 offset:1024
	ds_read_b128 v[138:141], v142 offset:2048
	ds_read_b128 v[142:145], v142 offset:3072
	ds_read_b128 v[146:149], v172
	ds_read_b128 v[150:153], v172 offset:1024
	ds_read_b128 v[168:171], v172 offset:2048
	ds_read_b128 v[172:175], v172 offset:3072
	s_add_i32 m0, s39, 0xc000
	ds_read_b128 v[176:179], v200
	ds_read_b128 v[180:183], v200 offset:1024
	ds_read_b128 v[202:205], v200 offset:2048
	ds_read_b128 v[206:209], v200 offset:3072
	ds_read_b128 v[210:213], v200 offset:4096
	ds_read_b128 v[232:235], v200 offset:5120
	ds_read_b128 v[236:239], v200 offset:6144
	ds_read_b128 v[240:243], v200 offset:7168
	global_load_lds_dwordx4 v164, s[26:27]
	s_add_i32 m0, s39, 0xe000
	s_nop 0
	global_load_lds_dwordx4 v166, s[26:27]
	s_waitcnt vmcnt(8)
	s_waitcnt lgkmcnt(0)
	s_barrier
	s_setprio 1
	v_mfma_f32_16x16x32_bf16 v[126:129], v[130:133], v[176:179], v[126:129]
	v_mfma_f32_16x16x32_bf16 v[122:125], v[138:141], v[176:179], v[122:125]
	v_mfma_f32_16x16x32_bf16 v[110:113], v[130:133], v[202:205], v[110:113]
	v_mfma_f32_16x16x32_bf16 v[106:109], v[138:141], v[202:205], v[106:109]
	v_mfma_f32_16x16x32_bf16 v[94:97], v[130:133], v[210:213], v[94:97]
	v_mfma_f32_16x16x32_bf16 v[90:93], v[138:141], v[210:213], v[90:93]
	v_mfma_f32_16x16x32_bf16 v[78:81], v[130:133], v[236:239], v[78:81]
	v_mfma_f32_16x16x32_bf16 v[74:77], v[138:141], v[236:239], v[74:77]
	v_mfma_f32_16x16x32_bf16 v[126:129], v[134:137], v[180:183], v[126:129]
	v_mfma_f32_16x16x32_bf16 v[122:125], v[142:145], v[180:183], v[122:125]
	v_mfma_f32_16x16x32_bf16 v[110:113], v[134:137], v[206:209], v[110:113]
	v_mfma_f32_16x16x32_bf16 v[106:109], v[142:145], v[206:209], v[106:109]
	v_mfma_f32_16x16x32_bf16 v[94:97], v[134:137], v[232:235], v[94:97]
	v_mfma_f32_16x16x32_bf16 v[90:93], v[142:145], v[232:235], v[90:93]
	v_mfma_f32_16x16x32_bf16 v[78:81], v[134:137], v[240:243], v[78:81]
	v_mfma_f32_16x16x32_bf16 v[74:77], v[142:145], v[240:243], v[74:77]
	s_setprio 0
	s_setprio 1
	v_mfma_f32_16x16x32_bf16 v[118:121], v[146:149], v[176:179], v[118:121]
	v_mfma_f32_16x16x32_bf16 v[114:117], v[168:171], v[176:179], v[114:117]
	v_mfma_f32_16x16x32_bf16 v[102:105], v[146:149], v[202:205], v[102:105]
	v_mfma_f32_16x16x32_bf16 v[98:101], v[168:171], v[202:205], v[98:101]
	v_mfma_f32_16x16x32_bf16 v[86:89], v[146:149], v[210:213], v[86:89]
	v_mfma_f32_16x16x32_bf16 v[82:85], v[168:171], v[210:213], v[82:85]
	v_mfma_f32_16x16x32_bf16 v[70:73], v[146:149], v[236:239], v[70:73]
	v_mfma_f32_16x16x32_bf16 v[66:69], v[168:171], v[236:239], v[66:69]
	v_mfma_f32_16x16x32_bf16 v[118:121], v[150:153], v[180:183], v[118:121]
	v_mfma_f32_16x16x32_bf16 v[114:117], v[172:175], v[180:183], v[114:117]
	v_mfma_f32_16x16x32_bf16 v[102:105], v[150:153], v[206:209], v[102:105]
	v_mfma_f32_16x16x32_bf16 v[98:101], v[172:175], v[206:209], v[98:101]
	v_mfma_f32_16x16x32_bf16 v[86:89], v[150:153], v[232:235], v[86:89]
	v_mfma_f32_16x16x32_bf16 v[82:85], v[172:175], v[232:235], v[82:85]
	v_mfma_f32_16x16x32_bf16 v[70:73], v[150:153], v[240:243], v[70:73]
	v_mfma_f32_16x16x32_bf16 v[66:69], v[172:175], v[240:243], v[66:69]
	s_setprio 0
	s_barrier
	s_add_i32 s52, s52, s38
	s_mov_b32 m0, s52
	ds_read_b128 v[176:179], v200 offset:16384
	ds_read_b128 v[180:183], v200 offset:17408
	ds_read_b128 v[202:205], v200 offset:18432
	ds_read_b128 v[206:209], v200 offset:19456
	ds_read_b128 v[210:213], v200 offset:20480
	ds_read_b128 v[232:235], v200 offset:21504
	ds_read_b128 v[236:239], v200 offset:22528
	ds_read_b128 v[240:243], v200 offset:23552
	s_add_u32 s60, s28, 0x80
	s_addc_u32 s61, s29, 0
	s_add_u32 s62, s30, 0x80
	s_addc_u32 s63, s31, 0
	global_load_lds_dwordx4 v156, s[28:29]
	s_add_i32 m0, s52, 0x2000
	s_add_u32 s52, s28, 0x40000
	s_addc_u32 s53, s29, 0
	s_add_i32 s54, s54, s38
	global_load_lds_dwordx4 v160, s[28:29]
	s_mov_b32 m0, s54
	s_nop 0
	global_load_lds_dwordx4 v156, s[52:53]
	s_add_i32 m0, s54, 0x2000
	s_nop 0
	global_load_lds_dwordx4 v160, s[52:53]
	s_mov_b32 m0, s39
	s_nop 0
	global_load_lds_dwordx4 v154, s[30:31]
	s_mov_b32 m0, s40
	s_nop 0
	global_load_lds_dwordx4 v158, s[30:31]
	s_waitcnt vmcnt(8)
	s_waitcnt lgkmcnt(0)
	s_barrier
; #define PG8_STAGE(bufoff, gbase, voff) do { _Pragma("unroll") for (int _i = 0; _i < 2; ++_i) \
;         __builtin_amdgcn_global_load_lds((const unsigned*)((const char*)(gbase) + (voff)[_i]), (PG8_LAS unsigned*)(lds + (bufoff) + ldsw + _i * 8192), 16, 0, 0); } while (0)
; #define PG8_LDA(dst, b, h) do { _Pragma("unroll") for (int m = 0; m < 4; ++m) _Pragma("unroll") for (int k = 0; k < 2; ++k) dst[m][k] = *(const PG8_LAS bf16x8*)(lds + PG8_SA(b, h) + aoff + m * 2048 + k * 1024); } while (0)
; #define PG8_LDB(dst, b, h) do { _Pragma("unroll") for (int n = 0; n < 2; ++n) _Pragma("unroll") for (int k = 0; k < 2; ++k) dst[n][k] = *(const PG8_LAS bf16x8*)(lds + PG8_SB(b, h) + boff + n * 2048 + k * 1024); } while (0)
; #define PG8_MMA(ai, bj, At, Bt) do { __builtin_amdgcn_s_setprio(1); _Pragma("unroll") for (int m = 0; m < 4; ++m) _Pragma("unroll") for (int n = 0; n < 2; ++n) _Pragma("unroll") for (int k = 0; k < 2; ++k) \
;         acc[ai][bj][m][n] = __builtin_amdgcn_mfma_f32_16x16x32_bf16(Bt[n][k], At[m][k], acc[ai][bj][m][n], 0, 0, 0); __builtin_amdgcn_s_setprio(0); } while (0)
; #define PG8_WAIT_V(n) asm volatile("s_waitcnt vmcnt(" #n ")" ::: "memory")
; #define PG8_WAIT_L(n) asm volatile("s_waitcnt lgkmcnt(" #n ")" ::: "memory")
; #define PG8_BAR __builtin_amdgcn_s_barrier()
; #define PG8_SCHED __builtin_amdgcn_sched_barrier(0)
; template <class Epi, class Sched, bool ALIGN_EPI = false, bool SP2 = false>
; __device__ __forceinline__ void gemm_phase(PG8_LAS unsigned char* lds, const Gemm g, const Sched& S, const Epi& E) {
;     ...
;             PG8_WAIT_V(8); PG8_WAIT_L(0); PG8_BAR; PG8_MMA(1, 0, At, B0); PG8_MMA(1, 1, At, B1); PG8_BAR; PG8_SCHED;
;             PG8_LDB(B0, 1, 0); PG8_LDB(B1, 1, 1); PG8_SCHED; PG8_LDA(At, 1, 0); PG8_STAGE(PG8_SA(0, 1), a2 + hstepA, voffA);
;             PG8_WAIT_V(8); PG8_WAIT_L(0); PG8_BAR; PG8_MMA(0, 0, At, B0); PG8_MMA(0, 1, At, B1); PG8_BAR; PG8_SCHED;
	s_setprio 1
	v_mfma_f32_16x16x32_bf16 v[62:65], v[130:133], v[176:179], v[62:65]
	v_mfma_f32_16x16x32_bf16 v[58:61], v[138:141], v[176:179], v[58:61]
	v_mfma_f32_16x16x32_bf16 v[46:49], v[130:133], v[202:205], v[46:49]
	v_mfma_f32_16x16x32_bf16 v[42:45], v[138:141], v[202:205], v[42:45]
	v_mfma_f32_16x16x32_bf16 v[30:33], v[130:133], v[210:213], v[30:33]
	v_mfma_f32_16x16x32_bf16 v[26:29], v[138:141], v[210:213], v[26:29]
	v_mfma_f32_16x16x32_bf16 v[14:17], v[130:133], v[236:239], v[14:17]
	v_mfma_f32_16x16x32_bf16 v[10:13], v[138:141], v[236:239], v[10:13]
	v_mfma_f32_16x16x32_bf16 v[62:65], v[134:137], v[180:183], v[62:65]
	v_mfma_f32_16x16x32_bf16 v[58:61], v[142:145], v[180:183], v[58:61]
	v_mfma_f32_16x16x32_bf16 v[46:49], v[134:137], v[206:209], v[46:49]
	v_mfma_f32_16x16x32_bf16 v[42:45], v[142:145], v[206:209], v[42:45]
	v_mfma_f32_16x16x32_bf16 v[30:33], v[134:137], v[232:235], v[30:33]
	v_mfma_f32_16x16x32_bf16 v[26:29], v[142:145], v[232:235], v[26:29]
	v_mfma_f32_16x16x32_bf16 v[14:17], v[134:137], v[240:243], v[14:17]
	v_mfma_f32_16x16x32_bf16 v[10:13], v[142:145], v[240:243], v[10:13]
	s_setprio 0
	s_setprio 1
	v_mfma_f32_16x16x32_bf16 v[54:57], v[146:149], v[176:179], v[54:57]
	v_mfma_f32_16x16x32_bf16 v[50:53], v[168:171], v[176:179], v[50:53]
	v_mfma_f32_16x16x32_bf16 v[38:41], v[146:149], v[202:205], v[38:41]
	v_mfma_f32_16x16x32_bf16 v[34:37], v[168:171], v[202:205], v[34:37]
	v_mfma_f32_16x16x32_bf16 v[22:25], v[146:149], v[210:213], v[22:25]
	v_mfma_f32_16x16x32_bf16 v[18:21], v[168:171], v[210:213], v[18:21]
	v_mfma_f32_16x16x32_bf16 v[6:9], v[146:149], v[236:239], v[6:9]
	v_mfma_f32_16x16x32_bf16 v[2:5], v[168:171], v[236:239], v[2:5]
	v_mfma_f32_16x16x32_bf16 v[54:57], v[150:153], v[180:183], v[54:57]
	v_mfma_f32_16x16x32_bf16 v[50:53], v[172:175], v[180:183], v[50:53]
	v_mfma_f32_16x16x32_bf16 v[38:41], v[150:153], v[206:209], v[38:41]
	v_mfma_f32_16x16x32_bf16 v[34:37], v[172:175], v[206:209], v[34:37]
	v_mfma_f32_16x16x32_bf16 v[22:25], v[150:153], v[232:235], v[22:25]
	v_mfma_f32_16x16x32_bf16 v[18:21], v[172:175], v[232:235], v[18:21]
	v_mfma_f32_16x16x32_bf16 v[6:9], v[150:153], v[240:243], v[6:9]
	v_mfma_f32_16x16x32_bf16 v[2:5], v[172:175], v[240:243], v[2:5]
	s_setprio 0
	s_barrier
	s_add_i32 s52, 0, 0x18000
	s_add_i32 s53, 0, 0x1c000
	v_add_u32_e32 v142, s52, v186
	v_add_u32_e32 v172, s53, v186
	ds_read_b128 v[130:133], v142
	ds_read_b128 v[134:137], v142 offset:1024
	ds_read_b128 v[138:141], v142 offset:2048
	ds_read_b128 v[142:145], v142 offset:3072
	ds_read_b128 v[146:149], v172
	ds_read_b128 v[150:153], v172 offset:1024
	ds_read_b128 v[168:171], v172 offset:2048
	ds_read_b128 v[172:175], v172 offset:3072
	s_add_u32 s30, s30, 0x40000
	s_addc_u32 s31, s31, 0
	s_mov_b32 m0, s41
	ds_read_b128 v[176:179], v200 offset:32768
	ds_read_b128 v[180:183], v200 offset:33792
	ds_read_b128 v[202:205], v200 offset:34816
	ds_read_b128 v[206:209], v200 offset:35840
	ds_read_b128 v[210:213], v200 offset:36864
	ds_read_b128 v[232:235], v200 offset:37888
	ds_read_b128 v[236:239], v200 offset:38912
	ds_read_b128 v[240:243], v200 offset:39936
	global_load_lds_dwordx4 v154, s[30:31]
	s_mov_b32 m0, s42
	s_nop 0
	global_load_lds_dwordx4 v158, s[30:31]
	s_waitcnt vmcnt(8)
	s_waitcnt lgkmcnt(0)
	s_barrier
	s_setprio 1
	v_mfma_f32_16x16x32_bf16 v[126:129], v[130:133], v[176:179], v[126:129]
	v_mfma_f32_16x16x32_bf16 v[122:125], v[138:141], v[176:179], v[122:125]
	v_mfma_f32_16x16x32_bf16 v[110:113], v[130:133], v[202:205], v[110:113]
	v_mfma_f32_16x16x32_bf16 v[106:109], v[138:141], v[202:205], v[106:109]
	v_mfma_f32_16x16x32_bf16 v[94:97], v[130:133], v[210:213], v[94:97]
	v_mfma_f32_16x16x32_bf16 v[90:93], v[138:141], v[210:213], v[90:93]
	v_mfma_f32_16x16x32_bf16 v[78:81], v[130:133], v[236:239], v[78:81]
	v_mfma_f32_16x16x32_bf16 v[74:77], v[138:141], v[236:239], v[74:77]
	v_mfma_f32_16x16x32_bf16 v[126:129], v[134:137], v[180:183], v[126:129]
	v_mfma_f32_16x16x32_bf16 v[122:125], v[142:145], v[180:183], v[122:125]
	v_mfma_f32_16x16x32_bf16 v[110:113], v[134:137], v[206:209], v[110:113]
	v_mfma_f32_16x16x32_bf16 v[106:109], v[142:145], v[206:209], v[106:109]
	v_mfma_f32_16x16x32_bf16 v[94:97], v[134:137], v[232:235], v[94:97]
	v_mfma_f32_16x16x32_bf16 v[90:93], v[142:145], v[232:235], v[90:93]
	v_mfma_f32_16x16x32_bf16 v[78:81], v[134:137], v[240:243], v[78:81]
	v_mfma_f32_16x16x32_bf16 v[74:77], v[142:145], v[240:243], v[74:77]
	s_setprio 0
	s_setprio 1
	v_mfma_f32_16x16x32_bf16 v[118:121], v[146:149], v[176:179], v[118:121]
	v_mfma_f32_16x16x32_bf16 v[114:117], v[168:171], v[176:179], v[114:117]
	v_mfma_f32_16x16x32_bf16 v[102:105], v[146:149], v[202:205], v[102:105]
	v_mfma_f32_16x16x32_bf16 v[98:101], v[168:171], v[202:205], v[98:101]
	v_mfma_f32_16x16x32_bf16 v[86:89], v[146:149], v[210:213], v[86:89]
	v_mfma_f32_16x16x32_bf16 v[82:85], v[168:171], v[210:213], v[82:85]
	v_mfma_f32_16x16x32_bf16 v[70:73], v[146:149], v[236:239], v[70:73]
	v_mfma_f32_16x16x32_bf16 v[66:69], v[168:171], v[236:239], v[66:69]
	v_mfma_f32_16x16x32_bf16 v[118:121], v[150:153], v[180:183], v[118:121]
	v_mfma_f32_16x16x32_bf16 v[114:117], v[172:175], v[180:183], v[114:117]
	v_mfma_f32_16x16x32_bf16 v[102:105], v[150:153], v[206:209], v[102:105]
	v_mfma_f32_16x16x32_bf16 v[98:101], v[172:175], v[206:209], v[98:101]
	v_mfma_f32_16x16x32_bf16 v[86:89], v[150:153], v[232:235], v[86:89]
	v_mfma_f32_16x16x32_bf16 v[82:85], v[172:175], v[232:235], v[82:85]
	v_mfma_f32_16x16x32_bf16 v[70:73], v[150:153], v[240:243], v[70:73]
	v_mfma_f32_16x16x32_bf16 v[66:69], v[172:175], v[240:243], v[66:69]
	s_setprio 0
	s_barrier
; #define PG8_STAGE(bufoff, gbase, voff) do { _Pragma("unroll") for (int _i = 0; _i < 2; ++_i) \
;         __builtin_amdgcn_global_load_lds((const unsigned*)((const char*)(gbase) + (voff)[_i]), (PG8_LAS unsigned*)(lds + (bufoff) + ldsw + _i * 8192), 16, 0, 0); } while (0)
; #define PG8_LDA(dst, b, h) do { _Pragma("unroll") for (int m = 0; m < 4; ++m) _Pragma("unroll") for (int k = 0; k < 2; ++k) dst[m][k] = *(const PG8_LAS bf16x8*)(lds + PG8_SA(b, h) + aoff + m * 2048 + k * 1024); } while (0)
; #define PG8_MMA(ai, bj, At, Bt) do { __builtin_amdgcn_s_setprio(1); _Pragma("unroll") for (int m = 0; m < 4; ++m) _Pragma("unroll") for (int n = 0; n < 2; ++n) _Pragma("unroll") for (int k = 0; k < 2; ++k) \
;         acc[ai][bj][m][n] = __builtin_amdgcn_mfma_f32_16x16x32_bf16(Bt[n][k], At[m][k], acc[ai][bj][m][n], 0, 0, 0); __builtin_amdgcn_s_setprio(0); } while (0)
; #define PG8_WAIT_V(n) asm volatile("s_waitcnt vmcnt(" #n ")" ::: "memory")
; #define PG8_WAIT_L(n) asm volatile("s_waitcnt lgkmcnt(" #n ")" ::: "memory")
; #define PG8_BAR __builtin_amdgcn_s_barrier()
; #define PG8_SCHED __builtin_amdgcn_sched_barrier(0)
; template <class Epi, class Sched, bool ALIGN_EPI = false, bool SP2 = false>
; __device__ __forceinline__ void gemm_phase(PG8_LAS unsigned char* lds, const Gemm g, const Sched& S, const Epi& E) {
;     ...
;             PG8_LDA(At, 1, 1); PG8_STAGE(PG8_SB(1, 0), b3, voffB); PG8_STAGE(PG8_SB(1, 1), b3 + hstepB, voffB); PG8_STAGE(PG8_SA(1, 0), a3, voffA);
;             PG8_WAIT_V(8); PG8_WAIT_L(0); PG8_BAR; PG8_MMA(1, 0, At, B0); PG8_MMA(1, 1, At, B1); PG8_BAR; PG8_SCHED;
	s_add_i32 s30, s52, s38
	s_mov_b32 m0, s30
	ds_read_b128 v[176:179], v200 offset:49152
	ds_read_b128 v[180:183], v200 offset:50176
	ds_read_b128 v[202:205], v200 offset:51200
	ds_read_b128 v[206:209], v200 offset:52224
	ds_read_b128 v[210:213], v200 offset:53248
	ds_read_b128 v[232:235], v200 offset:54272
	ds_read_b128 v[236:239], v200 offset:55296
	ds_read_b128 v[240:243], v200 offset:56320
	global_load_lds_dwordx4 v156, s[60:61]
	s_add_i32 m0, s30, 0x2000
	s_add_u32 s28, s28, 0x40080
	s_addc_u32 s29, s29, 0
	s_add_i32 s30, s53, s38
	global_load_lds_dwordx4 v160, s[60:61]
	s_mov_b32 m0, s30
	s_nop 0
	global_load_lds_dwordx4 v156, s[28:29]
	s_add_i32 m0, s30, 0x2000
	s_nop 0
	global_load_lds_dwordx4 v160, s[28:29]
	s_mov_b32 m0, s44
	s_nop 0
	global_load_lds_dwordx4 v154, s[62:63]
	s_mov_b32 m0, s45
	s_nop 0
	global_load_lds_dwordx4 v158, s[62:63]
	s_waitcnt vmcnt(8)
	s_waitcnt lgkmcnt(0)
	s_barrier
	s_setprio 1
	v_mfma_f32_16x16x32_bf16 v[62:65], v[130:133], v[176:179], v[62:65]
	v_mfma_f32_16x16x32_bf16 v[58:61], v[138:141], v[176:179], v[58:61]
	v_mfma_f32_16x16x32_bf16 v[46:49], v[130:133], v[202:205], v[46:49]
	v_mfma_f32_16x16x32_bf16 v[42:45], v[138:141], v[202:205], v[42:45]
	v_mfma_f32_16x16x32_bf16 v[30:33], v[130:133], v[210:213], v[30:33]
	v_mfma_f32_16x16x32_bf16 v[26:29], v[138:141], v[210:213], v[26:29]
	v_mfma_f32_16x16x32_bf16 v[14:17], v[130:133], v[236:239], v[14:17]
	v_mfma_f32_16x16x32_bf16 v[10:13], v[138:141], v[236:239], v[10:13]
	v_mfma_f32_16x16x32_bf16 v[62:65], v[134:137], v[180:183], v[62:65]
	v_mfma_f32_16x16x32_bf16 v[58:61], v[142:145], v[180:183], v[58:61]
	v_mfma_f32_16x16x32_bf16 v[46:49], v[134:137], v[206:209], v[46:49]
	v_mfma_f32_16x16x32_bf16 v[42:45], v[142:145], v[206:209], v[42:45]
	v_mfma_f32_16x16x32_bf16 v[30:33], v[134:137], v[232:235], v[30:33]
	v_mfma_f32_16x16x32_bf16 v[26:29], v[142:145], v[232:235], v[26:29]
	v_mfma_f32_16x16x32_bf16 v[14:17], v[134:137], v[240:243], v[14:17]
	v_mfma_f32_16x16x32_bf16 v[10:13], v[142:145], v[240:243], v[10:13]
	s_setprio 0
	s_setprio 1
	v_mfma_f32_16x16x32_bf16 v[54:57], v[146:149], v[176:179], v[54:57]
	v_mfma_f32_16x16x32_bf16 v[50:53], v[168:171], v[176:179], v[50:53]
	v_mfma_f32_16x16x32_bf16 v[38:41], v[146:149], v[202:205], v[38:41]
	v_mfma_f32_16x16x32_bf16 v[34:37], v[168:171], v[202:205], v[34:37]
	v_mfma_f32_16x16x32_bf16 v[22:25], v[146:149], v[210:213], v[22:25]
	v_mfma_f32_16x16x32_bf16 v[18:21], v[168:171], v[210:213], v[18:21]
	v_mfma_f32_16x16x32_bf16 v[6:9], v[146:149], v[236:239], v[6:9]
	v_mfma_f32_16x16x32_bf16 v[2:5], v[168:171], v[236:239], v[2:5]
	v_mfma_f32_16x16x32_bf16 v[54:57], v[150:153], v[180:183], v[54:57]
	v_mfma_f32_16x16x32_bf16 v[50:53], v[172:175], v[180:183], v[50:53]
	v_mfma_f32_16x16x32_bf16 v[38:41], v[150:153], v[206:209], v[38:41]
	v_mfma_f32_16x16x32_bf16 v[34:37], v[172:175], v[206:209], v[34:37]
	v_mfma_f32_16x16x32_bf16 v[22:25], v[150:153], v[232:235], v[22:25]
	v_mfma_f32_16x16x32_bf16 v[18:21], v[172:175], v[232:235], v[18:21]
	v_mfma_f32_16x16x32_bf16 v[6:9], v[150:153], v[240:243], v[6:9]
	v_mfma_f32_16x16x32_bf16 v[2:5], v[172:175], v[240:243], v[2:5]
	s_setprio 0
	s_barrier
	s_add_i32 s51, s51, 2
	s_add_u32 s26, s26, 0x100
	s_addc_u32 s27, s27, 0
	s_add_u32 s49, s49, 0x100
	s_addc_u32 s50, s50, 0
	s_cmp_gt_u32 s51, 13
	s_cbranch_scc0 .LBB0_1270
	s_and_b64 vcc, exec, s[12:13]
	s_cbranch_vccz .LBB0_1273
	s_barrier

; #define PG8_STAGE(bufoff, gbase, voff) do { _Pragma("unroll") for (int _i = 0; _i < 2; ++_i) \
;         __builtin_amdgcn_global_load_lds((const unsigned*)((const char*)(gbase) + (voff)[_i]), (PG8_LAS unsigned*)(lds + (bufoff) + ldsw + _i * 8192), 16, 0, 0); } while (0)
; #define PG8_LDA(dst, b, h) do { _Pragma("unroll") for (int m = 0; m < 4; ++m) _Pragma("unroll") for (int k = 0; k < 2; ++k) dst[m][k] = *(const PG8_LAS bf16x8*)(lds + PG8_SA(b, h) + aoff + m * 2048 + k * 1024); } while (0)
; #define PG8_LDB(dst, b, h) do { _Pragma("unroll") for (int n = 0; n < 2; ++n) _Pragma("unroll") for (int k = 0; k < 2; ++k) dst[n][k] = *(const PG8_LAS bf16x8*)(lds + PG8_SB(b, h) + boff + n * 2048 + k * 1024); } while (0)
; #define PG8_MMA(ai, bj, At, Bt) do { __builtin_amdgcn_s_setprio(1); _Pragma("unroll") for (int m = 0; m < 4; ++m) _Pragma("unroll") for (int n = 0; n < 2; ++n) _Pragma("unroll") for (int k = 0; k < 2; ++k) \
;         acc[ai][bj][m][n] = __builtin_amdgcn_mfma_f32_16x16x32_bf16(Bt[n][k], At[m][k], acc[ai][bj][m][n], 0, 0, 0); __builtin_amdgcn_s_setprio(0); } while (0)
; #define PG8_WAIT_V(n) asm volatile("s_waitcnt vmcnt(" #n ")" ::: "memory")
; #define PG8_WAIT_L(n) asm volatile("s_waitcnt lgkmcnt(" #n ")" ::: "memory")
; #define PG8_BAR __builtin_amdgcn_s_barrier()
; #define PG8_SCHED __builtin_amdgcn_sched_barrier(0)
; template <class Epi, class Sched, bool ALIGN_EPI = false, bool SP2 = false>
; __device__ __forceinline__ void gemm_phase(PG8_LAS unsigned char* lds, const Gemm g, const Sched& S, const Epi& E) {
;     ...
;             PG8_LDB(B0, 0, 0); PG8_LDB(B1, 0, 1); PG8_SCHED; PG8_LDA(At, 0, 0); PG8_STAGE(PG8_SA(1, 1), a1 + hstepA, voffA);
;             PG8_WAIT_V(8); PG8_WAIT_L(0); PG8_BAR; PG8_MMA(0, 0, At, B0); PG8_MMA(0, 1, At, B1); PG8_BAR; PG8_SCHED;
;             PG8_LDA(At, 0, 1); PG8_STAGE(PG8_SB(0, 0), b2, voffB); PG8_STAGE(PG8_SB(0, 1), b2 + hstepB, voffB); PG8_STAGE(PG8_SA(0, 0), a2, voffA);
.LBB0_1354:
	s_add_u32 s24, s22, 0xfffc0080
	s_addc_u32 s25, s23, -1
	s_add_i32 s49, 0, 0x10000
	s_cmp_eq_u32 s48, 12
	s_cselect_b32 s27, s15, s25
	s_cselect_b32 s26, s21, s24
	v_add_u32_e32 v142, s49, v145
	s_cselect_b32 s25, s13, s47
	s_cselect_b32 s24, s45, s46
	s_add_i32 s52, 0, 0x14000
	ds_read_b128 v[150:153], v142
	ds_read_b128 v[154:157], v142 offset:1024
	ds_read_b128 v[158:161], v142 offset:2048
	ds_read_b128 v[162:165], v142 offset:3072
	v_add_u32_e32 v142, s52, v145
	ds_read_b128 v[166:169], v142
	ds_read_b128 v[170:173], v142 offset:1024
	ds_read_b128 v[174:177], v142 offset:2048
	ds_read_b128 v[178:181], v142 offset:3072
	s_add_i32 m0, s36, 0xc000
	ds_read_b128 v[182:185], v148
	ds_read_b128 v[202:205], v148 offset:1024
	ds_read_b128 v[206:209], v148 offset:2048
	ds_read_b128 v[210:213], v148 offset:3072
	ds_read_b128 v[232:235], v148 offset:4096
	ds_read_b128 v[236:239], v148 offset:5120
	ds_read_b128 v[240:243], v148 offset:6144
	ds_read_b128 v[244:247], v148 offset:7168
	global_load_lds_dwordx4 v138, s[22:23]
	s_add_i32 m0, s36, 0xe000
	s_nop 0
	global_load_lds_dwordx4 v140, s[22:23]
	s_waitcnt vmcnt(8)
	s_waitcnt lgkmcnt(0)
	s_barrier
	s_setprio 1
	v_mfma_f32_16x16x32_bf16 v[126:129], v[150:153], v[182:185], v[126:129]
	v_mfma_f32_16x16x32_bf16 v[122:125], v[158:161], v[182:185], v[122:125]
	v_mfma_f32_16x16x32_bf16 v[114:117], v[150:153], v[206:209], v[114:117]
	v_mfma_f32_16x16x32_bf16 v[106:109], v[158:161], v[206:209], v[106:109]
	v_mfma_f32_16x16x32_bf16 v[98:101], v[150:153], v[232:235], v[98:101]
	v_mfma_f32_16x16x32_bf16 v[90:93], v[158:161], v[232:235], v[90:93]
	v_mfma_f32_16x16x32_bf16 v[78:81], v[150:153], v[240:243], v[78:81]
	v_mfma_f32_16x16x32_bf16 v[74:77], v[158:161], v[240:243], v[74:77]
	v_mfma_f32_16x16x32_bf16 v[126:129], v[154:157], v[202:205], v[126:129]
	v_mfma_f32_16x16x32_bf16 v[122:125], v[162:165], v[202:205], v[122:125]
	v_mfma_f32_16x16x32_bf16 v[114:117], v[154:157], v[210:213], v[114:117]
	v_mfma_f32_16x16x32_bf16 v[106:109], v[162:165], v[210:213], v[106:109]
	v_mfma_f32_16x16x32_bf16 v[98:101], v[154:157], v[236:239], v[98:101]
	v_mfma_f32_16x16x32_bf16 v[90:93], v[162:165], v[236:239], v[90:93]
	v_mfma_f32_16x16x32_bf16 v[78:81], v[154:157], v[244:247], v[78:81]
	v_mfma_f32_16x16x32_bf16 v[74:77], v[162:165], v[244:247], v[74:77]
	s_setprio 0
	s_setprio 1
	v_mfma_f32_16x16x32_bf16 v[118:121], v[166:169], v[182:185], v[118:121]
	v_mfma_f32_16x16x32_bf16 v[110:113], v[174:177], v[182:185], v[110:113]
	v_mfma_f32_16x16x32_bf16 v[102:105], v[166:169], v[206:209], v[102:105]
	v_mfma_f32_16x16x32_bf16 v[94:97], v[174:177], v[206:209], v[94:97]
	v_mfma_f32_16x16x32_bf16 v[86:89], v[166:169], v[232:235], v[86:89]
	v_mfma_f32_16x16x32_bf16 v[82:85], v[174:177], v[232:235], v[82:85]
	v_mfma_f32_16x16x32_bf16 v[70:73], v[166:169], v[240:243], v[70:73]
	v_mfma_f32_16x16x32_bf16 v[66:69], v[174:177], v[240:243], v[66:69]
	v_mfma_f32_16x16x32_bf16 v[118:121], v[170:173], v[202:205], v[118:121]
	v_mfma_f32_16x16x32_bf16 v[110:113], v[178:181], v[202:205], v[110:113]
	v_mfma_f32_16x16x32_bf16 v[102:105], v[170:173], v[210:213], v[102:105]
	v_mfma_f32_16x16x32_bf16 v[94:97], v[178:181], v[210:213], v[94:97]
	v_mfma_f32_16x16x32_bf16 v[86:89], v[170:173], v[236:239], v[86:89]
	v_mfma_f32_16x16x32_bf16 v[82:85], v[178:181], v[236:239], v[82:85]
	v_mfma_f32_16x16x32_bf16 v[70:73], v[170:173], v[244:247], v[70:73]
	v_mfma_f32_16x16x32_bf16 v[66:69], v[178:181], v[244:247], v[66:69]
	s_setprio 0
	s_barrier
	s_add_i32 s49, s49, s34
	s_mov_b32 m0, s49
	ds_read_b128 v[182:185], v148 offset:16384
	ds_read_b128 v[202:205], v148 offset:17408
	ds_read_b128 v[206:209], v148 offset:18432
	ds_read_b128 v[210:213], v148 offset:19456
	ds_read_b128 v[232:235], v148 offset:20480
	ds_read_b128 v[236:239], v148 offset:21504
	ds_read_b128 v[240:243], v148 offset:22528
	ds_read_b128 v[244:247], v148 offset:23552
	s_add_u32 s60, s24, 0x80
	s_addc_u32 s61, s25, 0
	s_add_u32 s62, s26, 0x80
	s_addc_u32 s63, s27, 0
	global_load_lds_dwordx4 v134, s[24:25]
	s_add_i32 m0, s49, 0x2000
	s_add_u32 s50, s24, 0x40000
	s_addc_u32 s51, s25, 0
	s_add_i32 s49, s52, s34
	global_load_lds_dwordx4 v130, s[24:25]
	s_mov_b32 m0, s49
	s_nop 0
	global_load_lds_dwordx4 v134, s[50:51]
	s_add_i32 m0, s49, 0x2000
	s_nop 0
	global_load_lds_dwordx4 v130, s[50:51]
	s_mov_b32 m0, s36
	s_nop 0
	global_load_lds_dwordx4 v136, s[26:27]
	s_mov_b32 m0, s37
	s_nop 0
	global_load_lds_dwordx4 v132, s[26:27]
	s_waitcnt vmcnt(8)
	s_waitcnt lgkmcnt(0)
	s_barrier
; #define PG8_STAGE(bufoff, gbase, voff) do { _Pragma("unroll") for (int _i = 0; _i < 2; ++_i) \
;         __builtin_amdgcn_global_load_lds((const unsigned*)((const char*)(gbase) + (voff)[_i]), (PG8_LAS unsigned*)(lds + (bufoff) + ldsw + _i * 8192), 16, 0, 0); } while (0)
; #define PG8_LDA(dst, b, h) do { _Pragma("unroll") for (int m = 0; m < 4; ++m) _Pragma("unroll") for (int k = 0; k < 2; ++k) dst[m][k] = *(const PG8_LAS bf16x8*)(lds + PG8_SA(b, h) + aoff + m * 2048 + k * 1024); } while (0)
; #define PG8_LDB(dst, b, h) do { _Pragma("unroll") for (int n = 0; n < 2; ++n) _Pragma("unroll") for (int k = 0; k < 2; ++k) dst[n][k] = *(const PG8_LAS bf16x8*)(lds + PG8_SB(b, h) + boff + n * 2048 + k * 1024); } while (0)
; #define PG8_MMA(ai, bj, At, Bt) do { __builtin_amdgcn_s_setprio(1); _Pragma("unroll") for (int m = 0; m < 4; ++m) _Pragma("unroll") for (int n = 0; n < 2; ++n) _Pragma("unroll") for (int k = 0; k < 2; ++k) \
;         acc[ai][bj][m][n] = __builtin_amdgcn_mfma_f32_16x16x32_bf16(Bt[n][k], At[m][k], acc[ai][bj][m][n], 0, 0, 0); __builtin_amdgcn_s_setprio(0); } while (0)
; #define PG8_WAIT_V(n) asm volatile("s_waitcnt vmcnt(" #n ")" ::: "memory")
; #define PG8_WAIT_L(n) asm volatile("s_waitcnt lgkmcnt(" #n ")" ::: "memory")
; #define PG8_BAR __builtin_amdgcn_s_barrier()
; #define PG8_SCHED __builtin_amdgcn_sched_barrier(0)
; template <class Epi, class Sched, bool ALIGN_EPI = false, bool SP2 = false>
; __device__ __forceinline__ void gemm_phase(PG8_LAS unsigned char* lds, const Gemm g, const Sched& S, const Epi& E) {
;     ...
;             PG8_WAIT_V(8); PG8_WAIT_L(0); PG8_BAR; PG8_MMA(1, 0, At, B0); PG8_MMA(1, 1, At, B1); PG8_BAR; PG8_SCHED;
;             PG8_LDB(B0, 1, 0); PG8_LDB(B1, 1, 1); PG8_SCHED; PG8_LDA(At, 1, 0); PG8_STAGE(PG8_SA(0, 1), a2 + hstepA, voffA);
;             PG8_WAIT_V(8); PG8_WAIT_L(0); PG8_BAR; PG8_MMA(0, 0, At, B0); PG8_MMA(0, 1, At, B1); PG8_BAR; PG8_SCHED;
	s_setprio 1
	v_mfma_f32_16x16x32_bf16 v[62:65], v[150:153], v[182:185], v[62:65]
	v_mfma_f32_16x16x32_bf16 v[58:61], v[158:161], v[182:185], v[58:61]
	v_mfma_f32_16x16x32_bf16 v[46:49], v[150:153], v[206:209], v[46:49]
	v_mfma_f32_16x16x32_bf16 v[42:45], v[158:161], v[206:209], v[42:45]
	v_mfma_f32_16x16x32_bf16 v[30:33], v[150:153], v[232:235], v[30:33]
	v_mfma_f32_16x16x32_bf16 v[26:29], v[158:161], v[232:235], v[26:29]
	v_mfma_f32_16x16x32_bf16 v[14:17], v[150:153], v[240:243], v[14:17]
	v_mfma_f32_16x16x32_bf16 v[10:13], v[158:161], v[240:243], v[10:13]
	v_mfma_f32_16x16x32_bf16 v[62:65], v[154:157], v[202:205], v[62:65]
	v_mfma_f32_16x16x32_bf16 v[58:61], v[162:165], v[202:205], v[58:61]
	v_mfma_f32_16x16x32_bf16 v[46:49], v[154:157], v[210:213], v[46:49]
	v_mfma_f32_16x16x32_bf16 v[42:45], v[162:165], v[210:213], v[42:45]
	v_mfma_f32_16x16x32_bf16 v[30:33], v[154:157], v[236:239], v[30:33]
	v_mfma_f32_16x16x32_bf16 v[26:29], v[162:165], v[236:239], v[26:29]
	v_mfma_f32_16x16x32_bf16 v[14:17], v[154:157], v[244:247], v[14:17]
	v_mfma_f32_16x16x32_bf16 v[10:13], v[162:165], v[244:247], v[10:13]
	s_setprio 0
	s_setprio 1
	v_mfma_f32_16x16x32_bf16 v[54:57], v[166:169], v[182:185], v[54:57]
	v_mfma_f32_16x16x32_bf16 v[50:53], v[174:177], v[182:185], v[50:53]
	v_mfma_f32_16x16x32_bf16 v[38:41], v[166:169], v[206:209], v[38:41]
	v_mfma_f32_16x16x32_bf16 v[34:37], v[174:177], v[206:209], v[34:37]
	v_mfma_f32_16x16x32_bf16 v[22:25], v[166:169], v[232:235], v[22:25]
	v_mfma_f32_16x16x32_bf16 v[18:21], v[174:177], v[232:235], v[18:21]
	v_mfma_f32_16x16x32_bf16 v[6:9], v[166:169], v[240:243], v[6:9]
	v_mfma_f32_16x16x32_bf16 v[2:5], v[174:177], v[240:243], v[2:5]
	v_mfma_f32_16x16x32_bf16 v[54:57], v[170:173], v[202:205], v[54:57]
	v_mfma_f32_16x16x32_bf16 v[50:53], v[178:181], v[202:205], v[50:53]
	v_mfma_f32_16x16x32_bf16 v[38:41], v[170:173], v[210:213], v[38:41]
	v_mfma_f32_16x16x32_bf16 v[34:37], v[178:181], v[210:213], v[34:37]
	v_mfma_f32_16x16x32_bf16 v[22:25], v[170:173], v[236:239], v[22:25]
	v_mfma_f32_16x16x32_bf16 v[18:21], v[178:181], v[236:239], v[18:21]
	v_mfma_f32_16x16x32_bf16 v[6:9], v[170:173], v[244:247], v[6:9]
	v_mfma_f32_16x16x32_bf16 v[2:5], v[178:181], v[244:247], v[2:5]
	s_setprio 0
	s_barrier
	s_add_i32 s49, 0, 0x18000
	v_add_u32_e32 v144, s49, v145
	s_add_i32 s50, 0, 0x1c000
	ds_read_b128 v[150:153], v144
	ds_read_b128 v[154:157], v144 offset:1024
	ds_read_b128 v[158:161], v144 offset:2048
	ds_read_b128 v[162:165], v144 offset:3072
	v_add_u32_e32 v144, s50, v145
	ds_read_b128 v[166:169], v144
	ds_read_b128 v[170:173], v144 offset:1024
	ds_read_b128 v[174:177], v144 offset:2048
	ds_read_b128 v[178:181], v144 offset:3072
	s_add_u32 s26, s26, 0x40000
	s_addc_u32 s27, s27, 0
	s_mov_b32 m0, s38
	ds_read_b128 v[182:185], v148 offset:32768
	ds_read_b128 v[202:205], v148 offset:33792
	ds_read_b128 v[206:209], v148 offset:34816
	ds_read_b128 v[210:213], v148 offset:35840
	ds_read_b128 v[232:235], v148 offset:36864
	ds_read_b128 v[236:239], v148 offset:37888
	ds_read_b128 v[240:243], v148 offset:38912
	ds_read_b128 v[244:247], v148 offset:39936
	global_load_lds_dwordx4 v136, s[26:27]
	s_mov_b32 m0, s39
	s_nop 0
	global_load_lds_dwordx4 v132, s[26:27]
	s_waitcnt vmcnt(8)
	s_waitcnt lgkmcnt(0)
	s_barrier
	s_setprio 1
	v_mfma_f32_16x16x32_bf16 v[126:129], v[150:153], v[182:185], v[126:129]
	v_mfma_f32_16x16x32_bf16 v[122:125], v[158:161], v[182:185], v[122:125]
	v_mfma_f32_16x16x32_bf16 v[114:117], v[150:153], v[206:209], v[114:117]
	v_mfma_f32_16x16x32_bf16 v[106:109], v[158:161], v[206:209], v[106:109]
	v_mfma_f32_16x16x32_bf16 v[98:101], v[150:153], v[232:235], v[98:101]
	v_mfma_f32_16x16x32_bf16 v[90:93], v[158:161], v[232:235], v[90:93]
	v_mfma_f32_16x16x32_bf16 v[78:81], v[150:153], v[240:243], v[78:81]
	v_mfma_f32_16x16x32_bf16 v[74:77], v[158:161], v[240:243], v[74:77]
	v_mfma_f32_16x16x32_bf16 v[126:129], v[154:157], v[202:205], v[126:129]
	v_mfma_f32_16x16x32_bf16 v[122:125], v[162:165], v[202:205], v[122:125]
	v_mfma_f32_16x16x32_bf16 v[114:117], v[154:157], v[210:213], v[114:117]
	v_mfma_f32_16x16x32_bf16 v[106:109], v[162:165], v[210:213], v[106:109]
	v_mfma_f32_16x16x32_bf16 v[98:101], v[154:157], v[236:239], v[98:101]
	v_mfma_f32_16x16x32_bf16 v[90:93], v[162:165], v[236:239], v[90:93]
	v_mfma_f32_16x16x32_bf16 v[78:81], v[154:157], v[244:247], v[78:81]
	v_mfma_f32_16x16x32_bf16 v[74:77], v[162:165], v[244:247], v[74:77]
	s_setprio 0
	s_setprio 1
	v_mfma_f32_16x16x32_bf16 v[118:121], v[166:169], v[182:185], v[118:121]
	v_mfma_f32_16x16x32_bf16 v[110:113], v[174:177], v[182:185], v[110:113]
	v_mfma_f32_16x16x32_bf16 v[102:105], v[166:169], v[206:209], v[102:105]
	v_mfma_f32_16x16x32_bf16 v[94:97], v[174:177], v[206:209], v[94:97]
	v_mfma_f32_16x16x32_bf16 v[86:89], v[166:169], v[232:235], v[86:89]
	v_mfma_f32_16x16x32_bf16 v[82:85], v[174:177], v[232:235], v[82:85]
	v_mfma_f32_16x16x32_bf16 v[70:73], v[166:169], v[240:243], v[70:73]
	v_mfma_f32_16x16x32_bf16 v[66:69], v[174:177], v[240:243], v[66:69]
	v_mfma_f32_16x16x32_bf16 v[118:121], v[170:173], v[202:205], v[118:121]
	v_mfma_f32_16x16x32_bf16 v[110:113], v[178:181], v[202:205], v[110:113]
	v_mfma_f32_16x16x32_bf16 v[102:105], v[170:173], v[210:213], v[102:105]
	v_mfma_f32_16x16x32_bf16 v[94:97], v[178:181], v[210:213], v[94:97]
	v_mfma_f32_16x16x32_bf16 v[86:89], v[170:173], v[236:239], v[86:89]
	v_mfma_f32_16x16x32_bf16 v[82:85], v[178:181], v[236:239], v[82:85]
	v_mfma_f32_16x16x32_bf16 v[70:73], v[170:173], v[244:247], v[70:73]
	v_mfma_f32_16x16x32_bf16 v[66:69], v[178:181], v[244:247], v[66:69]
	s_setprio 0
	s_barrier
; #define PG8_STAGE(bufoff, gbase, voff) do { _Pragma("unroll") for (int _i = 0; _i < 2; ++_i) \
;         __builtin_amdgcn_global_load_lds((const unsigned*)((const char*)(gbase) + (voff)[_i]), (PG8_LAS unsigned*)(lds + (bufoff) + ldsw + _i * 8192), 16, 0, 0); } while (0)
; #define PG8_LDA(dst, b, h) do { _Pragma("unroll") for (int m = 0; m < 4; ++m) _Pragma("unroll") for (int k = 0; k < 2; ++k) dst[m][k] = *(const PG8_LAS bf16x8*)(lds + PG8_SA(b, h) + aoff + m * 2048 + k * 1024); } while (0)
; #define PG8_MMA(ai, bj, At, Bt) do { __builtin_amdgcn_s_setprio(1); _Pragma("unroll") for (int m = 0; m < 4; ++m) _Pragma("unroll") for (int n = 0; n < 2; ++n) _Pragma("unroll") for (int k = 0; k < 2; ++k) \
;         acc[ai][bj][m][n] = __builtin_amdgcn_mfma_f32_16x16x32_bf16(Bt[n][k], At[m][k], acc[ai][bj][m][n], 0, 0, 0); __builtin_amdgcn_s_setprio(0); } while (0)
; #define PG8_WAIT_V(n) asm volatile("s_waitcnt vmcnt(" #n ")" ::: "memory")
; #define PG8_WAIT_L(n) asm volatile("s_waitcnt lgkmcnt(" #n ")" ::: "memory")
; #define PG8_BAR __builtin_amdgcn_s_barrier()
; #define PG8_SCHED __builtin_amdgcn_sched_barrier(0)
; template <class Epi, class Sched, bool ALIGN_EPI = false, bool SP2 = false>
; __device__ __forceinline__ void gemm_phase(PG8_LAS unsigned char* lds, const Gemm g, const Sched& S, const Epi& E) {
;     ...
;             PG8_LDA(At, 1, 1); PG8_STAGE(PG8_SB(1, 0), b3, voffB); PG8_STAGE(PG8_SB(1, 1), b3 + hstepB, voffB); PG8_STAGE(PG8_SA(1, 0), a3, voffA);
;             PG8_WAIT_V(8); PG8_WAIT_L(0); PG8_BAR; PG8_MMA(1, 0, At, B0); PG8_MMA(1, 1, At, B1); PG8_BAR; PG8_SCHED;
	s_add_i32 s26, s49, s34
	s_mov_b32 m0, s26
	ds_read_b128 v[182:185], v148 offset:49152
	ds_read_b128 v[202:205], v148 offset:50176
	ds_read_b128 v[206:209], v148 offset:51200
	ds_read_b128 v[210:213], v148 offset:52224
	ds_read_b128 v[232:235], v148 offset:53248
	ds_read_b128 v[236:239], v148 offset:54272
	ds_read_b128 v[240:243], v148 offset:55296
	ds_read_b128 v[244:247], v148 offset:56320
	global_load_lds_dwordx4 v134, s[60:61]
	s_add_i32 m0, s26, 0x2000
	s_add_u32 s24, s24, 0x40080
	s_addc_u32 s25, s25, 0
	s_add_i32 s26, s50, s34
	global_load_lds_dwordx4 v130, s[60:61]
	s_mov_b32 m0, s26
	s_nop 0
	global_load_lds_dwordx4 v134, s[24:25]
	s_add_i32 m0, s26, 0x2000
	s_nop 0
	global_load_lds_dwordx4 v130, s[24:25]
	s_mov_b32 m0, s40
	s_nop 0
	global_load_lds_dwordx4 v136, s[62:63]
	s_mov_b32 m0, s41
	s_nop 0
	global_load_lds_dwordx4 v132, s[62:63]
	s_waitcnt vmcnt(8)
	s_waitcnt lgkmcnt(0)
	s_barrier
	s_setprio 1
	v_mfma_f32_16x16x32_bf16 v[62:65], v[150:153], v[182:185], v[62:65]
	v_mfma_f32_16x16x32_bf16 v[58:61], v[158:161], v[182:185], v[58:61]
	v_mfma_f32_16x16x32_bf16 v[46:49], v[150:153], v[206:209], v[46:49]
	v_mfma_f32_16x16x32_bf16 v[42:45], v[158:161], v[206:209], v[42:45]
	v_mfma_f32_16x16x32_bf16 v[30:33], v[150:153], v[232:235], v[30:33]
	v_mfma_f32_16x16x32_bf16 v[26:29], v[158:161], v[232:235], v[26:29]
	v_mfma_f32_16x16x32_bf16 v[14:17], v[150:153], v[240:243], v[14:17]
	v_mfma_f32_16x16x32_bf16 v[10:13], v[158:161], v[240:243], v[10:13]
	v_mfma_f32_16x16x32_bf16 v[62:65], v[154:157], v[202:205], v[62:65]
	v_mfma_f32_16x16x32_bf16 v[58:61], v[162:165], v[202:205], v[58:61]
	v_mfma_f32_16x16x32_bf16 v[46:49], v[154:157], v[210:213], v[46:49]
	v_mfma_f32_16x16x32_bf16 v[42:45], v[162:165], v[210:213], v[42:45]
	v_mfma_f32_16x16x32_bf16 v[30:33], v[154:157], v[236:239], v[30:33]
	v_mfma_f32_16x16x32_bf16 v[26:29], v[162:165], v[236:239], v[26:29]
	v_mfma_f32_16x16x32_bf16 v[14:17], v[154:157], v[244:247], v[14:17]
	v_mfma_f32_16x16x32_bf16 v[10:13], v[162:165], v[244:247], v[10:13]
	s_setprio 0
	s_setprio 1
	v_mfma_f32_16x16x32_bf16 v[54:57], v[166:169], v[182:185], v[54:57]
	v_mfma_f32_16x16x32_bf16 v[50:53], v[174:177], v[182:185], v[50:53]
	v_mfma_f32_16x16x32_bf16 v[38:41], v[166:169], v[206:209], v[38:41]
	v_mfma_f32_16x16x32_bf16 v[34:37], v[174:177], v[206:209], v[34:37]
	v_mfma_f32_16x16x32_bf16 v[22:25], v[166:169], v[232:235], v[22:25]
	v_mfma_f32_16x16x32_bf16 v[18:21], v[174:177], v[232:235], v[18:21]
	v_mfma_f32_16x16x32_bf16 v[6:9], v[166:169], v[240:243], v[6:9]
	v_mfma_f32_16x16x32_bf16 v[2:5], v[174:177], v[240:243], v[2:5]
	v_mfma_f32_16x16x32_bf16 v[54:57], v[170:173], v[202:205], v[54:57]
	v_mfma_f32_16x16x32_bf16 v[50:53], v[178:181], v[202:205], v[50:53]
	v_mfma_f32_16x16x32_bf16 v[38:41], v[170:173], v[210:213], v[38:41]
	v_mfma_f32_16x16x32_bf16 v[34:37], v[178:181], v[210:213], v[34:37]
	v_mfma_f32_16x16x32_bf16 v[22:25], v[170:173], v[236:239], v[22:25]
	v_mfma_f32_16x16x32_bf16 v[18:21], v[178:181], v[236:239], v[18:21]
	v_mfma_f32_16x16x32_bf16 v[6:9], v[170:173], v[244:247], v[6:9]
	v_mfma_f32_16x16x32_bf16 v[2:5], v[178:181], v[244:247], v[2:5]
	s_setprio 0
	s_barrier
	s_add_i32 s48, s48, 2
	s_add_u32 s22, s22, 0x100
	s_addc_u32 s23, s23, 0
	s_add_u32 s46, s46, 0x100
	s_addc_u32 s47, s47, 0
	s_cmp_gt_u32 s48, 13
	s_cbranch_scc0 .LBB0_1354
	s_and_b64 vcc, exec, s[10:11]
	s_cbranch_vccz .LBB0_1357
	s_barrier

; #define PG8_STAGE(bufoff, gbase, voff) do { _Pragma("unroll") for (int _i = 0; _i < 2; ++_i) \
;         __builtin_amdgcn_global_load_lds((const unsigned*)((const char*)(gbase) + (voff)[_i]), (PG8_LAS unsigned*)(lds + (bufoff) + ldsw + _i * 8192), 16, 0, 0); } while (0)
; #define PG8_LDA(dst, b, h) do { _Pragma("unroll") for (int m = 0; m < 4; ++m) _Pragma("unroll") for (int k = 0; k < 2; ++k) dst[m][k] = *(const PG8_LAS bf16x8*)(lds + PG8_SA(b, h) + aoff + m * 2048 + k * 1024); } while (0)
; #define PG8_LDB(dst, b, h) do { _Pragma("unroll") for (int n = 0; n < 2; ++n) _Pragma("unroll") for (int k = 0; k < 2; ++k) dst[n][k] = *(const PG8_LAS bf16x8*)(lds + PG8_SB(b, h) + boff + n * 2048 + k * 1024); } while (0)
; #define PG8_MMA(ai, bj, At, Bt) do { __builtin_amdgcn_s_setprio(1); _Pragma("unroll") for (int m = 0; m < 4; ++m) _Pragma("unroll") for (int n = 0; n < 2; ++n) _Pragma("unroll") for (int k = 0; k < 2; ++k) \
;         acc[ai][bj][m][n] = __builtin_amdgcn_mfma_f32_16x16x32_bf16(Bt[n][k], At[m][k], acc[ai][bj][m][n], 0, 0, 0); __builtin_amdgcn_s_setprio(0); } while (0)
; #define PG8_WAIT_V(n) asm volatile("s_waitcnt vmcnt(" #n ")" ::: "memory")
; #define PG8_WAIT_L(n) asm volatile("s_waitcnt lgkmcnt(" #n ")" ::: "memory")
; #define PG8_BAR __builtin_amdgcn_s_barrier()
; #define PG8_SCHED __builtin_amdgcn_sched_barrier(0)
; template <class Epi, class Sched, bool ALIGN_EPI = false, bool SP2 = false>
; __device__ __forceinline__ void gemm_phase(PG8_LAS unsigned char* lds, const Gemm g, const Sched& S, const Epi& E) {
;     ...
;             PG8_LDB(B0, 0, 0); PG8_LDB(B1, 0, 1); PG8_SCHED; PG8_LDA(At, 0, 0); PG8_STAGE(PG8_SA(1, 1), a1 + hstepA, voffA);
;             PG8_WAIT_V(8); PG8_WAIT_L(0); PG8_BAR; PG8_MMA(0, 0, At, B0); PG8_MMA(0, 1, At, B1); PG8_BAR; PG8_SCHED;
;             PG8_LDA(At, 0, 1); PG8_STAGE(PG8_SB(0, 0), b2, voffB); PG8_STAGE(PG8_SB(0, 1), b2 + hstepB, voffB); PG8_STAGE(PG8_SA(0, 0), a2, voffA);
;             PG8_WAIT_V(8); PG8_WAIT_L(0); PG8_BAR; PG8_MMA(1, 0, At, B0); PG8_MMA(1, 1, At, B1); PG8_BAR; PG8_SCHED;
.LBB0_1438:
	s_add_u32 s20, s18, 0x100
	s_addc_u32 s21, s19, 0
	s_add_i32 s50, 0, 0x10000
	s_cmp_eq_u32 s49, 40
	s_cselect_b32 s25, s9, s21
	s_cselect_b32 s24, s8, s20
	s_cselect_b32 s23, s17, s48
	s_cselect_b32 s22, s16, s47
	s_add_i32 s51, 0, 0x14000
	v_add_u32_e32 v142, s50, v186
	v_add_u32_e32 v172, s51, v186
	ds_read_b128 v[130:133], v142
	ds_read_b128 v[134:137], v142 offset:1024
	ds_read_b128 v[138:141], v142 offset:2048
	ds_read_b128 v[142:145], v142 offset:3072
	ds_read_b128 v[146:149], v172
	ds_read_b128 v[150:153], v172 offset:1024
	ds_read_b128 v[168:171], v172 offset:2048
	ds_read_b128 v[172:175], v172 offset:3072
	s_add_i32 m0, s31, 0xc000
	ds_read_b128 v[176:179], v200
	ds_read_b128 v[180:183], v200 offset:1024
	ds_read_b128 v[202:205], v200 offset:2048
	ds_read_b128 v[206:209], v200 offset:3072
	ds_read_b128 v[210:213], v200 offset:4096
	ds_read_b128 v[232:235], v200 offset:5120
	ds_read_b128 v[236:239], v200 offset:6144
	ds_read_b128 v[240:243], v200 offset:7168
	global_load_lds_dwordx4 v164, s[18:19]
	s_add_i32 m0, s31, 0xe000
	s_nop 0
	global_load_lds_dwordx4 v166, s[18:19]
	s_waitcnt vmcnt(8)
	s_waitcnt lgkmcnt(0)
	s_barrier
	s_setprio 1
	v_mfma_f32_16x16x32_bf16 v[126:129], v[130:133], v[176:179], v[126:129]
	v_mfma_f32_16x16x32_bf16 v[122:125], v[138:141], v[176:179], v[122:125]
	v_mfma_f32_16x16x32_bf16 v[110:113], v[130:133], v[202:205], v[110:113]
	v_mfma_f32_16x16x32_bf16 v[106:109], v[138:141], v[202:205], v[106:109]
	v_mfma_f32_16x16x32_bf16 v[94:97], v[130:133], v[210:213], v[94:97]
	v_mfma_f32_16x16x32_bf16 v[90:93], v[138:141], v[210:213], v[90:93]
	v_mfma_f32_16x16x32_bf16 v[78:81], v[130:133], v[236:239], v[78:81]
	v_mfma_f32_16x16x32_bf16 v[74:77], v[138:141], v[236:239], v[74:77]
	v_mfma_f32_16x16x32_bf16 v[126:129], v[134:137], v[180:183], v[126:129]
	v_mfma_f32_16x16x32_bf16 v[122:125], v[142:145], v[180:183], v[122:125]
	v_mfma_f32_16x16x32_bf16 v[110:113], v[134:137], v[206:209], v[110:113]
	v_mfma_f32_16x16x32_bf16 v[106:109], v[142:145], v[206:209], v[106:109]
	v_mfma_f32_16x16x32_bf16 v[94:97], v[134:137], v[232:235], v[94:97]
	v_mfma_f32_16x16x32_bf16 v[90:93], v[142:145], v[232:235], v[90:93]
	v_mfma_f32_16x16x32_bf16 v[78:81], v[134:137], v[240:243], v[78:81]
	v_mfma_f32_16x16x32_bf16 v[74:77], v[142:145], v[240:243], v[74:77]
	s_setprio 0
	s_setprio 1
	v_mfma_f32_16x16x32_bf16 v[118:121], v[146:149], v[176:179], v[118:121]
	v_mfma_f32_16x16x32_bf16 v[114:117], v[168:171], v[176:179], v[114:117]
	v_mfma_f32_16x16x32_bf16 v[102:105], v[146:149], v[202:205], v[102:105]
	v_mfma_f32_16x16x32_bf16 v[98:101], v[168:171], v[202:205], v[98:101]
	v_mfma_f32_16x16x32_bf16 v[86:89], v[146:149], v[210:213], v[86:89]
	v_mfma_f32_16x16x32_bf16 v[82:85], v[168:171], v[210:213], v[82:85]
	v_mfma_f32_16x16x32_bf16 v[70:73], v[146:149], v[236:239], v[70:73]
	v_mfma_f32_16x16x32_bf16 v[66:69], v[168:171], v[236:239], v[66:69]
	v_mfma_f32_16x16x32_bf16 v[118:121], v[150:153], v[180:183], v[118:121]
	v_mfma_f32_16x16x32_bf16 v[114:117], v[172:175], v[180:183], v[114:117]
	v_mfma_f32_16x16x32_bf16 v[102:105], v[150:153], v[206:209], v[102:105]
	v_mfma_f32_16x16x32_bf16 v[98:101], v[172:175], v[206:209], v[98:101]
	v_mfma_f32_16x16x32_bf16 v[86:89], v[150:153], v[232:235], v[86:89]
	v_mfma_f32_16x16x32_bf16 v[82:85], v[172:175], v[232:235], v[82:85]
	v_mfma_f32_16x16x32_bf16 v[70:73], v[150:153], v[240:243], v[70:73]
	v_mfma_f32_16x16x32_bf16 v[66:69], v[172:175], v[240:243], v[66:69]
	s_setprio 0
	s_barrier
	s_add_i32 s18, s50, s30
	s_mov_b32 m0, s18
	ds_read_b128 v[176:179], v200 offset:16384
	ds_read_b128 v[180:183], v200 offset:17408
	ds_read_b128 v[202:205], v200 offset:18432
	ds_read_b128 v[206:209], v200 offset:19456
	ds_read_b128 v[210:213], v200 offset:20480
	ds_read_b128 v[232:235], v200 offset:21504
	ds_read_b128 v[236:239], v200 offset:22528
	ds_read_b128 v[240:243], v200 offset:23552
	s_add_u32 s60, s22, 0x80
	s_addc_u32 s61, s23, 0
	s_add_u32 s62, s24, 0x80
	s_addc_u32 s63, s25, 0
	global_load_lds_dwordx4 v156, s[22:23]
	s_add_i32 m0, s18, 0x2000
	s_add_u32 s18, s22, 0xb0000
	s_addc_u32 s19, s23, 0
	s_add_i32 s50, s51, s30
	global_load_lds_dwordx4 v160, s[22:23]
	s_mov_b32 m0, s50
	s_nop 0
	global_load_lds_dwordx4 v156, s[18:19]
	s_add_i32 m0, s50, 0x2000
	s_nop 0
	global_load_lds_dwordx4 v160, s[18:19]
	s_mov_b32 m0, s31
	s_nop 0
	global_load_lds_dwordx4 v154, s[24:25]
	s_mov_b32 m0, s34
	s_nop 0
	global_load_lds_dwordx4 v158, s[24:25]
	s_waitcnt vmcnt(8)
	s_waitcnt lgkmcnt(0)
	s_barrier
	s_setprio 1
	v_mfma_f32_16x16x32_bf16 v[62:65], v[130:133], v[176:179], v[62:65]
	v_mfma_f32_16x16x32_bf16 v[58:61], v[138:141], v[176:179], v[58:61]
	v_mfma_f32_16x16x32_bf16 v[46:49], v[130:133], v[202:205], v[46:49]
	v_mfma_f32_16x16x32_bf16 v[42:45], v[138:141], v[202:205], v[42:45]
	v_mfma_f32_16x16x32_bf16 v[30:33], v[130:133], v[210:213], v[30:33]
	v_mfma_f32_16x16x32_bf16 v[26:29], v[138:141], v[210:213], v[26:29]
	v_mfma_f32_16x16x32_bf16 v[14:17], v[130:133], v[236:239], v[14:17]
	v_mfma_f32_16x16x32_bf16 v[10:13], v[138:141], v[236:239], v[10:13]
	v_mfma_f32_16x16x32_bf16 v[62:65], v[134:137], v[180:183], v[62:65]
	v_mfma_f32_16x16x32_bf16 v[58:61], v[142:145], v[180:183], v[58:61]
	v_mfma_f32_16x16x32_bf16 v[46:49], v[134:137], v[206:209], v[46:49]
	v_mfma_f32_16x16x32_bf16 v[42:45], v[142:145], v[206:209], v[42:45]
	v_mfma_f32_16x16x32_bf16 v[30:33], v[134:137], v[232:235], v[30:33]
	v_mfma_f32_16x16x32_bf16 v[26:29], v[142:145], v[232:235], v[26:29]
	v_mfma_f32_16x16x32_bf16 v[14:17], v[134:137], v[240:243], v[14:17]
	v_mfma_f32_16x16x32_bf16 v[10:13], v[142:145], v[240:243], v[10:13]
	s_setprio 0
	s_setprio 1
	v_mfma_f32_16x16x32_bf16 v[54:57], v[146:149], v[176:179], v[54:57]
	v_mfma_f32_16x16x32_bf16 v[50:53], v[168:171], v[176:179], v[50:53]
	v_mfma_f32_16x16x32_bf16 v[38:41], v[146:149], v[202:205], v[38:41]
	v_mfma_f32_16x16x32_bf16 v[34:37], v[168:171], v[202:205], v[34:37]
	v_mfma_f32_16x16x32_bf16 v[22:25], v[146:149], v[210:213], v[22:25]
	v_mfma_f32_16x16x32_bf16 v[18:21], v[168:171], v[210:213], v[18:21]
	v_mfma_f32_16x16x32_bf16 v[6:9], v[146:149], v[236:239], v[6:9]
	v_mfma_f32_16x16x32_bf16 v[2:5], v[168:171], v[236:239], v[2:5]
	v_mfma_f32_16x16x32_bf16 v[54:57], v[150:153], v[180:183], v[54:57]
	v_mfma_f32_16x16x32_bf16 v[50:53], v[172:175], v[180:183], v[50:53]
	v_mfma_f32_16x16x32_bf16 v[38:41], v[150:153], v[206:209], v[38:41]
	v_mfma_f32_16x16x32_bf16 v[34:37], v[172:175], v[206:209], v[34:37]
	v_mfma_f32_16x16x32_bf16 v[22:25], v[150:153], v[232:235], v[22:25]
	v_mfma_f32_16x16x32_bf16 v[18:21], v[172:175], v[232:235], v[18:21]
	v_mfma_f32_16x16x32_bf16 v[6:9], v[150:153], v[240:243], v[6:9]
	v_mfma_f32_16x16x32_bf16 v[2:5], v[172:175], v[240:243], v[2:5]
	s_setprio 0
	s_barrier
; #define PG8_STAGE(bufoff, gbase, voff) do { _Pragma("unroll") for (int _i = 0; _i < 2; ++_i) \
;         __builtin_amdgcn_global_load_lds((const unsigned*)((const char*)(gbase) + (voff)[_i]), (PG8_LAS unsigned*)(lds + (bufoff) + ldsw + _i * 8192), 16, 0, 0); } while (0)
; #define PG8_LDA(dst, b, h) do { _Pragma("unroll") for (int m = 0; m < 4; ++m) _Pragma("unroll") for (int k = 0; k < 2; ++k) dst[m][k] = *(const PG8_LAS bf16x8*)(lds + PG8_SA(b, h) + aoff + m * 2048 + k * 1024); } while (0)
; #define PG8_LDB(dst, b, h) do { _Pragma("unroll") for (int n = 0; n < 2; ++n) _Pragma("unroll") for (int k = 0; k < 2; ++k) dst[n][k] = *(const PG8_LAS bf16x8*)(lds + PG8_SB(b, h) + boff + n * 2048 + k * 1024); } while (0)
; #define PG8_MMA(ai, bj, At, Bt) do { __builtin_amdgcn_s_setprio(1); _Pragma("unroll") for (int m = 0; m < 4; ++m) _Pragma("unroll") for (int n = 0; n < 2; ++n) _Pragma("unroll") for (int k = 0; k < 2; ++k) \
;         acc[ai][bj][m][n] = __builtin_amdgcn_mfma_f32_16x16x32_bf16(Bt[n][k], At[m][k], acc[ai][bj][m][n], 0, 0, 0); __builtin_amdgcn_s_setprio(0); } while (0)
; #define PG8_WAIT_V(n) asm volatile("s_waitcnt vmcnt(" #n ")" ::: "memory")
; #define PG8_WAIT_L(n) asm volatile("s_waitcnt lgkmcnt(" #n ")" ::: "memory")
; #define PG8_BAR __builtin_amdgcn_s_barrier()
; template <class Epi, class Sched, bool ALIGN_EPI = false, bool SP2 = false>
; __device__ __forceinline__ void gemm_phase(PG8_LAS unsigned char* lds, const Gemm g, const Sched& S, const Epi& E) {
;     ...
;         for (int t = 0; t < nt; t += 2) {
;             const bool last = (t == nt - 2);
;             const char* a1 = cA + (size_t)(t + 1) * kstep;
;             const char* a2 = last ? nA : cA + (size_t)(t + 2) * kstep; const char* b2 = last ? nB : cB + (size_t)(t + 2) * kstep;
;             const char* a3 = a2 + kstep; const char* b3 = b2 + kstep;
;     ...
;             PG8_LDB(B0, 1, 0); PG8_LDB(B1, 1, 1); PG8_SCHED; PG8_LDA(At, 1, 0); PG8_STAGE(PG8_SA(0, 1), a2 + hstepA, voffA);
;             PG8_WAIT_V(8); PG8_WAIT_L(0); PG8_BAR; PG8_MMA(0, 0, At, B0); PG8_MMA(0, 1, At, B1); PG8_BAR; PG8_SCHED;
;             PG8_LDA(At, 1, 1); PG8_STAGE(PG8_SB(1, 0), b3, voffB); PG8_STAGE(PG8_SB(1, 1), b3 + hstepB, voffB); PG8_STAGE(PG8_SA(1, 0), a3, voffA);
;             PG8_WAIT_V(8); PG8_WAIT_L(0); PG8_BAR; PG8_MMA(1, 0, At, B0); PG8_MMA(1, 1, At, B1); PG8_BAR; PG8_SCHED;
	s_add_i32 s50, 0, 0x18000
	s_add_i32 s51, 0, 0x1c000
	v_add_u32_e32 v142, s50, v186
	v_add_u32_e32 v172, s51, v186
	ds_read_b128 v[130:133], v142
	ds_read_b128 v[134:137], v142 offset:1024
	ds_read_b128 v[138:141], v142 offset:2048
	ds_read_b128 v[142:145], v142 offset:3072
	ds_read_b128 v[146:149], v172
	ds_read_b128 v[150:153], v172 offset:1024
	ds_read_b128 v[168:171], v172 offset:2048
	ds_read_b128 v[172:175], v172 offset:3072
	s_add_u32 s18, s24, 0xb0000
	s_addc_u32 s19, s25, 0
	s_mov_b32 m0, s35
	ds_read_b128 v[176:179], v200 offset:32768
	ds_read_b128 v[180:183], v200 offset:33792
	ds_read_b128 v[202:205], v200 offset:34816
	ds_read_b128 v[206:209], v200 offset:35840
	ds_read_b128 v[210:213], v200 offset:36864
	ds_read_b128 v[232:235], v200 offset:37888
	ds_read_b128 v[236:239], v200 offset:38912
	ds_read_b128 v[240:243], v200 offset:39936
	global_load_lds_dwordx4 v154, s[18:19]
	s_mov_b32 m0, s36
	s_nop 0
	global_load_lds_dwordx4 v158, s[18:19]
	s_waitcnt vmcnt(8)
	s_waitcnt lgkmcnt(0)
	s_barrier
	s_setprio 1
	v_mfma_f32_16x16x32_bf16 v[126:129], v[130:133], v[176:179], v[126:129]
	v_mfma_f32_16x16x32_bf16 v[122:125], v[138:141], v[176:179], v[122:125]
	v_mfma_f32_16x16x32_bf16 v[110:113], v[130:133], v[202:205], v[110:113]
	v_mfma_f32_16x16x32_bf16 v[106:109], v[138:141], v[202:205], v[106:109]
	v_mfma_f32_16x16x32_bf16 v[94:97], v[130:133], v[210:213], v[94:97]
	v_mfma_f32_16x16x32_bf16 v[90:93], v[138:141], v[210:213], v[90:93]
	v_mfma_f32_16x16x32_bf16 v[78:81], v[130:133], v[236:239], v[78:81]
	v_mfma_f32_16x16x32_bf16 v[74:77], v[138:141], v[236:239], v[74:77]
	v_mfma_f32_16x16x32_bf16 v[126:129], v[134:137], v[180:183], v[126:129]
	v_mfma_f32_16x16x32_bf16 v[122:125], v[142:145], v[180:183], v[122:125]
	v_mfma_f32_16x16x32_bf16 v[110:113], v[134:137], v[206:209], v[110:113]
	v_mfma_f32_16x16x32_bf16 v[106:109], v[142:145], v[206:209], v[106:109]
	v_mfma_f32_16x16x32_bf16 v[94:97], v[134:137], v[232:235], v[94:97]
	v_mfma_f32_16x16x32_bf16 v[90:93], v[142:145], v[232:235], v[90:93]
	v_mfma_f32_16x16x32_bf16 v[78:81], v[134:137], v[240:243], v[78:81]
	v_mfma_f32_16x16x32_bf16 v[74:77], v[142:145], v[240:243], v[74:77]
	s_setprio 0
	s_setprio 1
	v_mfma_f32_16x16x32_bf16 v[118:121], v[146:149], v[176:179], v[118:121]
	v_mfma_f32_16x16x32_bf16 v[114:117], v[168:171], v[176:179], v[114:117]
	v_mfma_f32_16x16x32_bf16 v[102:105], v[146:149], v[202:205], v[102:105]
	v_mfma_f32_16x16x32_bf16 v[98:101], v[168:171], v[202:205], v[98:101]
	v_mfma_f32_16x16x32_bf16 v[86:89], v[146:149], v[210:213], v[86:89]
	v_mfma_f32_16x16x32_bf16 v[82:85], v[168:171], v[210:213], v[82:85]
	v_mfma_f32_16x16x32_bf16 v[70:73], v[146:149], v[236:239], v[70:73]
	v_mfma_f32_16x16x32_bf16 v[66:69], v[168:171], v[236:239], v[66:69]
	v_mfma_f32_16x16x32_bf16 v[118:121], v[150:153], v[180:183], v[118:121]
	v_mfma_f32_16x16x32_bf16 v[114:117], v[172:175], v[180:183], v[114:117]
	v_mfma_f32_16x16x32_bf16 v[102:105], v[150:153], v[206:209], v[102:105]
	v_mfma_f32_16x16x32_bf16 v[98:101], v[172:175], v[206:209], v[98:101]
	v_mfma_f32_16x16x32_bf16 v[86:89], v[150:153], v[232:235], v[86:89]
	v_mfma_f32_16x16x32_bf16 v[82:85], v[172:175], v[232:235], v[82:85]
	v_mfma_f32_16x16x32_bf16 v[70:73], v[150:153], v[240:243], v[70:73]
	v_mfma_f32_16x16x32_bf16 v[66:69], v[172:175], v[240:243], v[66:69]
	s_setprio 0
	s_barrier
	s_add_i32 s18, s50, s30
	s_mov_b32 m0, s18
	ds_read_b128 v[176:179], v200 offset:49152
	ds_read_b128 v[180:183], v200 offset:50176
	ds_read_b128 v[202:205], v200 offset:51200
	ds_read_b128 v[206:209], v200 offset:52224
	ds_read_b128 v[210:213], v200 offset:53248
	ds_read_b128 v[232:235], v200 offset:54272
	ds_read_b128 v[236:239], v200 offset:55296
	ds_read_b128 v[240:243], v200 offset:56320
	global_load_lds_dwordx4 v156, s[60:61]
	s_add_i32 m0, s18, 0x2000
	s_add_u32 s18, s22, 0xb0080
	s_addc_u32 s19, s23, 0
	s_add_i32 s22, s51, s30
	global_load_lds_dwordx4 v160, s[60:61]
	s_mov_b32 m0, s22
	s_nop 0
	global_load_lds_dwordx4 v156, s[18:19]
	s_add_i32 m0, s22, 0x2000
	s_nop 0
	global_load_lds_dwordx4 v160, s[18:19]
	s_mov_b32 m0, s38
	s_nop 0
	global_load_lds_dwordx4 v154, s[62:63]
	s_mov_b32 m0, s39
	s_nop 0
	global_load_lds_dwordx4 v158, s[62:63]
	s_waitcnt vmcnt(8)
	s_waitcnt lgkmcnt(0)
	s_barrier
	s_setprio 1
	v_mfma_f32_16x16x32_bf16 v[62:65], v[130:133], v[176:179], v[62:65]
	v_mfma_f32_16x16x32_bf16 v[58:61], v[138:141], v[176:179], v[58:61]
	v_mfma_f32_16x16x32_bf16 v[46:49], v[130:133], v[202:205], v[46:49]
	v_mfma_f32_16x16x32_bf16 v[42:45], v[138:141], v[202:205], v[42:45]
	v_mfma_f32_16x16x32_bf16 v[30:33], v[130:133], v[210:213], v[30:33]
	v_mfma_f32_16x16x32_bf16 v[26:29], v[138:141], v[210:213], v[26:29]
	v_mfma_f32_16x16x32_bf16 v[14:17], v[130:133], v[236:239], v[14:17]
	v_mfma_f32_16x16x32_bf16 v[10:13], v[138:141], v[236:239], v[10:13]
	v_mfma_f32_16x16x32_bf16 v[62:65], v[134:137], v[180:183], v[62:65]
	v_mfma_f32_16x16x32_bf16 v[58:61], v[142:145], v[180:183], v[58:61]
	v_mfma_f32_16x16x32_bf16 v[46:49], v[134:137], v[206:209], v[46:49]
	v_mfma_f32_16x16x32_bf16 v[42:45], v[142:145], v[206:209], v[42:45]
	v_mfma_f32_16x16x32_bf16 v[30:33], v[134:137], v[232:235], v[30:33]
	v_mfma_f32_16x16x32_bf16 v[26:29], v[142:145], v[232:235], v[26:29]
	v_mfma_f32_16x16x32_bf16 v[14:17], v[134:137], v[240:243], v[14:17]
	v_mfma_f32_16x16x32_bf16 v[10:13], v[142:145], v[240:243], v[10:13]
	s_setprio 0
	s_setprio 1
	v_mfma_f32_16x16x32_bf16 v[54:57], v[146:149], v[176:179], v[54:57]
	v_mfma_f32_16x16x32_bf16 v[50:53], v[168:171], v[176:179], v[50:53]
	v_mfma_f32_16x16x32_bf16 v[38:41], v[146:149], v[202:205], v[38:41]
	v_mfma_f32_16x16x32_bf16 v[34:37], v[168:171], v[202:205], v[34:37]
	v_mfma_f32_16x16x32_bf16 v[22:25], v[146:149], v[210:213], v[22:25]
	v_mfma_f32_16x16x32_bf16 v[18:21], v[168:171], v[210:213], v[18:21]
	v_mfma_f32_16x16x32_bf16 v[6:9], v[146:149], v[236:239], v[6:9]
	v_mfma_f32_16x16x32_bf16 v[2:5], v[168:171], v[236:239], v[2:5]
	v_mfma_f32_16x16x32_bf16 v[54:57], v[150:153], v[180:183], v[54:57]
	v_mfma_f32_16x16x32_bf16 v[50:53], v[172:175], v[180:183], v[50:53]
	v_mfma_f32_16x16x32_bf16 v[38:41], v[150:153], v[206:209], v[38:41]
	v_mfma_f32_16x16x32_bf16 v[34:37], v[172:175], v[206:209], v[34:37]
	v_mfma_f32_16x16x32_bf16 v[22:25], v[150:153], v[232:235], v[22:25]
	v_mfma_f32_16x16x32_bf16 v[18:21], v[172:175], v[232:235], v[18:21]
	v_mfma_f32_16x16x32_bf16 v[6:9], v[150:153], v[240:243], v[6:9]
	v_mfma_f32_16x16x32_bf16 v[2:5], v[172:175], v[240:243], v[2:5]
	s_setprio 0
	s_barrier
	s_add_i32 s49, s49, 2
	s_add_u32 s47, s47, 0x100
	s_addc_u32 s48, s48, 0
	s_cmp_gt_u32 s49, 41
	s_mov_b64 s[18:19], s[20:21]
	s_cbranch_scc0 .LBB0_1438
	s_and_b64 vcc, exec, s[14:15]
	s_cbranch_vccz .LBB0_1441
	s_barrier
